# K-loop LDS-DMA staging rebalanced 2/6/2/6 -> 4/4/4/4 pieces per load segment (A-half-0 stage moved one segment later), waits 8/6/8/6
# baseline (speedup 1.0000x reference)
; #define PG8_STAGE(bufoff, gbase, voff) do { const unsigned long long gb_ = (unsigned long long)(gbase); _Pragma("unroll") for (int _i = 0; _i < 2; ++_i) { unsigned keep_; \
;         asm volatile("s_mov_b32 m0, %2\n\ts_nop 0\n\tglobal_load_lds_dwordx4 %0, %1" : : "v"((voff)[_i]), "s"(gb_), "s"((unsigned)(size_t)(lds + (bufoff) + ldsw + _i * 8192)) : "memory", "m0"); (void)keep_; } } while (0)
; #define PG8_LDA(dst, b, h) do { _Pragma("unroll") for (int m = 0; m < 4; ++m) _Pragma("unroll") for (int k = 0; k < 2; ++k) dst[m][k] = *(const PG8_LAS bf16x8*)(lds + PG8_SA(b, h) + aoff + m * 2048 + k * 1024); } while (0)
; #define PG8_LDB(dst, b, h) do { _Pragma("unroll") for (int n = 0; n < 2; ++n) _Pragma("unroll") for (int k = 0; k < 2; ++k) dst[n][k] = *(const PG8_LAS bf16x8*)(lds + PG8_SB(b, h) + boff + n * 2048 + k * 1024); } while (0)
; #define PG8_MMA(ai, bj, At, Bt) do { __builtin_amdgcn_s_setprio(1); _Pragma("unroll") for (int m = 0; m < 4; ++m) _Pragma("unroll") for (int n = 0; n < 2; ++n) _Pragma("unroll") for (int k = 0; k < 2; ++k) \
;         acc[ai][bj][m][n] = __builtin_amdgcn_mfma_f32_16x16x32_bf16(Bt[n][k], At[m][k], acc[ai][bj][m][n], 0, 0, 0); __builtin_amdgcn_s_setprio(0); } while (0)
; #define PG8_WAIT_V(n) asm volatile("s_waitcnt vmcnt(" #n ")" ::: "memory")
; #define PG8_BAR __builtin_amdgcn_s_barrier()
; template <class Epi, class Sched, bool ALIGN_EPI = false, bool SP2 = false>
; __device__ __forceinline__ void gemm_phase(PG8_LAS unsigned char* lds, const Gemm g, const Sched& S, const Epi& E) {
;     ...
;         for (int t = 0; t < nt; t += 2) {
;             const bool last = (t == nt - 2);
;     ...
;             const char* a1 = cA + PG8_KOFFA(t + 1);
;             const char* a2 = last ? nA : cA + PG8_KOFFA(t + 2); const char* b2 = last ? nB : cB + (size_t)(t + 2) * kstep;
;             const char* a3 = last ? nA + kstep : cA + PG8_KOFFA(t + 3); const char* b3 = b2 + kstep;
;     ...
;             if (last && has_next) S.a_ready(nxt);
;             if constexpr (SP2) {
;             PG8_LDB(B0, 0, 0); PG8_LDB(B1, 0, 1); PG8_SCHED; PG8_LDA(At, 0, 0); PG8_STAGE(PG8_SA(1, 1), a1 + hstepA, voffA);
;             PG8_WAIT_V(8); PG8_WAIT_L(0); PG8_BAR; PG8_MMA(0, 0, At, B0); PG8_MMA(0, 1, At, B1); PG8_BAR; PG8_SCHED;
;             PG8_LDA(At, 0, 1); PG8_STAGE(PG8_SB(0, 0), b2, voffB); PG8_STAGE(PG8_SB(0, 1), b2 + hstepB, voffB); PG8_STAGE(PG8_SA(0, 0), a2, voffA);
.LBB0_371:
	s_add_i32 s39, s73, 0xfffe8000
	s_and_b32 s38, s36, 0x100
	s_and_b32 s39, s39, 0xe0000
	s_or_b32 s38, s38, s39
	s_add_u32 s76, s8, s38
	s_addc_u32 s77, s9, 0
	s_add_u32 s38, s36, 0x100
	s_addc_u32 s39, s37, 0
	s_add_i32 s41, s73, 0xffff8000
	s_and_b32 s40, s38, 0x100
	s_and_b32 s41, s41, 0x1e0000
	s_or_b32 s40, s41, s40
	ds_read_b128 v[154:157], v167
	ds_read_b128 v[178:181], v167 offset:1024
	ds_read_b128 v[182:185], v167 offset:2048
	ds_read_b128 v[186:189], v167 offset:3072
	ds_read_b128 v[190:193], v169
	ds_read_b128 v[194:197], v169 offset:1024
	ds_read_b128 v[202:205], v169 offset:2048
	ds_read_b128 v[206:209], v169 offset:3072
	s_add_u32 s40, s8, s40
	s_addc_u32 s41, s9, 0
	s_add_u32 s78, s70, s36
	s_addc_u32 s37, s71, s37
	s_add_i32 s42, s36, 0x180
	s_and_b32 s42, s42, 0x180
	s_and_b32 s43, s73, 0x1e0000
	s_or_b32 s42, s43, s42
	s_add_u32 s79, s8, s42
	s_addc_u32 s80, s9, 0
	s_cmpk_eq_i32 s36, 0xf00
	s_cselect_b32 s43, s0, s41
	s_cselect_b32 s41, s23, s37
	s_cselect_b32 s37, s69, s80
	s_cselect_b32 s36, s31, s79
	s_cselect_b32 s42, s1, s40
	s_cselect_b32 s40, s25, s78
	ds_read_b128 v[210:213], v172
	ds_read_b128 v[214:217], v172 offset:1024
	ds_read_b128 v[218:221], v172 offset:2048
	ds_read_b128 v[222:225], v172 offset:3072
	ds_read_b128 v[226:229], v172 offset:4096
	ds_read_b128 v[230:233], v172 offset:5120
	ds_read_b128 v[234:237], v172 offset:6144
	ds_read_b128 v[238:241], v172 offset:7168
	s_add_u32 s76, s76, 0x10080
	s_addc_u32 s77, s77, 0
	s_sub_u32 s98, s76, 0x10000
	s_subb_u32 s99, s77, 0
	s_mov_b32 m0, s59
	s_nop 0
	global_load_lds_dwordx4 v159, s[98:99]
	s_nop 0
	s_mov_b32 m0, s60
	s_nop 0
	global_load_lds_dwordx4 v163, s[98:99]
	s_nop 0
	s_mov_b32 m0, s63
	s_nop 0
	global_load_lds_dwordx4 v159, s[76:77]
	s_nop 0
	s_mov_b32 m0, s64
	s_nop 0
	global_load_lds_dwordx4 v163, s[76:77]
	s_waitcnt vmcnt(8)
	s_waitcnt lgkmcnt(0)
	s_barrier
	s_setprio 1
	s_waitcnt lgkmcnt(7)
	v_mfma_f32_16x16x32_bf16 v[124:127], v[154:157], v[210:213], v[124:127]
	v_mfma_f32_16x16x32_bf16 v[116:119], v[182:185], v[210:213], v[116:119]
	s_waitcnt lgkmcnt(5)
	v_mfma_f32_16x16x32_bf16 v[108:111], v[154:157], v[218:221], v[108:111]
	v_mfma_f32_16x16x32_bf16 v[100:103], v[182:185], v[218:221], v[100:103]
	s_waitcnt lgkmcnt(3)
	v_mfma_f32_16x16x32_bf16 v[92:95], v[154:157], v[226:229], v[92:95]
	v_mfma_f32_16x16x32_bf16 v[84:87], v[182:185], v[226:229], v[84:87]
	s_waitcnt lgkmcnt(1)
	v_mfma_f32_16x16x32_bf16 v[76:79], v[154:157], v[234:237], v[76:79]
	v_mfma_f32_16x16x32_bf16 v[68:71], v[182:185], v[234:237], v[68:71]
	v_mfma_f32_16x16x32_bf16 v[124:127], v[178:181], v[214:217], v[124:127]
	v_mfma_f32_16x16x32_bf16 v[116:119], v[186:189], v[214:217], v[116:119]
	v_mfma_f32_16x16x32_bf16 v[108:111], v[178:181], v[222:225], v[108:111]
	v_mfma_f32_16x16x32_bf16 v[100:103], v[186:189], v[222:225], v[100:103]
	v_mfma_f32_16x16x32_bf16 v[92:95], v[178:181], v[230:233], v[92:95]
	v_mfma_f32_16x16x32_bf16 v[84:87], v[186:189], v[230:233], v[84:87]
	s_waitcnt lgkmcnt(0)
	v_mfma_f32_16x16x32_bf16 v[76:79], v[178:181], v[238:241], v[76:79]
	v_mfma_f32_16x16x32_bf16 v[68:71], v[186:189], v[238:241], v[68:71]
	s_setprio 0
	s_setprio 1
	v_mfma_f32_16x16x32_bf16 v[120:123], v[190:193], v[210:213], v[120:123]
	v_mfma_f32_16x16x32_bf16 v[112:115], v[202:205], v[210:213], v[112:115]
	v_mfma_f32_16x16x32_bf16 v[104:107], v[190:193], v[218:221], v[104:107]
	v_mfma_f32_16x16x32_bf16 v[96:99], v[202:205], v[218:221], v[96:99]
	v_mfma_f32_16x16x32_bf16 v[88:91], v[190:193], v[226:229], v[88:91]
	v_mfma_f32_16x16x32_bf16 v[80:83], v[202:205], v[226:229], v[80:83]
	v_mfma_f32_16x16x32_bf16 v[72:75], v[190:193], v[234:237], v[72:75]
	v_mfma_f32_16x16x32_bf16 v[64:67], v[202:205], v[234:237], v[64:67]
	v_mfma_f32_16x16x32_bf16 v[120:123], v[194:197], v[214:217], v[120:123]
	v_mfma_f32_16x16x32_bf16 v[112:115], v[206:209], v[214:217], v[112:115]
	v_mfma_f32_16x16x32_bf16 v[104:107], v[194:197], v[222:225], v[104:107]
	v_mfma_f32_16x16x32_bf16 v[96:99], v[206:209], v[222:225], v[96:99]
	v_mfma_f32_16x16x32_bf16 v[88:91], v[194:197], v[230:233], v[88:91]
	v_mfma_f32_16x16x32_bf16 v[80:83], v[206:209], v[230:233], v[80:83]
	v_mfma_f32_16x16x32_bf16 v[72:75], v[194:197], v[238:241], v[72:75]
	v_mfma_f32_16x16x32_bf16 v[64:67], v[206:209], v[238:241], v[64:67]
	s_setprio 0
	s_barrier
	ds_read_b128 v[210:213], v172 offset:16384
	ds_read_b128 v[214:217], v172 offset:17408
	ds_read_b128 v[218:221], v172 offset:18432
	ds_read_b128 v[222:225], v172 offset:19456
	ds_read_b128 v[226:229], v172 offset:20480
	ds_read_b128 v[230:233], v172 offset:21504
	ds_read_b128 v[234:237], v172 offset:22528
	ds_read_b128 v[238:241], v172 offset:23552
	s_mov_b32 m0, s47
	s_nop 0
	global_load_lds_dwordx4 v161, s[40:41]
	s_add_u32 s76, s40, 0x80000
	s_mov_b32 m0, s48
	s_nop 0
	global_load_lds_dwordx4 v165, s[40:41]
	s_addc_u32 s77, s41, 0
	s_mov_b32 m0, s49
	s_nop 0
	global_load_lds_dwordx4 v161, s[76:77]
	s_nop 0
	s_mov_b32 m0, s50
	s_nop 0
	global_load_lds_dwordx4 v165, s[76:77]
	s_nop 0
	s_nop 0
	s_waitcnt vmcnt(6)
	s_waitcnt lgkmcnt(0)
	s_barrier
; #define PG8_STAGE(bufoff, gbase, voff) do { const unsigned long long gb_ = (unsigned long long)(gbase); _Pragma("unroll") for (int _i = 0; _i < 2; ++_i) { unsigned keep_; \
;         asm volatile("s_mov_b32 m0, %2\n\ts_nop 0\n\tglobal_load_lds_dwordx4 %0, %1" : : "v"((voff)[_i]), "s"(gb_), "s"((unsigned)(size_t)(lds + (bufoff) + ldsw + _i * 8192)) : "memory", "m0"); (void)keep_; } } while (0)
; #define PG8_LDA(dst, b, h) do { _Pragma("unroll") for (int m = 0; m < 4; ++m) _Pragma("unroll") for (int k = 0; k < 2; ++k) dst[m][k] = *(const PG8_LAS bf16x8*)(lds + PG8_SA(b, h) + aoff + m * 2048 + k * 1024); } while (0)
; #define PG8_LDB(dst, b, h) do { _Pragma("unroll") for (int n = 0; n < 2; ++n) _Pragma("unroll") for (int k = 0; k < 2; ++k) dst[n][k] = *(const PG8_LAS bf16x8*)(lds + PG8_SB(b, h) + boff + n * 2048 + k * 1024); } while (0)
; #define PG8_MMA(ai, bj, At, Bt) do { __builtin_amdgcn_s_setprio(1); _Pragma("unroll") for (int m = 0; m < 4; ++m) _Pragma("unroll") for (int n = 0; n < 2; ++n) _Pragma("unroll") for (int k = 0; k < 2; ++k) \
;         acc[ai][bj][m][n] = __builtin_amdgcn_mfma_f32_16x16x32_bf16(Bt[n][k], At[m][k], acc[ai][bj][m][n], 0, 0, 0); __builtin_amdgcn_s_setprio(0); } while (0)
; #define PG8_WAIT_V(n) asm volatile("s_waitcnt vmcnt(" #n ")" ::: "memory")
; #define PG8_WAIT_L(n) asm volatile("s_waitcnt lgkmcnt(" #n ")" ::: "memory")
; #define PG8_BAR __builtin_amdgcn_s_barrier()
; #define PG8_SCHED __builtin_amdgcn_sched_barrier(0)
; template <class Epi, class Sched, bool ALIGN_EPI = false, bool SP2 = false>
; __device__ __forceinline__ void gemm_phase(PG8_LAS unsigned char* lds, const Gemm g, const Sched& S, const Epi& E) {
;     ...
;             PG8_WAIT_V(8); PG8_WAIT_L(0); PG8_BAR; PG8_MMA(1, 0, At, B0); PG8_MMA(1, 1, At, B1); PG8_BAR; PG8_SCHED;
;             PG8_LDB(B0, 1, 0); PG8_LDB(B1, 1, 1); PG8_SCHED; PG8_LDA(At, 1, 0); PG8_STAGE(PG8_SA(0, 1), a2 + hstepA, voffA);
	s_setprio 1
	s_waitcnt lgkmcnt(7)
	v_mfma_f32_16x16x32_bf16 v[60:63], v[154:157], v[210:213], v[60:63]
	v_mfma_f32_16x16x32_bf16 v[52:55], v[182:185], v[210:213], v[52:55]
	s_waitcnt lgkmcnt(5)
	v_mfma_f32_16x16x32_bf16 v[44:47], v[154:157], v[218:221], v[44:47]
	v_mfma_f32_16x16x32_bf16 v[36:39], v[182:185], v[218:221], v[36:39]
	s_waitcnt lgkmcnt(3)
	v_mfma_f32_16x16x32_bf16 v[28:31], v[154:157], v[226:229], v[28:31]
	v_mfma_f32_16x16x32_bf16 v[20:23], v[182:185], v[226:229], v[20:23]
	s_waitcnt lgkmcnt(1)
	v_mfma_f32_16x16x32_bf16 v[12:15], v[154:157], v[234:237], v[12:15]
	v_mfma_f32_16x16x32_bf16 v[4:7], v[182:185], v[234:237], v[4:7]
	v_mfma_f32_16x16x32_bf16 v[60:63], v[178:181], v[214:217], v[60:63]
	v_mfma_f32_16x16x32_bf16 v[52:55], v[186:189], v[214:217], v[52:55]
	v_mfma_f32_16x16x32_bf16 v[44:47], v[178:181], v[222:225], v[44:47]
	v_mfma_f32_16x16x32_bf16 v[36:39], v[186:189], v[222:225], v[36:39]
	v_mfma_f32_16x16x32_bf16 v[28:31], v[178:181], v[230:233], v[28:31]
	v_mfma_f32_16x16x32_bf16 v[20:23], v[186:189], v[230:233], v[20:23]
	s_waitcnt lgkmcnt(0)
	v_mfma_f32_16x16x32_bf16 v[12:15], v[178:181], v[238:241], v[12:15]
	v_mfma_f32_16x16x32_bf16 v[4:7], v[186:189], v[238:241], v[4:7]
	s_setprio 0
	s_setprio 1
	v_mfma_f32_16x16x32_bf16 v[56:59], v[190:193], v[210:213], v[56:59]
	v_mfma_f32_16x16x32_bf16 v[48:51], v[202:205], v[210:213], v[48:51]
	v_mfma_f32_16x16x32_bf16 v[40:43], v[190:193], v[218:221], v[40:43]
	v_mfma_f32_16x16x32_bf16 v[32:35], v[202:205], v[218:221], v[32:35]
	v_mfma_f32_16x16x32_bf16 v[24:27], v[190:193], v[226:229], v[24:27]
	v_mfma_f32_16x16x32_bf16 v[16:19], v[202:205], v[226:229], v[16:19]
	v_mfma_f32_16x16x32_bf16 v[8:11], v[190:193], v[234:237], v[8:11]
	v_mfma_f32_16x16x32_bf16 v[0:3], v[202:205], v[234:237], v[0:3]
	v_mfma_f32_16x16x32_bf16 v[56:59], v[194:197], v[214:217], v[56:59]
	v_mfma_f32_16x16x32_bf16 v[48:51], v[206:209], v[214:217], v[48:51]
	v_mfma_f32_16x16x32_bf16 v[40:43], v[194:197], v[222:225], v[40:43]
	v_mfma_f32_16x16x32_bf16 v[32:35], v[206:209], v[222:225], v[32:35]
	v_mfma_f32_16x16x32_bf16 v[24:27], v[194:197], v[230:233], v[24:27]
	v_mfma_f32_16x16x32_bf16 v[16:19], v[206:209], v[230:233], v[16:19]
	v_mfma_f32_16x16x32_bf16 v[8:11], v[194:197], v[238:241], v[8:11]
	v_mfma_f32_16x16x32_bf16 v[0:3], v[206:209], v[238:241], v[0:3]
	s_setprio 0
	s_barrier
	ds_read_b128 v[154:157], v173
	ds_read_b128 v[178:181], v173 offset:1024
	ds_read_b128 v[182:185], v173 offset:2048
	ds_read_b128 v[186:189], v173 offset:3072
	ds_read_b128 v[190:193], v174
	ds_read_b128 v[194:197], v174 offset:1024
	ds_read_b128 v[202:205], v174 offset:2048
	ds_read_b128 v[206:209], v174 offset:3072
	ds_read_b128 v[210:213], v172 offset:32768
	ds_read_b128 v[214:217], v172 offset:33792
	ds_read_b128 v[218:221], v172 offset:34816
	ds_read_b128 v[222:225], v172 offset:35840
	ds_read_b128 v[226:229], v172 offset:36864
	ds_read_b128 v[230:233], v172 offset:37888
	ds_read_b128 v[234:237], v172 offset:38912
	ds_read_b128 v[238:241], v172 offset:39936
	s_mov_b32 m0, s35
	s_nop 0
	global_load_lds_dwordx4 v159, s[42:43]
	s_nop 0
	s_mov_b32 m0, s51
	s_nop 0
	global_load_lds_dwordx4 v163, s[42:43]
	s_nop 0
	s_add_u32 s42, s42, 0x10000
	s_addc_u32 s43, s43, 0
	s_mov_b32 m0, s52
	s_nop 0
	global_load_lds_dwordx4 v159, s[42:43]
	s_nop 0
	s_mov_b32 m0, s53
	s_nop 0
	global_load_lds_dwordx4 v163, s[42:43]
	s_waitcnt vmcnt(8)
	s_waitcnt lgkmcnt(0)
	s_barrier
; #define PG8_STAGE(bufoff, gbase, voff) do { const unsigned long long gb_ = (unsigned long long)(gbase); _Pragma("unroll") for (int _i = 0; _i < 2; ++_i) { unsigned keep_; \
;         asm volatile("s_mov_b32 m0, %2\n\ts_nop 0\n\tglobal_load_lds_dwordx4 %0, %1" : : "v"((voff)[_i]), "s"(gb_), "s"((unsigned)(size_t)(lds + (bufoff) + ldsw + _i * 8192)) : "memory", "m0"); (void)keep_; } } while (0)
; #define PG8_LDA(dst, b, h) do { _Pragma("unroll") for (int m = 0; m < 4; ++m) _Pragma("unroll") for (int k = 0; k < 2; ++k) dst[m][k] = *(const PG8_LAS bf16x8*)(lds + PG8_SA(b, h) + aoff + m * 2048 + k * 1024); } while (0)
; #define PG8_MMA(ai, bj, At, Bt) do { __builtin_amdgcn_s_setprio(1); _Pragma("unroll") for (int m = 0; m < 4; ++m) _Pragma("unroll") for (int n = 0; n < 2; ++n) _Pragma("unroll") for (int k = 0; k < 2; ++k) \
;         acc[ai][bj][m][n] = __builtin_amdgcn_mfma_f32_16x16x32_bf16(Bt[n][k], At[m][k], acc[ai][bj][m][n], 0, 0, 0); __builtin_amdgcn_s_setprio(0); } while (0)
; #define PG8_WAIT_V(n) asm volatile("s_waitcnt vmcnt(" #n ")" ::: "memory")
; #define PG8_WAIT_L(n) asm volatile("s_waitcnt lgkmcnt(" #n ")" ::: "memory")
; #define PG8_BAR __builtin_amdgcn_s_barrier()
; #define PG8_SCHED __builtin_amdgcn_sched_barrier(0)
; template <class Epi, class Sched, bool ALIGN_EPI = false, bool SP2 = false>
; __device__ __forceinline__ void gemm_phase(PG8_LAS unsigned char* lds, const Gemm g, const Sched& S, const Epi& E) {
;     ...
;             PG8_WAIT_V(8); PG8_WAIT_L(0); PG8_BAR; PG8_MMA(0, 0, At, B0); PG8_MMA(0, 1, At, B1); PG8_BAR; PG8_SCHED;
;             PG8_LDA(At, 1, 1); PG8_STAGE(PG8_SB(1, 0), b3, voffB); PG8_STAGE(PG8_SB(1, 1), b3 + hstepB, voffB); PG8_STAGE(PG8_SA(1, 0), a3, voffA);
;             PG8_WAIT_V(8); PG8_WAIT_L(0); PG8_BAR; PG8_MMA(1, 0, At, B0); PG8_MMA(1, 1, At, B1); PG8_BAR; PG8_SCHED;
	s_setprio 1
	s_waitcnt lgkmcnt(7)
	v_mfma_f32_16x16x32_bf16 v[124:127], v[154:157], v[210:213], v[124:127]
	v_mfma_f32_16x16x32_bf16 v[116:119], v[182:185], v[210:213], v[116:119]
	s_waitcnt lgkmcnt(5)
	v_mfma_f32_16x16x32_bf16 v[108:111], v[154:157], v[218:221], v[108:111]
	v_mfma_f32_16x16x32_bf16 v[100:103], v[182:185], v[218:221], v[100:103]
	s_waitcnt lgkmcnt(3)
	v_mfma_f32_16x16x32_bf16 v[92:95], v[154:157], v[226:229], v[92:95]
	v_mfma_f32_16x16x32_bf16 v[84:87], v[182:185], v[226:229], v[84:87]
	s_waitcnt lgkmcnt(1)
	v_mfma_f32_16x16x32_bf16 v[76:79], v[154:157], v[234:237], v[76:79]
	v_mfma_f32_16x16x32_bf16 v[68:71], v[182:185], v[234:237], v[68:71]
	v_mfma_f32_16x16x32_bf16 v[124:127], v[178:181], v[214:217], v[124:127]
	v_mfma_f32_16x16x32_bf16 v[116:119], v[186:189], v[214:217], v[116:119]
	v_mfma_f32_16x16x32_bf16 v[108:111], v[178:181], v[222:225], v[108:111]
	v_mfma_f32_16x16x32_bf16 v[100:103], v[186:189], v[222:225], v[100:103]
	v_mfma_f32_16x16x32_bf16 v[92:95], v[178:181], v[230:233], v[92:95]
	v_mfma_f32_16x16x32_bf16 v[84:87], v[186:189], v[230:233], v[84:87]
	s_waitcnt lgkmcnt(0)
	v_mfma_f32_16x16x32_bf16 v[76:79], v[178:181], v[238:241], v[76:79]
	v_mfma_f32_16x16x32_bf16 v[68:71], v[186:189], v[238:241], v[68:71]
	s_setprio 0
	s_setprio 1
	v_mfma_f32_16x16x32_bf16 v[120:123], v[190:193], v[210:213], v[120:123]
	v_mfma_f32_16x16x32_bf16 v[112:115], v[202:205], v[210:213], v[112:115]
	v_mfma_f32_16x16x32_bf16 v[104:107], v[190:193], v[218:221], v[104:107]
	v_mfma_f32_16x16x32_bf16 v[96:99], v[202:205], v[218:221], v[96:99]
	v_mfma_f32_16x16x32_bf16 v[88:91], v[190:193], v[226:229], v[88:91]
	v_mfma_f32_16x16x32_bf16 v[80:83], v[202:205], v[226:229], v[80:83]
	v_mfma_f32_16x16x32_bf16 v[72:75], v[190:193], v[234:237], v[72:75]
	v_mfma_f32_16x16x32_bf16 v[64:67], v[202:205], v[234:237], v[64:67]
	v_mfma_f32_16x16x32_bf16 v[120:123], v[194:197], v[214:217], v[120:123]
	v_mfma_f32_16x16x32_bf16 v[112:115], v[206:209], v[214:217], v[112:115]
	v_mfma_f32_16x16x32_bf16 v[104:107], v[194:197], v[222:225], v[104:107]
	v_mfma_f32_16x16x32_bf16 v[96:99], v[206:209], v[222:225], v[96:99]
	v_mfma_f32_16x16x32_bf16 v[88:91], v[194:197], v[230:233], v[88:91]
	v_mfma_f32_16x16x32_bf16 v[80:83], v[206:209], v[230:233], v[80:83]
	v_mfma_f32_16x16x32_bf16 v[72:75], v[194:197], v[238:241], v[72:75]
	v_mfma_f32_16x16x32_bf16 v[64:67], v[206:209], v[238:241], v[64:67]
	s_setprio 0
	s_barrier
	ds_read_b128 v[210:213], v172 offset:49152
	ds_read_b128 v[214:217], v172 offset:50176
	ds_read_b128 v[218:221], v172 offset:51200
	ds_read_b128 v[222:225], v172 offset:52224
	ds_read_b128 v[226:229], v172 offset:53248
	ds_read_b128 v[230:233], v172 offset:54272
	ds_read_b128 v[234:237], v172 offset:55296
	ds_read_b128 v[238:241], v172 offset:56320
	s_add_u32 s42, s40, 0x80
	s_addc_u32 s43, s41, 0
	s_mov_b32 m0, s57
	s_nop 0
	global_load_lds_dwordx4 v161, s[42:43]
	s_add_u32 s40, s40, 0x80080
	s_mov_b32 m0, s58
	s_nop 0
	global_load_lds_dwordx4 v165, s[42:43]
	s_addc_u32 s41, s41, 0
	s_mov_b32 m0, s61
	s_nop 0
	global_load_lds_dwordx4 v161, s[40:41]
	s_nop 0
	s_mov_b32 m0, s62
	s_nop 0
	global_load_lds_dwordx4 v165, s[40:41]
	s_nop 0
	s_nop 0
	s_waitcnt vmcnt(6)
	s_waitcnt lgkmcnt(0)
	s_barrier
	s_setprio 1
	s_waitcnt lgkmcnt(7)
	v_mfma_f32_16x16x32_bf16 v[60:63], v[154:157], v[210:213], v[60:63]
	v_mfma_f32_16x16x32_bf16 v[52:55], v[182:185], v[210:213], v[52:55]
	s_waitcnt lgkmcnt(5)
	v_mfma_f32_16x16x32_bf16 v[44:47], v[154:157], v[218:221], v[44:47]
	v_mfma_f32_16x16x32_bf16 v[36:39], v[182:185], v[218:221], v[36:39]
	s_waitcnt lgkmcnt(3)
	v_mfma_f32_16x16x32_bf16 v[28:31], v[154:157], v[226:229], v[28:31]
	v_mfma_f32_16x16x32_bf16 v[20:23], v[182:185], v[226:229], v[20:23]
	s_waitcnt lgkmcnt(1)
	v_mfma_f32_16x16x32_bf16 v[12:15], v[154:157], v[234:237], v[12:15]
	v_mfma_f32_16x16x32_bf16 v[4:7], v[182:185], v[234:237], v[4:7]
	v_mfma_f32_16x16x32_bf16 v[60:63], v[178:181], v[214:217], v[60:63]
	v_mfma_f32_16x16x32_bf16 v[52:55], v[186:189], v[214:217], v[52:55]
	v_mfma_f32_16x16x32_bf16 v[44:47], v[178:181], v[222:225], v[44:47]
	v_mfma_f32_16x16x32_bf16 v[36:39], v[186:189], v[222:225], v[36:39]
	v_mfma_f32_16x16x32_bf16 v[28:31], v[178:181], v[230:233], v[28:31]
	v_mfma_f32_16x16x32_bf16 v[20:23], v[186:189], v[230:233], v[20:23]
	s_waitcnt lgkmcnt(0)
	v_mfma_f32_16x16x32_bf16 v[12:15], v[178:181], v[238:241], v[12:15]
	v_mfma_f32_16x16x32_bf16 v[4:7], v[186:189], v[238:241], v[4:7]
	s_setprio 0
	s_setprio 1
	v_mfma_f32_16x16x32_bf16 v[56:59], v[190:193], v[210:213], v[56:59]
	v_mfma_f32_16x16x32_bf16 v[48:51], v[202:205], v[210:213], v[48:51]
	v_mfma_f32_16x16x32_bf16 v[40:43], v[190:193], v[218:221], v[40:43]
	v_mfma_f32_16x16x32_bf16 v[32:35], v[202:205], v[218:221], v[32:35]
	v_mfma_f32_16x16x32_bf16 v[24:27], v[190:193], v[226:229], v[24:27]
	v_mfma_f32_16x16x32_bf16 v[16:19], v[202:205], v[226:229], v[16:19]
	v_mfma_f32_16x16x32_bf16 v[8:11], v[190:193], v[234:237], v[8:11]
	v_mfma_f32_16x16x32_bf16 v[0:3], v[202:205], v[234:237], v[0:3]
	v_mfma_f32_16x16x32_bf16 v[56:59], v[194:197], v[214:217], v[56:59]
	v_mfma_f32_16x16x32_bf16 v[48:51], v[206:209], v[214:217], v[48:51]
	v_mfma_f32_16x16x32_bf16 v[40:43], v[194:197], v[222:225], v[40:43]
	v_mfma_f32_16x16x32_bf16 v[32:35], v[206:209], v[222:225], v[32:35]
	v_mfma_f32_16x16x32_bf16 v[24:27], v[194:197], v[230:233], v[24:27]
	v_mfma_f32_16x16x32_bf16 v[16:19], v[206:209], v[230:233], v[16:19]
	v_mfma_f32_16x16x32_bf16 v[8:11], v[194:197], v[238:241], v[8:11]
	v_mfma_f32_16x16x32_bf16 v[0:3], v[206:209], v[238:241], v[0:3]
	s_setprio 0
	s_barrier
	s_add_i32 s72, s72, 2
	s_add_i32 s73, s73, 0x10000
	s_cmp_gt_u32 s72, 29
	s_mov_b64 s[36:37], s[38:39]
	s_cbranch_scc0 .LBB0_371
	s_and_b64 vcc, exec, s[20:21]
	s_cbranch_vccz .LBB0_374
	s_barrier

; #define PG8_STAGE(bufoff, gbase, voff) do { const unsigned long long gb_ = (unsigned long long)(gbase); _Pragma("unroll") for (int _i = 0; _i < 2; ++_i) { unsigned keep_; \
;         asm volatile("s_mov_b32 m0, %2\n\ts_nop 0\n\tglobal_load_lds_dwordx4 %0, %1" : : "v"((voff)[_i]), "s"(gb_), "s"((unsigned)(size_t)(lds + (bufoff) + ldsw + _i * 8192)) : "memory", "m0"); (void)keep_; } } while (0)
; #define PG8_LDA(dst, b, h) do { _Pragma("unroll") for (int m = 0; m < 4; ++m) _Pragma("unroll") for (int k = 0; k < 2; ++k) dst[m][k] = *(const PG8_LAS bf16x8*)(lds + PG8_SA(b, h) + aoff + m * 2048 + k * 1024); } while (0)
; #define PG8_LDB(dst, b, h) do { _Pragma("unroll") for (int n = 0; n < 2; ++n) _Pragma("unroll") for (int k = 0; k < 2; ++k) dst[n][k] = *(const PG8_LAS bf16x8*)(lds + PG8_SB(b, h) + boff + n * 2048 + k * 1024); } while (0)
; #define PG8_MMA(ai, bj, At, Bt) do { __builtin_amdgcn_s_setprio(1); _Pragma("unroll") for (int m = 0; m < 4; ++m) _Pragma("unroll") for (int n = 0; n < 2; ++n) _Pragma("unroll") for (int k = 0; k < 2; ++k) \
;         acc[ai][bj][m][n] = __builtin_amdgcn_mfma_f32_16x16x32_bf16(Bt[n][k], At[m][k], acc[ai][bj][m][n], 0, 0, 0); __builtin_amdgcn_s_setprio(0); } while (0)
; #define PG8_WAIT_V(n) asm volatile("s_waitcnt vmcnt(" #n ")" ::: "memory")
; #define PG8_BAR __builtin_amdgcn_s_barrier()
; template <class Epi, class Sched, bool ALIGN_EPI = false, bool SP2 = false>
; __device__ __forceinline__ void gemm_phase(PG8_LAS unsigned char* lds, const Gemm g, const Sched& S, const Epi& E) {
;     ...
;         for (int t = 0; t < nt; t += 2) {
;             const bool last = (t == nt - 2);
;     ...
;             const char* a1 = cA + PG8_KOFFA(t + 1);
;             const char* a2 = last ? nA : cA + PG8_KOFFA(t + 2); const char* b2 = last ? nB : cB + (size_t)(t + 2) * kstep;
;             const char* a3 = last ? nA + kstep : cA + PG8_KOFFA(t + 3); const char* b3 = b2 + kstep;
;     ...
;             if (last && has_next) S.a_ready(nxt);
;             if constexpr (SP2) {
;             PG8_LDB(B0, 0, 0); PG8_LDB(B1, 0, 1); PG8_SCHED; PG8_LDA(At, 0, 0); PG8_STAGE(PG8_SA(1, 1), a1 + hstepA, voffA);
;             PG8_WAIT_V(8); PG8_WAIT_L(0); PG8_BAR; PG8_MMA(0, 0, At, B0); PG8_MMA(0, 1, At, B1); PG8_BAR; PG8_SCHED;
;             PG8_LDA(At, 0, 1); PG8_STAGE(PG8_SB(0, 0), b2, voffB); PG8_STAGE(PG8_SB(0, 1), b2 + hstepB, voffB); PG8_STAGE(PG8_SA(0, 0), a2, voffA);
.LBB0_511:
	ds_read_b128 v[128:131], v180
	ds_read_b128 v[132:135], v180 offset:1024
	ds_read_b128 v[136:139], v180 offset:2048
	ds_read_b128 v[140:143], v180 offset:3072
	ds_read_b128 v[168:171], v181
	ds_read_b128 v[172:175], v181 offset:1024
	ds_read_b128 v[186:189], v181 offset:2048
	ds_read_b128 v[190:193], v181 offset:3072
	s_add_u32 s28, s26, 0x10000
	s_addc_u32 s29, s27, 0
	s_cmpk_eq_i32 s64, 0x54
	s_cselect_b32 s36, s10, s28
	s_cselect_b32 s37, s11, s29
	s_cselect_b32 s34, s24, s0
	s_cselect_b32 s35, s25, s1
	s_add_u32 s30, s36, 0x80
	s_addc_u32 s31, s37, 0
	ds_read_b128 v[194:197], v182
	ds_read_b128 v[202:205], v182 offset:1024
	ds_read_b128 v[206:209], v182 offset:2048
	ds_read_b128 v[210:213], v182 offset:3072
	ds_read_b128 v[214:217], v182 offset:4096
	ds_read_b128 v[218:221], v182 offset:5120
	ds_read_b128 v[222:225], v182 offset:6144
	ds_read_b128 v[226:229], v182 offset:7168
	s_add_u32 s26, s26, 0x8080
	s_addc_u32 s27, s27, 0
	s_sub_u32 s98, s26, 0x8000
	s_subb_u32 s99, s27, 0
	s_mov_b32 m0, s52
	s_nop 0
	global_load_lds_dwordx4 v176, s[98:99]
	s_nop 0
	s_mov_b32 m0, s53
	s_nop 0
	global_load_lds_dwordx4 v178, s[98:99]
	s_nop 0
	s_mov_b32 m0, s56
	s_nop 0
	global_load_lds_dwordx4 v176, s[26:27]
	s_nop 0
	s_mov_b32 m0, s57
	s_nop 0
	global_load_lds_dwordx4 v178, s[26:27]
	s_waitcnt vmcnt(8)
	s_waitcnt lgkmcnt(0)
	s_barrier
	s_setprio 1
	s_waitcnt lgkmcnt(7)
	v_mfma_f32_16x16x32_bf16 v[124:127], v[128:131], v[194:197], v[124:127]
	v_mfma_f32_16x16x32_bf16 v[120:123], v[136:139], v[194:197], v[120:123]
	s_waitcnt lgkmcnt(5)
	v_mfma_f32_16x16x32_bf16 v[108:111], v[128:131], v[206:209], v[108:111]
	v_mfma_f32_16x16x32_bf16 v[104:107], v[136:139], v[206:209], v[104:107]
	s_waitcnt lgkmcnt(3)
	v_mfma_f32_16x16x32_bf16 v[92:95], v[128:131], v[214:217], v[92:95]
	v_mfma_f32_16x16x32_bf16 v[88:91], v[136:139], v[214:217], v[88:91]
	s_waitcnt lgkmcnt(1)
	v_mfma_f32_16x16x32_bf16 v[76:79], v[128:131], v[222:225], v[76:79]
	v_mfma_f32_16x16x32_bf16 v[72:75], v[136:139], v[222:225], v[72:75]
	v_mfma_f32_16x16x32_bf16 v[124:127], v[132:135], v[202:205], v[124:127]
	v_mfma_f32_16x16x32_bf16 v[120:123], v[140:143], v[202:205], v[120:123]
	v_mfma_f32_16x16x32_bf16 v[108:111], v[132:135], v[210:213], v[108:111]
	v_mfma_f32_16x16x32_bf16 v[104:107], v[140:143], v[210:213], v[104:107]
	v_mfma_f32_16x16x32_bf16 v[92:95], v[132:135], v[218:221], v[92:95]
	v_mfma_f32_16x16x32_bf16 v[88:91], v[140:143], v[218:221], v[88:91]
	s_waitcnt lgkmcnt(0)
	v_mfma_f32_16x16x32_bf16 v[76:79], v[132:135], v[226:229], v[76:79]
	v_mfma_f32_16x16x32_bf16 v[72:75], v[140:143], v[226:229], v[72:75]
	s_setprio 0
	s_setprio 1
	v_mfma_f32_16x16x32_bf16 v[116:119], v[168:171], v[194:197], v[116:119]
	v_mfma_f32_16x16x32_bf16 v[112:115], v[186:189], v[194:197], v[112:115]
	v_mfma_f32_16x16x32_bf16 v[100:103], v[168:171], v[206:209], v[100:103]
	v_mfma_f32_16x16x32_bf16 v[96:99], v[186:189], v[206:209], v[96:99]
	v_mfma_f32_16x16x32_bf16 v[84:87], v[168:171], v[214:217], v[84:87]
	v_mfma_f32_16x16x32_bf16 v[80:83], v[186:189], v[214:217], v[80:83]
	v_mfma_f32_16x16x32_bf16 v[68:71], v[168:171], v[222:225], v[68:71]
	v_mfma_f32_16x16x32_bf16 v[64:67], v[186:189], v[222:225], v[64:67]
	v_mfma_f32_16x16x32_bf16 v[116:119], v[172:175], v[202:205], v[116:119]
	v_mfma_f32_16x16x32_bf16 v[112:115], v[190:193], v[202:205], v[112:115]
	v_mfma_f32_16x16x32_bf16 v[100:103], v[172:175], v[210:213], v[100:103]
	v_mfma_f32_16x16x32_bf16 v[96:99], v[190:193], v[210:213], v[96:99]
	v_mfma_f32_16x16x32_bf16 v[84:87], v[172:175], v[218:221], v[84:87]
	v_mfma_f32_16x16x32_bf16 v[80:83], v[190:193], v[218:221], v[80:83]
	v_mfma_f32_16x16x32_bf16 v[68:71], v[172:175], v[226:229], v[68:71]
	v_mfma_f32_16x16x32_bf16 v[64:67], v[190:193], v[226:229], v[64:67]
	s_setprio 0
	s_barrier
	ds_read_b128 v[194:197], v182 offset:16384
	ds_read_b128 v[202:205], v182 offset:17408
	ds_read_b128 v[206:209], v182 offset:18432
	ds_read_b128 v[210:213], v182 offset:19456
	ds_read_b128 v[214:217], v182 offset:20480
	ds_read_b128 v[218:221], v182 offset:21504
	ds_read_b128 v[222:225], v182 offset:22528
	ds_read_b128 v[226:229], v182 offset:23552
	s_mov_b32 m0, s42
	s_nop 0
	global_load_lds_dwordx4 v177, s[34:35]
	s_add_u32 s26, s34, 0x160000
	s_mov_b32 m0, s43
	s_nop 0
	global_load_lds_dwordx4 v179, s[34:35]
	s_addc_u32 s27, s35, 0
	s_mov_b32 m0, s44
	s_nop 0
	global_load_lds_dwordx4 v177, s[26:27]
	s_nop 0
	s_mov_b32 m0, s45
	s_nop 0
	global_load_lds_dwordx4 v179, s[26:27]
	s_nop 0
	s_nop 0
	s_waitcnt vmcnt(6)
	s_waitcnt lgkmcnt(0)
	s_barrier
; #define PG8_STAGE(bufoff, gbase, voff) do { const unsigned long long gb_ = (unsigned long long)(gbase); _Pragma("unroll") for (int _i = 0; _i < 2; ++_i) { unsigned keep_; \
;         asm volatile("s_mov_b32 m0, %2\n\ts_nop 0\n\tglobal_load_lds_dwordx4 %0, %1" : : "v"((voff)[_i]), "s"(gb_), "s"((unsigned)(size_t)(lds + (bufoff) + ldsw + _i * 8192)) : "memory", "m0"); (void)keep_; } } while (0)
; #define PG8_LDA(dst, b, h) do { _Pragma("unroll") for (int m = 0; m < 4; ++m) _Pragma("unroll") for (int k = 0; k < 2; ++k) dst[m][k] = *(const PG8_LAS bf16x8*)(lds + PG8_SA(b, h) + aoff + m * 2048 + k * 1024); } while (0)
; #define PG8_LDB(dst, b, h) do { _Pragma("unroll") for (int n = 0; n < 2; ++n) _Pragma("unroll") for (int k = 0; k < 2; ++k) dst[n][k] = *(const PG8_LAS bf16x8*)(lds + PG8_SB(b, h) + boff + n * 2048 + k * 1024); } while (0)
; #define PG8_MMA(ai, bj, At, Bt) do { __builtin_amdgcn_s_setprio(1); _Pragma("unroll") for (int m = 0; m < 4; ++m) _Pragma("unroll") for (int n = 0; n < 2; ++n) _Pragma("unroll") for (int k = 0; k < 2; ++k) \
;         acc[ai][bj][m][n] = __builtin_amdgcn_mfma_f32_16x16x32_bf16(Bt[n][k], At[m][k], acc[ai][bj][m][n], 0, 0, 0); __builtin_amdgcn_s_setprio(0); } while (0)
; #define PG8_WAIT_V(n) asm volatile("s_waitcnt vmcnt(" #n ")" ::: "memory")
; #define PG8_WAIT_L(n) asm volatile("s_waitcnt lgkmcnt(" #n ")" ::: "memory")
; #define PG8_BAR __builtin_amdgcn_s_barrier()
; #define PG8_SCHED __builtin_amdgcn_sched_barrier(0)
; template <class Epi, class Sched, bool ALIGN_EPI = false, bool SP2 = false>
; __device__ __forceinline__ void gemm_phase(PG8_LAS unsigned char* lds, const Gemm g, const Sched& S, const Epi& E) {
;     ...
;             PG8_WAIT_V(8); PG8_WAIT_L(0); PG8_BAR; PG8_MMA(1, 0, At, B0); PG8_MMA(1, 1, At, B1); PG8_BAR; PG8_SCHED;
;             PG8_LDB(B0, 1, 0); PG8_LDB(B1, 1, 1); PG8_SCHED; PG8_LDA(At, 1, 0); PG8_STAGE(PG8_SA(0, 1), a2 + hstepA, voffA);
	s_setprio 1
	s_waitcnt lgkmcnt(7)
	v_mfma_f32_16x16x32_bf16 v[60:63], v[128:131], v[194:197], v[60:63]
	v_mfma_f32_16x16x32_bf16 v[56:59], v[136:139], v[194:197], v[56:59]
	s_waitcnt lgkmcnt(5)
	v_mfma_f32_16x16x32_bf16 v[44:47], v[128:131], v[206:209], v[44:47]
	v_mfma_f32_16x16x32_bf16 v[40:43], v[136:139], v[206:209], v[40:43]
	s_waitcnt lgkmcnt(3)
	v_mfma_f32_16x16x32_bf16 v[28:31], v[128:131], v[214:217], v[28:31]
	v_mfma_f32_16x16x32_bf16 v[24:27], v[136:139], v[214:217], v[24:27]
	s_waitcnt lgkmcnt(1)
	v_mfma_f32_16x16x32_bf16 v[12:15], v[128:131], v[222:225], v[12:15]
	v_mfma_f32_16x16x32_bf16 v[8:11], v[136:139], v[222:225], v[8:11]
	v_mfma_f32_16x16x32_bf16 v[60:63], v[132:135], v[202:205], v[60:63]
	v_mfma_f32_16x16x32_bf16 v[56:59], v[140:143], v[202:205], v[56:59]
	v_mfma_f32_16x16x32_bf16 v[44:47], v[132:135], v[210:213], v[44:47]
	v_mfma_f32_16x16x32_bf16 v[40:43], v[140:143], v[210:213], v[40:43]
	v_mfma_f32_16x16x32_bf16 v[28:31], v[132:135], v[218:221], v[28:31]
	v_mfma_f32_16x16x32_bf16 v[24:27], v[140:143], v[218:221], v[24:27]
	s_waitcnt lgkmcnt(0)
	v_mfma_f32_16x16x32_bf16 v[12:15], v[132:135], v[226:229], v[12:15]
	v_mfma_f32_16x16x32_bf16 v[8:11], v[140:143], v[226:229], v[8:11]
	s_setprio 0
	s_setprio 1
	v_mfma_f32_16x16x32_bf16 v[52:55], v[168:171], v[194:197], v[52:55]
	v_mfma_f32_16x16x32_bf16 v[48:51], v[186:189], v[194:197], v[48:51]
	v_mfma_f32_16x16x32_bf16 v[36:39], v[168:171], v[206:209], v[36:39]
	v_mfma_f32_16x16x32_bf16 v[32:35], v[186:189], v[206:209], v[32:35]
	v_mfma_f32_16x16x32_bf16 v[20:23], v[168:171], v[214:217], v[20:23]
	v_mfma_f32_16x16x32_bf16 v[16:19], v[186:189], v[214:217], v[16:19]
	v_mfma_f32_16x16x32_bf16 v[4:7], v[168:171], v[222:225], v[4:7]
	v_mfma_f32_16x16x32_bf16 v[0:3], v[186:189], v[222:225], v[0:3]
	v_mfma_f32_16x16x32_bf16 v[52:55], v[172:175], v[202:205], v[52:55]
	v_mfma_f32_16x16x32_bf16 v[48:51], v[190:193], v[202:205], v[48:51]
	v_mfma_f32_16x16x32_bf16 v[36:39], v[172:175], v[210:213], v[36:39]
	v_mfma_f32_16x16x32_bf16 v[32:35], v[190:193], v[210:213], v[32:35]
	v_mfma_f32_16x16x32_bf16 v[20:23], v[172:175], v[218:221], v[20:23]
	v_mfma_f32_16x16x32_bf16 v[16:19], v[190:193], v[218:221], v[16:19]
	v_mfma_f32_16x16x32_bf16 v[4:7], v[172:175], v[226:229], v[4:7]
	v_mfma_f32_16x16x32_bf16 v[0:3], v[190:193], v[226:229], v[0:3]
	s_setprio 0
	s_barrier
	ds_read_b128 v[128:131], v183
	ds_read_b128 v[132:135], v183 offset:1024
	ds_read_b128 v[136:139], v183 offset:2048
	ds_read_b128 v[140:143], v183 offset:3072
	ds_read_b128 v[168:171], v184
	ds_read_b128 v[172:175], v184 offset:1024
	ds_read_b128 v[186:189], v184 offset:2048
	ds_read_b128 v[190:193], v184 offset:3072
	ds_read_b128 v[194:197], v182 offset:32768
	ds_read_b128 v[202:205], v182 offset:33792
	ds_read_b128 v[206:209], v182 offset:34816
	ds_read_b128 v[210:213], v182 offset:35840
	ds_read_b128 v[214:217], v182 offset:36864
	ds_read_b128 v[218:221], v182 offset:37888
	ds_read_b128 v[222:225], v182 offset:38912
	ds_read_b128 v[226:229], v182 offset:39936
	s_mov_b32 m0, s41
	s_nop 0
	global_load_lds_dwordx4 v176, s[36:37]
	s_nop 0
	s_mov_b32 m0, s46
	s_nop 0
	global_load_lds_dwordx4 v178, s[36:37]
	s_nop 0
	s_add_u32 s26, s36, 0x8000
	s_addc_u32 s27, s37, 0
	s_mov_b32 m0, s47
	s_nop 0
	global_load_lds_dwordx4 v176, s[26:27]
	s_nop 0
	s_mov_b32 m0, s48
	s_nop 0
	global_load_lds_dwordx4 v178, s[26:27]
	s_waitcnt vmcnt(8)
	s_waitcnt lgkmcnt(0)
	s_barrier
; #define PG8_STAGE(bufoff, gbase, voff) do { const unsigned long long gb_ = (unsigned long long)(gbase); _Pragma("unroll") for (int _i = 0; _i < 2; ++_i) { unsigned keep_; \
;         asm volatile("s_mov_b32 m0, %2\n\ts_nop 0\n\tglobal_load_lds_dwordx4 %0, %1" : : "v"((voff)[_i]), "s"(gb_), "s"((unsigned)(size_t)(lds + (bufoff) + ldsw + _i * 8192)) : "memory", "m0"); (void)keep_; } } while (0)
; #define PG8_LDA(dst, b, h) do { _Pragma("unroll") for (int m = 0; m < 4; ++m) _Pragma("unroll") for (int k = 0; k < 2; ++k) dst[m][k] = *(const PG8_LAS bf16x8*)(lds + PG8_SA(b, h) + aoff + m * 2048 + k * 1024); } while (0)
; #define PG8_MMA(ai, bj, At, Bt) do { __builtin_amdgcn_s_setprio(1); _Pragma("unroll") for (int m = 0; m < 4; ++m) _Pragma("unroll") for (int n = 0; n < 2; ++n) _Pragma("unroll") for (int k = 0; k < 2; ++k) \
;         acc[ai][bj][m][n] = __builtin_amdgcn_mfma_f32_16x16x32_bf16(Bt[n][k], At[m][k], acc[ai][bj][m][n], 0, 0, 0); __builtin_amdgcn_s_setprio(0); } while (0)
; #define PG8_WAIT_V(n) asm volatile("s_waitcnt vmcnt(" #n ")" ::: "memory")
; #define PG8_WAIT_L(n) asm volatile("s_waitcnt lgkmcnt(" #n ")" ::: "memory")
; #define PG8_BAR __builtin_amdgcn_s_barrier()
; #define PG8_SCHED __builtin_amdgcn_sched_barrier(0)
; template <class Epi, class Sched, bool ALIGN_EPI = false, bool SP2 = false>
; __device__ __forceinline__ void gemm_phase(PG8_LAS unsigned char* lds, const Gemm g, const Sched& S, const Epi& E) {
;     ...
;             PG8_WAIT_V(8); PG8_WAIT_L(0); PG8_BAR; PG8_MMA(0, 0, At, B0); PG8_MMA(0, 1, At, B1); PG8_BAR; PG8_SCHED;
;             PG8_LDA(At, 1, 1); PG8_STAGE(PG8_SB(1, 0), b3, voffB); PG8_STAGE(PG8_SB(1, 1), b3 + hstepB, voffB); PG8_STAGE(PG8_SA(1, 0), a3, voffA);
;             PG8_WAIT_V(8); PG8_WAIT_L(0); PG8_BAR; PG8_MMA(1, 0, At, B0); PG8_MMA(1, 1, At, B1); PG8_BAR; PG8_SCHED;
	s_setprio 1
	s_waitcnt lgkmcnt(7)
	v_mfma_f32_16x16x32_bf16 v[124:127], v[128:131], v[194:197], v[124:127]
	v_mfma_f32_16x16x32_bf16 v[120:123], v[136:139], v[194:197], v[120:123]
	s_waitcnt lgkmcnt(5)
	v_mfma_f32_16x16x32_bf16 v[108:111], v[128:131], v[206:209], v[108:111]
	v_mfma_f32_16x16x32_bf16 v[104:107], v[136:139], v[206:209], v[104:107]
	s_waitcnt lgkmcnt(3)
	v_mfma_f32_16x16x32_bf16 v[92:95], v[128:131], v[214:217], v[92:95]
	v_mfma_f32_16x16x32_bf16 v[88:91], v[136:139], v[214:217], v[88:91]
	s_waitcnt lgkmcnt(1)
	v_mfma_f32_16x16x32_bf16 v[76:79], v[128:131], v[222:225], v[76:79]
	v_mfma_f32_16x16x32_bf16 v[72:75], v[136:139], v[222:225], v[72:75]
	v_mfma_f32_16x16x32_bf16 v[124:127], v[132:135], v[202:205], v[124:127]
	v_mfma_f32_16x16x32_bf16 v[120:123], v[140:143], v[202:205], v[120:123]
	v_mfma_f32_16x16x32_bf16 v[108:111], v[132:135], v[210:213], v[108:111]
	v_mfma_f32_16x16x32_bf16 v[104:107], v[140:143], v[210:213], v[104:107]
	v_mfma_f32_16x16x32_bf16 v[92:95], v[132:135], v[218:221], v[92:95]
	v_mfma_f32_16x16x32_bf16 v[88:91], v[140:143], v[218:221], v[88:91]
	s_waitcnt lgkmcnt(0)
	v_mfma_f32_16x16x32_bf16 v[76:79], v[132:135], v[226:229], v[76:79]
	v_mfma_f32_16x16x32_bf16 v[72:75], v[140:143], v[226:229], v[72:75]
	s_setprio 0
	s_setprio 1
	v_mfma_f32_16x16x32_bf16 v[116:119], v[168:171], v[194:197], v[116:119]
	v_mfma_f32_16x16x32_bf16 v[112:115], v[186:189], v[194:197], v[112:115]
	v_mfma_f32_16x16x32_bf16 v[100:103], v[168:171], v[206:209], v[100:103]
	v_mfma_f32_16x16x32_bf16 v[96:99], v[186:189], v[206:209], v[96:99]
	v_mfma_f32_16x16x32_bf16 v[84:87], v[168:171], v[214:217], v[84:87]
	v_mfma_f32_16x16x32_bf16 v[80:83], v[186:189], v[214:217], v[80:83]
	v_mfma_f32_16x16x32_bf16 v[68:71], v[168:171], v[222:225], v[68:71]
	v_mfma_f32_16x16x32_bf16 v[64:67], v[186:189], v[222:225], v[64:67]
	v_mfma_f32_16x16x32_bf16 v[116:119], v[172:175], v[202:205], v[116:119]
	v_mfma_f32_16x16x32_bf16 v[112:115], v[190:193], v[202:205], v[112:115]
	v_mfma_f32_16x16x32_bf16 v[100:103], v[172:175], v[210:213], v[100:103]
	v_mfma_f32_16x16x32_bf16 v[96:99], v[190:193], v[210:213], v[96:99]
	v_mfma_f32_16x16x32_bf16 v[84:87], v[172:175], v[218:221], v[84:87]
	v_mfma_f32_16x16x32_bf16 v[80:83], v[190:193], v[218:221], v[80:83]
	v_mfma_f32_16x16x32_bf16 v[68:71], v[172:175], v[226:229], v[68:71]
	v_mfma_f32_16x16x32_bf16 v[64:67], v[190:193], v[226:229], v[64:67]
	s_setprio 0
	s_barrier
	ds_read_b128 v[194:197], v182 offset:49152
	ds_read_b128 v[202:205], v182 offset:50176
	ds_read_b128 v[206:209], v182 offset:51200
	ds_read_b128 v[210:213], v182 offset:52224
	ds_read_b128 v[214:217], v182 offset:53248
	ds_read_b128 v[218:221], v182 offset:54272
	ds_read_b128 v[222:225], v182 offset:55296
	ds_read_b128 v[226:229], v182 offset:56320
	s_add_u32 s26, s34, 0x80
	s_addc_u32 s27, s35, 0
	s_mov_b32 m0, s50
	s_nop 0
	global_load_lds_dwordx4 v177, s[26:27]
	s_nop 0
	s_mov_b32 m0, s51
	s_nop 0
	global_load_lds_dwordx4 v179, s[26:27]
	s_add_u32 s26, s34, 0x160080
	s_addc_u32 s27, s35, 0
	s_mov_b32 m0, s54
	s_nop 0
	global_load_lds_dwordx4 v177, s[26:27]
	s_nop 0
	s_mov_b32 m0, s55
	s_nop 0
	global_load_lds_dwordx4 v179, s[26:27]
	s_nop 0
	s_nop 0
	s_waitcnt vmcnt(6)
	s_waitcnt lgkmcnt(0)
	s_barrier
	s_setprio 1
	s_waitcnt lgkmcnt(7)
	v_mfma_f32_16x16x32_bf16 v[60:63], v[128:131], v[194:197], v[60:63]
	v_mfma_f32_16x16x32_bf16 v[56:59], v[136:139], v[194:197], v[56:59]
	s_waitcnt lgkmcnt(5)
	v_mfma_f32_16x16x32_bf16 v[44:47], v[128:131], v[206:209], v[44:47]
	v_mfma_f32_16x16x32_bf16 v[40:43], v[136:139], v[206:209], v[40:43]
	s_waitcnt lgkmcnt(3)
	v_mfma_f32_16x16x32_bf16 v[28:31], v[128:131], v[214:217], v[28:31]
	v_mfma_f32_16x16x32_bf16 v[24:27], v[136:139], v[214:217], v[24:27]
	s_waitcnt lgkmcnt(1)
	v_mfma_f32_16x16x32_bf16 v[12:15], v[128:131], v[222:225], v[12:15]
	v_mfma_f32_16x16x32_bf16 v[8:11], v[136:139], v[222:225], v[8:11]
	v_mfma_f32_16x16x32_bf16 v[60:63], v[132:135], v[202:205], v[60:63]
	v_mfma_f32_16x16x32_bf16 v[56:59], v[140:143], v[202:205], v[56:59]
	v_mfma_f32_16x16x32_bf16 v[44:47], v[132:135], v[210:213], v[44:47]
	v_mfma_f32_16x16x32_bf16 v[40:43], v[140:143], v[210:213], v[40:43]
	v_mfma_f32_16x16x32_bf16 v[28:31], v[132:135], v[218:221], v[28:31]
	v_mfma_f32_16x16x32_bf16 v[24:27], v[140:143], v[218:221], v[24:27]
	s_waitcnt lgkmcnt(0)
	v_mfma_f32_16x16x32_bf16 v[12:15], v[132:135], v[226:229], v[12:15]
	v_mfma_f32_16x16x32_bf16 v[8:11], v[140:143], v[226:229], v[8:11]
	s_setprio 0
	s_setprio 1
	v_mfma_f32_16x16x32_bf16 v[52:55], v[168:171], v[194:197], v[52:55]
	v_mfma_f32_16x16x32_bf16 v[48:51], v[186:189], v[194:197], v[48:51]
	v_mfma_f32_16x16x32_bf16 v[36:39], v[168:171], v[206:209], v[36:39]
	v_mfma_f32_16x16x32_bf16 v[32:35], v[186:189], v[206:209], v[32:35]
	v_mfma_f32_16x16x32_bf16 v[20:23], v[168:171], v[214:217], v[20:23]
	v_mfma_f32_16x16x32_bf16 v[16:19], v[186:189], v[214:217], v[16:19]
	v_mfma_f32_16x16x32_bf16 v[4:7], v[168:171], v[222:225], v[4:7]
	v_mfma_f32_16x16x32_bf16 v[0:3], v[186:189], v[222:225], v[0:3]
	v_mfma_f32_16x16x32_bf16 v[52:55], v[172:175], v[202:205], v[52:55]
	v_mfma_f32_16x16x32_bf16 v[48:51], v[190:193], v[202:205], v[48:51]
	v_mfma_f32_16x16x32_bf16 v[36:39], v[172:175], v[210:213], v[36:39]
	v_mfma_f32_16x16x32_bf16 v[32:35], v[190:193], v[210:213], v[32:35]
	v_mfma_f32_16x16x32_bf16 v[20:23], v[172:175], v[218:221], v[20:23]
	v_mfma_f32_16x16x32_bf16 v[16:19], v[190:193], v[218:221], v[16:19]
	v_mfma_f32_16x16x32_bf16 v[4:7], v[172:175], v[226:229], v[4:7]
	v_mfma_f32_16x16x32_bf16 v[0:3], v[190:193], v[226:229], v[0:3]
	s_setprio 0
	s_barrier
	s_add_i32 s64, s64, 2
	s_add_u32 s0, s0, 0x100
	s_addc_u32 s1, s1, 0
	s_cmpk_gt_u32 s64, 0x55
	s_mov_b64 s[26:27], s[28:29]
	s_cbranch_scc0 .LBB0_511
	s_and_b64 vcc, exec, s[22:23]
	s_cbranch_vccz .LBB0_514
	s_barrier

; #define PG8_STAGE(bufoff, gbase, voff) do { const unsigned long long gb_ = (unsigned long long)(gbase); _Pragma("unroll") for (int _i = 0; _i < 2; ++_i) { unsigned keep_; \
;         asm volatile("s_mov_b32 m0, %2\n\ts_nop 0\n\tglobal_load_lds_dwordx4 %0, %1" : : "v"((voff)[_i]), "s"(gb_), "s"((unsigned)(size_t)(lds + (bufoff) + ldsw + _i * 8192)) : "memory", "m0"); (void)keep_; } } while (0)
; #define PG8_LDA(dst, b, h) do { _Pragma("unroll") for (int m = 0; m < 4; ++m) _Pragma("unroll") for (int k = 0; k < 2; ++k) dst[m][k] = *(const PG8_LAS bf16x8*)(lds + PG8_SA(b, h) + aoff + m * 2048 + k * 1024); } while (0)
; #define PG8_LDB(dst, b, h) do { _Pragma("unroll") for (int n = 0; n < 2; ++n) _Pragma("unroll") for (int k = 0; k < 2; ++k) dst[n][k] = *(const PG8_LAS bf16x8*)(lds + PG8_SB(b, h) + boff + n * 2048 + k * 1024); } while (0)
; #define PG8_MMA(ai, bj, At, Bt) do { __builtin_amdgcn_s_setprio(1); _Pragma("unroll") for (int m = 0; m < 4; ++m) _Pragma("unroll") for (int n = 0; n < 2; ++n) _Pragma("unroll") for (int k = 0; k < 2; ++k) \
;         acc[ai][bj][m][n] = __builtin_amdgcn_mfma_f32_16x16x32_bf16(Bt[n][k], At[m][k], acc[ai][bj][m][n], 0, 0, 0); __builtin_amdgcn_s_setprio(0); } while (0)
; #define PG8_WAIT_V(n) asm volatile("s_waitcnt vmcnt(" #n ")" ::: "memory")
; #define PG8_BAR __builtin_amdgcn_s_barrier()
; template <class Epi, class Sched, bool ALIGN_EPI = false, bool SP2 = false>
; __device__ __forceinline__ void gemm_phase(PG8_LAS unsigned char* lds, const Gemm g, const Sched& S, const Epi& E) {
;     ...
;         for (int t = 0; t < nt; t += 2) {
;             const bool last = (t == nt - 2);
;     ...
;             const char* a1 = cA + PG8_KOFFA(t + 1);
;             const char* a2 = last ? nA : cA + PG8_KOFFA(t + 2); const char* b2 = last ? nB : cB + (size_t)(t + 2) * kstep;
;             const char* a3 = last ? nA + kstep : cA + PG8_KOFFA(t + 3); const char* b3 = b2 + kstep;
;     ...
;             if (last && has_next) S.a_ready(nxt);
;             if constexpr (SP2) {
;             PG8_LDB(B0, 0, 0); PG8_LDB(B1, 0, 1); PG8_SCHED; PG8_LDA(At, 0, 0); PG8_STAGE(PG8_SA(1, 1), a1 + hstepA, voffA);
;             PG8_WAIT_V(8); PG8_WAIT_L(0); PG8_BAR; PG8_MMA(0, 0, At, B0); PG8_MMA(0, 1, At, B1); PG8_BAR; PG8_SCHED;
;             PG8_LDA(At, 0, 1); PG8_STAGE(PG8_SB(0, 0), b2, voffB); PG8_STAGE(PG8_SB(0, 1), b2 + hstepB, voffB); PG8_STAGE(PG8_SA(0, 0), a2, voffA);
.LBB0_632:
	s_add_i32 s57, s84, 0xfffe8000
	s_and_b32 s56, s52, 0x100
	s_and_b32 s57, s57, 0xe0000
	s_or_b32 s56, s56, s57
	s_add_u32 s85, s10, s56
	s_addc_u32 s87, s11, 0
	s_add_u32 s56, s52, 0x100
	s_addc_u32 s57, s53, 0
	s_add_i32 s59, s84, 0xffff8000
	s_and_b32 s58, s56, 0x100
	s_and_b32 s59, s59, 0x1e0000
	s_or_b32 s58, s59, s58
	ds_read_b128 v[182:185], v173
	ds_read_b128 v[186:189], v173 offset:1024
	ds_read_b128 v[194:197], v173 offset:2048
	ds_read_b128 v[202:205], v173 offset:3072
	ds_read_b128 v[206:209], v177
	ds_read_b128 v[210:213], v177 offset:1024
	ds_read_b128 v[214:217], v177 offset:2048
	ds_read_b128 v[218:221], v177 offset:3072
	s_add_u32 s58, s10, s58
	s_addc_u32 s59, s11, 0
	s_add_u32 s86, s45, s52
	s_addc_u32 s53, s51, s53
	s_add_i32 s60, s52, 0x180
	s_and_b32 s60, s60, 0x180
	s_and_b32 s61, s84, 0x1e0000
	s_or_b32 s60, s61, s60
	s_add_u32 s90, s10, s60
	s_addc_u32 s91, s11, 0
	s_cmpk_eq_i32 s52, 0xf00
	s_cselect_b32 s61, s0, s59
	s_cselect_b32 s59, s4, s53
	s_cselect_b32 s53, s43, s91
	s_cselect_b32 s52, s16, s90
	s_cselect_b32 s60, s1, s58
	s_cselect_b32 s58, s5, s86
	ds_read_b128 v[222:225], v181
	ds_read_b128 v[226:229], v181 offset:1024
	ds_read_b128 v[230:233], v181 offset:2048
	ds_read_b128 v[234:237], v181 offset:3072
	ds_read_b128 v[238:241], v181 offset:4096
	ds_read_b128 v[242:245], v181 offset:5120
	ds_read_b128 v[246:249], v181 offset:6144
	ds_read_b128 v[250:253], v181 offset:7168
	s_add_u32 s86, s85, 0x10080
	s_addc_u32 s87, s87, 0
	s_sub_u32 s98, s86, 0x10000
	s_subb_u32 s99, s87, 0
	s_mov_b32 m0, s73
	s_nop 0
	global_load_lds_dwordx4 v157, s[98:99]
	s_nop 0
	s_mov_b32 m0, s76
	s_nop 0
	global_load_lds_dwordx4 v165, s[98:99]
	s_nop 0
	s_mov_b32 m0, s79
	s_nop 0
	global_load_lds_dwordx4 v157, s[86:87]
	s_nop 0
	s_mov_b32 m0, s80
	s_nop 0
	global_load_lds_dwordx4 v165, s[86:87]
	s_waitcnt vmcnt(8)
	s_waitcnt lgkmcnt(0)
	s_barrier
	s_setprio 1
	s_waitcnt lgkmcnt(7)
	v_mfma_f32_16x16x32_bf16 v[124:127], v[182:185], v[222:225], v[124:127]
	v_mfma_f32_16x16x32_bf16 v[120:123], v[194:197], v[222:225], v[120:123]
	s_waitcnt lgkmcnt(5)
	v_mfma_f32_16x16x32_bf16 v[108:111], v[182:185], v[230:233], v[108:111]
	v_mfma_f32_16x16x32_bf16 v[104:107], v[194:197], v[230:233], v[104:107]
	s_waitcnt lgkmcnt(3)
	v_mfma_f32_16x16x32_bf16 v[92:95], v[182:185], v[238:241], v[92:95]
	v_mfma_f32_16x16x32_bf16 v[88:91], v[194:197], v[238:241], v[88:91]
	s_waitcnt lgkmcnt(1)
	v_mfma_f32_16x16x32_bf16 v[76:79], v[182:185], v[246:249], v[76:79]
	v_mfma_f32_16x16x32_bf16 v[72:75], v[194:197], v[246:249], v[72:75]
	v_mfma_f32_16x16x32_bf16 v[124:127], v[186:189], v[226:229], v[124:127]
	v_mfma_f32_16x16x32_bf16 v[120:123], v[202:205], v[226:229], v[120:123]
	v_mfma_f32_16x16x32_bf16 v[108:111], v[186:189], v[234:237], v[108:111]
	v_mfma_f32_16x16x32_bf16 v[104:107], v[202:205], v[234:237], v[104:107]
	v_mfma_f32_16x16x32_bf16 v[92:95], v[186:189], v[242:245], v[92:95]
	v_mfma_f32_16x16x32_bf16 v[88:91], v[202:205], v[242:245], v[88:91]
	s_waitcnt lgkmcnt(0)
	v_mfma_f32_16x16x32_bf16 v[76:79], v[186:189], v[250:253], v[76:79]
	v_mfma_f32_16x16x32_bf16 v[72:75], v[202:205], v[250:253], v[72:75]
	s_setprio 0
	s_setprio 1
	v_mfma_f32_16x16x32_bf16 v[116:119], v[206:209], v[222:225], v[116:119]
	v_mfma_f32_16x16x32_bf16 v[112:115], v[214:217], v[222:225], v[112:115]
	v_mfma_f32_16x16x32_bf16 v[100:103], v[206:209], v[230:233], v[100:103]
	v_mfma_f32_16x16x32_bf16 v[96:99], v[214:217], v[230:233], v[96:99]
	v_mfma_f32_16x16x32_bf16 v[84:87], v[206:209], v[238:241], v[84:87]
	v_mfma_f32_16x16x32_bf16 v[80:83], v[214:217], v[238:241], v[80:83]
	v_mfma_f32_16x16x32_bf16 v[68:71], v[206:209], v[246:249], v[68:71]
	v_mfma_f32_16x16x32_bf16 v[64:67], v[214:217], v[246:249], v[64:67]
	v_mfma_f32_16x16x32_bf16 v[116:119], v[210:213], v[226:229], v[116:119]
	v_mfma_f32_16x16x32_bf16 v[112:115], v[218:221], v[226:229], v[112:115]
	v_mfma_f32_16x16x32_bf16 v[100:103], v[210:213], v[234:237], v[100:103]
	v_mfma_f32_16x16x32_bf16 v[96:99], v[218:221], v[234:237], v[96:99]
	v_mfma_f32_16x16x32_bf16 v[84:87], v[210:213], v[242:245], v[84:87]
	v_mfma_f32_16x16x32_bf16 v[80:83], v[218:221], v[242:245], v[80:83]
	v_mfma_f32_16x16x32_bf16 v[68:71], v[210:213], v[250:253], v[68:71]
	v_mfma_f32_16x16x32_bf16 v[64:67], v[218:221], v[250:253], v[64:67]
	s_setprio 0
	s_barrier
	ds_read_b128 v[222:225], v181 offset:16384
	ds_read_b128 v[226:229], v181 offset:17408
	ds_read_b128 v[230:233], v181 offset:18432
	ds_read_b128 v[234:237], v181 offset:19456
	ds_read_b128 v[238:241], v181 offset:20480
	ds_read_b128 v[242:245], v181 offset:21504
	ds_read_b128 v[246:249], v181 offset:22528
	ds_read_b128 v[250:253], v181 offset:23552
	s_mov_b32 m0, s41
	s_nop 0
	global_load_lds_dwordx4 v161, s[58:59]
	s_add_u32 s86, s58, 0x80000
	s_mov_b32 m0, s62
	s_nop 0
	global_load_lds_dwordx4 v169, s[58:59]
	s_addc_u32 s87, s59, 0
	s_mov_b32 m0, s63
	s_nop 0
	global_load_lds_dwordx4 v161, s[86:87]
	s_nop 0
	s_mov_b32 m0, s64
	s_nop 0
	global_load_lds_dwordx4 v169, s[86:87]
	s_nop 0
	s_nop 0
	s_waitcnt vmcnt(6)
	s_waitcnt lgkmcnt(0)
	s_barrier
; #define PG8_STAGE(bufoff, gbase, voff) do { const unsigned long long gb_ = (unsigned long long)(gbase); _Pragma("unroll") for (int _i = 0; _i < 2; ++_i) { unsigned keep_; \
;         asm volatile("s_mov_b32 m0, %2\n\ts_nop 0\n\tglobal_load_lds_dwordx4 %0, %1" : : "v"((voff)[_i]), "s"(gb_), "s"((unsigned)(size_t)(lds + (bufoff) + ldsw + _i * 8192)) : "memory", "m0"); (void)keep_; } } while (0)
; #define PG8_LDA(dst, b, h) do { _Pragma("unroll") for (int m = 0; m < 4; ++m) _Pragma("unroll") for (int k = 0; k < 2; ++k) dst[m][k] = *(const PG8_LAS bf16x8*)(lds + PG8_SA(b, h) + aoff + m * 2048 + k * 1024); } while (0)
; #define PG8_LDB(dst, b, h) do { _Pragma("unroll") for (int n = 0; n < 2; ++n) _Pragma("unroll") for (int k = 0; k < 2; ++k) dst[n][k] = *(const PG8_LAS bf16x8*)(lds + PG8_SB(b, h) + boff + n * 2048 + k * 1024); } while (0)
; #define PG8_MMA(ai, bj, At, Bt) do { __builtin_amdgcn_s_setprio(1); _Pragma("unroll") for (int m = 0; m < 4; ++m) _Pragma("unroll") for (int n = 0; n < 2; ++n) _Pragma("unroll") for (int k = 0; k < 2; ++k) \
;         acc[ai][bj][m][n] = __builtin_amdgcn_mfma_f32_16x16x32_bf16(Bt[n][k], At[m][k], acc[ai][bj][m][n], 0, 0, 0); __builtin_amdgcn_s_setprio(0); } while (0)
; #define PG8_WAIT_V(n) asm volatile("s_waitcnt vmcnt(" #n ")" ::: "memory")
; #define PG8_WAIT_L(n) asm volatile("s_waitcnt lgkmcnt(" #n ")" ::: "memory")
; #define PG8_BAR __builtin_amdgcn_s_barrier()
; #define PG8_SCHED __builtin_amdgcn_sched_barrier(0)
; template <class Epi, class Sched, bool ALIGN_EPI = false, bool SP2 = false>
; __device__ __forceinline__ void gemm_phase(PG8_LAS unsigned char* lds, const Gemm g, const Sched& S, const Epi& E) {
;     ...
;             PG8_WAIT_V(8); PG8_WAIT_L(0); PG8_BAR; PG8_MMA(1, 0, At, B0); PG8_MMA(1, 1, At, B1); PG8_BAR; PG8_SCHED;
;             PG8_LDB(B0, 1, 0); PG8_LDB(B1, 1, 1); PG8_SCHED; PG8_LDA(At, 1, 0); PG8_STAGE(PG8_SA(0, 1), a2 + hstepA, voffA);
	s_setprio 1
	s_waitcnt lgkmcnt(7)
	v_mfma_f32_16x16x32_bf16 v[60:63], v[182:185], v[222:225], v[60:63]
	v_mfma_f32_16x16x32_bf16 v[56:59], v[194:197], v[222:225], v[56:59]
	s_waitcnt lgkmcnt(5)
	v_mfma_f32_16x16x32_bf16 v[44:47], v[182:185], v[230:233], v[44:47]
	v_mfma_f32_16x16x32_bf16 v[40:43], v[194:197], v[230:233], v[40:43]
	s_waitcnt lgkmcnt(3)
	v_mfma_f32_16x16x32_bf16 v[28:31], v[182:185], v[238:241], v[28:31]
	v_mfma_f32_16x16x32_bf16 v[24:27], v[194:197], v[238:241], v[24:27]
	s_waitcnt lgkmcnt(1)
	v_mfma_f32_16x16x32_bf16 v[12:15], v[182:185], v[246:249], v[12:15]
	v_mfma_f32_16x16x32_bf16 v[8:11], v[194:197], v[246:249], v[8:11]
	v_mfma_f32_16x16x32_bf16 v[60:63], v[186:189], v[226:229], v[60:63]
	v_mfma_f32_16x16x32_bf16 v[56:59], v[202:205], v[226:229], v[56:59]
	v_mfma_f32_16x16x32_bf16 v[44:47], v[186:189], v[234:237], v[44:47]
	v_mfma_f32_16x16x32_bf16 v[40:43], v[202:205], v[234:237], v[40:43]
	v_mfma_f32_16x16x32_bf16 v[28:31], v[186:189], v[242:245], v[28:31]
	v_mfma_f32_16x16x32_bf16 v[24:27], v[202:205], v[242:245], v[24:27]
	s_waitcnt lgkmcnt(0)
	v_mfma_f32_16x16x32_bf16 v[12:15], v[186:189], v[250:253], v[12:15]
	v_mfma_f32_16x16x32_bf16 v[8:11], v[202:205], v[250:253], v[8:11]
	s_setprio 0
	s_setprio 1
	v_mfma_f32_16x16x32_bf16 v[52:55], v[206:209], v[222:225], v[52:55]
	v_mfma_f32_16x16x32_bf16 v[48:51], v[214:217], v[222:225], v[48:51]
	v_mfma_f32_16x16x32_bf16 v[36:39], v[206:209], v[230:233], v[36:39]
	v_mfma_f32_16x16x32_bf16 v[32:35], v[214:217], v[230:233], v[32:35]
	v_mfma_f32_16x16x32_bf16 v[20:23], v[206:209], v[238:241], v[20:23]
	v_mfma_f32_16x16x32_bf16 v[16:19], v[214:217], v[238:241], v[16:19]
	v_mfma_f32_16x16x32_bf16 v[4:7], v[206:209], v[246:249], v[4:7]
	v_mfma_f32_16x16x32_bf16 v[0:3], v[214:217], v[246:249], v[0:3]
	v_mfma_f32_16x16x32_bf16 v[52:55], v[210:213], v[226:229], v[52:55]
	v_mfma_f32_16x16x32_bf16 v[48:51], v[218:221], v[226:229], v[48:51]
	v_mfma_f32_16x16x32_bf16 v[36:39], v[210:213], v[234:237], v[36:39]
	v_mfma_f32_16x16x32_bf16 v[32:35], v[218:221], v[234:237], v[32:35]
	v_mfma_f32_16x16x32_bf16 v[20:23], v[210:213], v[242:245], v[20:23]
	v_mfma_f32_16x16x32_bf16 v[16:19], v[218:221], v[242:245], v[16:19]
	v_mfma_f32_16x16x32_bf16 v[4:7], v[210:213], v[250:253], v[4:7]
	v_mfma_f32_16x16x32_bf16 v[0:3], v[218:221], v[250:253], v[0:3]
	s_setprio 0
	s_barrier
	ds_read_b128 v[182:185], v190
	ds_read_b128 v[186:189], v190 offset:1024
	ds_read_b128 v[194:197], v190 offset:2048
	ds_read_b128 v[202:205], v190 offset:3072
	ds_read_b128 v[206:209], v191
	ds_read_b128 v[210:213], v191 offset:1024
	ds_read_b128 v[214:217], v191 offset:2048
	ds_read_b128 v[218:221], v191 offset:3072
	ds_read_b128 v[222:225], v181 offset:32768
	ds_read_b128 v[226:229], v181 offset:33792
	ds_read_b128 v[230:233], v181 offset:34816
	ds_read_b128 v[234:237], v181 offset:35840
	ds_read_b128 v[238:241], v181 offset:36864
	ds_read_b128 v[242:245], v181 offset:37888
	ds_read_b128 v[246:249], v181 offset:38912
	ds_read_b128 v[250:253], v181 offset:39936
	s_mov_b32 m0, s39
	s_nop 0
	global_load_lds_dwordx4 v157, s[60:61]
	s_nop 0
	s_mov_b32 m0, s65
	s_nop 0
	global_load_lds_dwordx4 v165, s[60:61]
	s_nop 0
	s_add_u32 s60, s60, 0x10000
	s_addc_u32 s61, s61, 0
	s_mov_b32 m0, s66
	s_nop 0
	global_load_lds_dwordx4 v157, s[60:61]
	s_nop 0
	s_mov_b32 m0, s67
	s_nop 0
	global_load_lds_dwordx4 v165, s[60:61]
	s_waitcnt vmcnt(8)
	s_waitcnt lgkmcnt(0)
	s_barrier
; #define PG8_STAGE(bufoff, gbase, voff) do { const unsigned long long gb_ = (unsigned long long)(gbase); _Pragma("unroll") for (int _i = 0; _i < 2; ++_i) { unsigned keep_; \
;         asm volatile("s_mov_b32 m0, %2\n\ts_nop 0\n\tglobal_load_lds_dwordx4 %0, %1" : : "v"((voff)[_i]), "s"(gb_), "s"((unsigned)(size_t)(lds + (bufoff) + ldsw + _i * 8192)) : "memory", "m0"); (void)keep_; } } while (0)
; #define PG8_LDA(dst, b, h) do { _Pragma("unroll") for (int m = 0; m < 4; ++m) _Pragma("unroll") for (int k = 0; k < 2; ++k) dst[m][k] = *(const PG8_LAS bf16x8*)(lds + PG8_SA(b, h) + aoff + m * 2048 + k * 1024); } while (0)
; #define PG8_MMA(ai, bj, At, Bt) do { __builtin_amdgcn_s_setprio(1); _Pragma("unroll") for (int m = 0; m < 4; ++m) _Pragma("unroll") for (int n = 0; n < 2; ++n) _Pragma("unroll") for (int k = 0; k < 2; ++k) \
;         acc[ai][bj][m][n] = __builtin_amdgcn_mfma_f32_16x16x32_bf16(Bt[n][k], At[m][k], acc[ai][bj][m][n], 0, 0, 0); __builtin_amdgcn_s_setprio(0); } while (0)
; #define PG8_WAIT_V(n) asm volatile("s_waitcnt vmcnt(" #n ")" ::: "memory")
; #define PG8_WAIT_L(n) asm volatile("s_waitcnt lgkmcnt(" #n ")" ::: "memory")
; #define PG8_BAR __builtin_amdgcn_s_barrier()
; #define PG8_SCHED __builtin_amdgcn_sched_barrier(0)
; template <class Epi, class Sched, bool ALIGN_EPI = false, bool SP2 = false>
; __device__ __forceinline__ void gemm_phase(PG8_LAS unsigned char* lds, const Gemm g, const Sched& S, const Epi& E) {
;     ...
;             PG8_WAIT_V(8); PG8_WAIT_L(0); PG8_BAR; PG8_MMA(0, 0, At, B0); PG8_MMA(0, 1, At, B1); PG8_BAR; PG8_SCHED;
;             PG8_LDA(At, 1, 1); PG8_STAGE(PG8_SB(1, 0), b3, voffB); PG8_STAGE(PG8_SB(1, 1), b3 + hstepB, voffB); PG8_STAGE(PG8_SA(1, 0), a3, voffA);
;             PG8_WAIT_V(8); PG8_WAIT_L(0); PG8_BAR; PG8_MMA(1, 0, At, B0); PG8_MMA(1, 1, At, B1); PG8_BAR; PG8_SCHED;
	s_setprio 1
	s_waitcnt lgkmcnt(7)
	v_mfma_f32_16x16x32_bf16 v[124:127], v[182:185], v[222:225], v[124:127]
	v_mfma_f32_16x16x32_bf16 v[120:123], v[194:197], v[222:225], v[120:123]
	s_waitcnt lgkmcnt(5)
	v_mfma_f32_16x16x32_bf16 v[108:111], v[182:185], v[230:233], v[108:111]
	v_mfma_f32_16x16x32_bf16 v[104:107], v[194:197], v[230:233], v[104:107]
	s_waitcnt lgkmcnt(3)
	v_mfma_f32_16x16x32_bf16 v[92:95], v[182:185], v[238:241], v[92:95]
	v_mfma_f32_16x16x32_bf16 v[88:91], v[194:197], v[238:241], v[88:91]
	s_waitcnt lgkmcnt(1)
	v_mfma_f32_16x16x32_bf16 v[76:79], v[182:185], v[246:249], v[76:79]
	v_mfma_f32_16x16x32_bf16 v[72:75], v[194:197], v[246:249], v[72:75]
	v_mfma_f32_16x16x32_bf16 v[124:127], v[186:189], v[226:229], v[124:127]
	v_mfma_f32_16x16x32_bf16 v[120:123], v[202:205], v[226:229], v[120:123]
	v_mfma_f32_16x16x32_bf16 v[108:111], v[186:189], v[234:237], v[108:111]
	v_mfma_f32_16x16x32_bf16 v[104:107], v[202:205], v[234:237], v[104:107]
	v_mfma_f32_16x16x32_bf16 v[92:95], v[186:189], v[242:245], v[92:95]
	v_mfma_f32_16x16x32_bf16 v[88:91], v[202:205], v[242:245], v[88:91]
	s_waitcnt lgkmcnt(0)
	v_mfma_f32_16x16x32_bf16 v[76:79], v[186:189], v[250:253], v[76:79]
	v_mfma_f32_16x16x32_bf16 v[72:75], v[202:205], v[250:253], v[72:75]
	s_setprio 0
	s_setprio 1
	v_mfma_f32_16x16x32_bf16 v[116:119], v[206:209], v[222:225], v[116:119]
	v_mfma_f32_16x16x32_bf16 v[112:115], v[214:217], v[222:225], v[112:115]
	v_mfma_f32_16x16x32_bf16 v[100:103], v[206:209], v[230:233], v[100:103]
	v_mfma_f32_16x16x32_bf16 v[96:99], v[214:217], v[230:233], v[96:99]
	v_mfma_f32_16x16x32_bf16 v[84:87], v[206:209], v[238:241], v[84:87]
	v_mfma_f32_16x16x32_bf16 v[80:83], v[214:217], v[238:241], v[80:83]
	v_mfma_f32_16x16x32_bf16 v[68:71], v[206:209], v[246:249], v[68:71]
	v_mfma_f32_16x16x32_bf16 v[64:67], v[214:217], v[246:249], v[64:67]
	v_mfma_f32_16x16x32_bf16 v[116:119], v[210:213], v[226:229], v[116:119]
	v_mfma_f32_16x16x32_bf16 v[112:115], v[218:221], v[226:229], v[112:115]
	v_mfma_f32_16x16x32_bf16 v[100:103], v[210:213], v[234:237], v[100:103]
	v_mfma_f32_16x16x32_bf16 v[96:99], v[218:221], v[234:237], v[96:99]
	v_mfma_f32_16x16x32_bf16 v[84:87], v[210:213], v[242:245], v[84:87]
	v_mfma_f32_16x16x32_bf16 v[80:83], v[218:221], v[242:245], v[80:83]
	v_mfma_f32_16x16x32_bf16 v[68:71], v[210:213], v[250:253], v[68:71]
	v_mfma_f32_16x16x32_bf16 v[64:67], v[218:221], v[250:253], v[64:67]
	s_setprio 0
	s_barrier
	ds_read_b128 v[222:225], v181 offset:49152
	ds_read_b128 v[226:229], v181 offset:50176
	ds_read_b128 v[230:233], v181 offset:51200
	ds_read_b128 v[234:237], v181 offset:52224
	ds_read_b128 v[238:241], v181 offset:53248
	ds_read_b128 v[242:245], v181 offset:54272
	ds_read_b128 v[246:249], v181 offset:55296
	ds_read_b128 v[250:253], v181 offset:56320
	s_add_u32 s60, s58, 0x80
	s_addc_u32 s61, s59, 0
	s_mov_b32 m0, s71
	s_nop 0
	global_load_lds_dwordx4 v161, s[60:61]
	s_add_u32 s58, s58, 0x80080
	s_mov_b32 m0, s72
	s_nop 0
	global_load_lds_dwordx4 v169, s[60:61]
	s_addc_u32 s59, s59, 0
	s_mov_b32 m0, s77
	s_nop 0
	global_load_lds_dwordx4 v161, s[58:59]
	s_nop 0
	s_mov_b32 m0, s78
	s_nop 0
	global_load_lds_dwordx4 v169, s[58:59]
	s_nop 0
	s_nop 0
	s_waitcnt vmcnt(6)
	s_waitcnt lgkmcnt(0)
	s_barrier
	s_setprio 1
	s_waitcnt lgkmcnt(7)
	v_mfma_f32_16x16x32_bf16 v[60:63], v[182:185], v[222:225], v[60:63]
	v_mfma_f32_16x16x32_bf16 v[56:59], v[194:197], v[222:225], v[56:59]
	s_waitcnt lgkmcnt(5)
	v_mfma_f32_16x16x32_bf16 v[44:47], v[182:185], v[230:233], v[44:47]
	v_mfma_f32_16x16x32_bf16 v[40:43], v[194:197], v[230:233], v[40:43]
	s_waitcnt lgkmcnt(3)
	v_mfma_f32_16x16x32_bf16 v[28:31], v[182:185], v[238:241], v[28:31]
	v_mfma_f32_16x16x32_bf16 v[24:27], v[194:197], v[238:241], v[24:27]
	s_waitcnt lgkmcnt(1)
	v_mfma_f32_16x16x32_bf16 v[12:15], v[182:185], v[246:249], v[12:15]
	v_mfma_f32_16x16x32_bf16 v[8:11], v[194:197], v[246:249], v[8:11]
	v_mfma_f32_16x16x32_bf16 v[60:63], v[186:189], v[226:229], v[60:63]
	v_mfma_f32_16x16x32_bf16 v[56:59], v[202:205], v[226:229], v[56:59]
	v_mfma_f32_16x16x32_bf16 v[44:47], v[186:189], v[234:237], v[44:47]
	v_mfma_f32_16x16x32_bf16 v[40:43], v[202:205], v[234:237], v[40:43]
	v_mfma_f32_16x16x32_bf16 v[28:31], v[186:189], v[242:245], v[28:31]
	v_mfma_f32_16x16x32_bf16 v[24:27], v[202:205], v[242:245], v[24:27]
	s_waitcnt lgkmcnt(0)
	v_mfma_f32_16x16x32_bf16 v[12:15], v[186:189], v[250:253], v[12:15]
	v_mfma_f32_16x16x32_bf16 v[8:11], v[202:205], v[250:253], v[8:11]
	s_setprio 0
	s_setprio 1
	v_mfma_f32_16x16x32_bf16 v[52:55], v[206:209], v[222:225], v[52:55]
	v_mfma_f32_16x16x32_bf16 v[48:51], v[214:217], v[222:225], v[48:51]
	v_mfma_f32_16x16x32_bf16 v[36:39], v[206:209], v[230:233], v[36:39]
	v_mfma_f32_16x16x32_bf16 v[32:35], v[214:217], v[230:233], v[32:35]
	v_mfma_f32_16x16x32_bf16 v[20:23], v[206:209], v[238:241], v[20:23]
	v_mfma_f32_16x16x32_bf16 v[16:19], v[214:217], v[238:241], v[16:19]
	v_mfma_f32_16x16x32_bf16 v[4:7], v[206:209], v[246:249], v[4:7]
	v_mfma_f32_16x16x32_bf16 v[0:3], v[214:217], v[246:249], v[0:3]
	v_mfma_f32_16x16x32_bf16 v[52:55], v[210:213], v[226:229], v[52:55]
	v_mfma_f32_16x16x32_bf16 v[48:51], v[218:221], v[226:229], v[48:51]
	v_mfma_f32_16x16x32_bf16 v[36:39], v[210:213], v[234:237], v[36:39]
	v_mfma_f32_16x16x32_bf16 v[32:35], v[218:221], v[234:237], v[32:35]
	v_mfma_f32_16x16x32_bf16 v[20:23], v[210:213], v[242:245], v[20:23]
	v_mfma_f32_16x16x32_bf16 v[16:19], v[218:221], v[242:245], v[16:19]
	v_mfma_f32_16x16x32_bf16 v[4:7], v[210:213], v[250:253], v[4:7]
	v_mfma_f32_16x16x32_bf16 v[0:3], v[218:221], v[250:253], v[0:3]
	s_setprio 0
	s_barrier
	s_add_i32 s55, s55, 2
	s_add_i32 s84, s84, 0x10000
	s_cmp_gt_u32 s55, 29
	s_mov_b64 s[52:53], s[56:57]
	s_cbranch_scc0 .LBB0_632
	s_and_b64 vcc, exec, s[24:25]
	s_cbranch_vccz .LBB0_635
	s_barrier

; #define PG8_STAGE(bufoff, gbase, voff) do { const unsigned long long gb_ = (unsigned long long)(gbase); _Pragma("unroll") for (int _i = 0; _i < 2; ++_i) { unsigned keep_; \
;         asm volatile("s_mov_b32 m0, %2\n\ts_nop 0\n\tglobal_load_lds_dwordx4 %0, %1" : : "v"((voff)[_i]), "s"(gb_), "s"((unsigned)(size_t)(lds + (bufoff) + ldsw + _i * 8192)) : "memory", "m0"); (void)keep_; } } while (0)
; #define PG8_LDA(dst, b, h) do { _Pragma("unroll") for (int m = 0; m < 4; ++m) _Pragma("unroll") for (int k = 0; k < 2; ++k) dst[m][k] = *(const PG8_LAS bf16x8*)(lds + PG8_SA(b, h) + aoff + m * 2048 + k * 1024); } while (0)
; #define PG8_LDB(dst, b, h) do { _Pragma("unroll") for (int n = 0; n < 2; ++n) _Pragma("unroll") for (int k = 0; k < 2; ++k) dst[n][k] = *(const PG8_LAS bf16x8*)(lds + PG8_SB(b, h) + boff + n * 2048 + k * 1024); } while (0)
; #define PG8_MMA(ai, bj, At, Bt) do { __builtin_amdgcn_s_setprio(1); _Pragma("unroll") for (int m = 0; m < 4; ++m) _Pragma("unroll") for (int n = 0; n < 2; ++n) _Pragma("unroll") for (int k = 0; k < 2; ++k) \
;         acc[ai][bj][m][n] = __builtin_amdgcn_mfma_f32_16x16x32_bf16(Bt[n][k], At[m][k], acc[ai][bj][m][n], 0, 0, 0); __builtin_amdgcn_s_setprio(0); } while (0)
; #define PG8_WAIT_V(n) asm volatile("s_waitcnt vmcnt(" #n ")" ::: "memory")
; #define PG8_BAR __builtin_amdgcn_s_barrier()
; template <class Epi, class Sched, bool ALIGN_EPI = false, bool SP2 = false>
; __device__ __forceinline__ void gemm_phase(PG8_LAS unsigned char* lds, const Gemm g, const Sched& S, const Epi& E) {
;     ...
;         for (int t = 0; t < nt; t += 2) {
;             const bool last = (t == nt - 2);
;     ...
;             const char* a1 = cA + PG8_KOFFA(t + 1);
;             const char* a2 = last ? nA : cA + PG8_KOFFA(t + 2); const char* b2 = last ? nB : cB + (size_t)(t + 2) * kstep;
;             const char* a3 = last ? nA + kstep : cA + PG8_KOFFA(t + 3); const char* b3 = b2 + kstep;
;     ...
;             if (last && has_next) S.a_ready(nxt);
;             if constexpr (SP2) {
;             PG8_LDB(B0, 0, 0); PG8_LDB(B1, 0, 1); PG8_SCHED; PG8_LDA(At, 0, 0); PG8_STAGE(PG8_SA(1, 1), a1 + hstepA, voffA);
;             PG8_WAIT_V(8); PG8_WAIT_L(0); PG8_BAR; PG8_MMA(0, 0, At, B0); PG8_MMA(0, 1, At, B1); PG8_BAR; PG8_SCHED;
;             PG8_LDA(At, 0, 1); PG8_STAGE(PG8_SB(0, 0), b2, voffB); PG8_STAGE(PG8_SB(0, 1), b2 + hstepB, voffB); PG8_STAGE(PG8_SA(0, 0), a2, voffA);
.LBB0_840:
	s_add_i32 s72, s44, 2
	s_lshr_b32 s12, s72, 2
	s_lshl_b64 s[76:77], s[12:13], 17
	s_add_i32 s12, s42, 0xffffff00
	s_and_b32 s73, s12, 0x100
	s_add_i32 s12, s44, 4
	s_lshr_b32 s12, s12, 2
	s_lshl_b64 s[46:47], s[12:13], 17
	s_and_b32 s12, s42, 0x100
	s_add_u32 s45, s40, s46
	s_addc_u32 s46, s41, s47
	s_add_u32 s45, s45, s12
	s_addc_u32 s48, s46, 0
	s_add_u32 s78, s38, s42
	ds_read_b128 v[104:107], v185
	ds_read_b128 v[116:119], v185 offset:1024
	ds_read_b128 v[128:131], v185 offset:2048
	ds_read_b128 v[140:143], v185 offset:3072
	ds_read_b128 v[144:147], v214
	ds_read_b128 v[148:151], v214 offset:1024
	ds_read_b128 v[152:155], v214 offset:2048
	ds_read_b128 v[156:159], v214 offset:3072
	s_addc_u32 s79, s39, s43
	s_add_i32 s12, s44, 5
	s_lshr_b32 s12, s12, 2
	s_lshl_b64 s[46:47], s[12:13], 17
	s_add_i32 s12, s42, 0x80
	s_and_b32 s12, s12, 0x180
	s_add_u32 s46, s40, s46
	s_addc_u32 s47, s41, s47
	s_add_u32 s12, s46, s12
	s_addc_u32 s80, s47, 0
	s_cmp_eq_u32 s44, 60
	s_cselect_b32 s44, s37, s12
	s_cselect_b32 s49, s0, s48
	s_cselect_b32 s48, s1, s45
	s_cselect_b32 s47, s25, s79
	s_cselect_b32 s46, s27, s78
	s_cselect_b32 s45, s71, s80
	ds_read_b128 v[160:163], v215
	ds_read_b128 v[164:167], v215 offset:1024
	ds_read_b128 v[168:171], v215 offset:2048
	ds_read_b128 v[172:175], v215 offset:3072
	ds_read_b128 v[176:179], v215 offset:4096
	ds_read_b128 v[180:183], v215 offset:5120
	ds_read_b128 v[220:223], v215 offset:6144
	ds_read_b128 v[224:227], v215 offset:7168
	s_add_u32 s12, s40, s76
	s_addc_u32 s76, s41, s77
	s_add_u32 s12, s12, s73
	s_addc_u32 s73, s76, 0
	s_add_u32 s76, s12, 0x10080
	s_addc_u32 s77, s73, 0
	s_sub_u32 s98, s76, 0x10000
	s_subb_u32 s99, s77, 0
	s_mov_b32 m0, s62
	s_nop 0
	global_load_lds_dwordx4 v187, s[98:99]
	s_nop 0
	s_mov_b32 m0, s63
	s_nop 0
	global_load_lds_dwordx4 v212, s[98:99]
	s_nop 0
	s_mov_b32 m0, s66
	s_nop 0
	global_load_lds_dwordx4 v187, s[76:77]
	s_nop 0
	s_mov_b32 m0, s67
	s_nop 0
	global_load_lds_dwordx4 v212, s[76:77]
	s_waitcnt vmcnt(8)
	s_waitcnt lgkmcnt(0)
	s_barrier
	s_setprio 1
	s_waitcnt lgkmcnt(7)
	v_mfma_f32_16x16x32_bf16 v[136:139], v[104:107], v[160:163], v[136:139]
	v_mfma_f32_16x16x32_bf16 v[132:135], v[128:131], v[160:163], v[132:135]
	s_waitcnt lgkmcnt(5)
	v_mfma_f32_16x16x32_bf16 v[112:115], v[104:107], v[168:171], v[112:115]
	v_mfma_f32_16x16x32_bf16 v[108:111], v[128:131], v[168:171], v[108:111]
	s_waitcnt lgkmcnt(3)
	v_mfma_f32_16x16x32_bf16 v[92:95], v[104:107], v[176:179], v[92:95]
	v_mfma_f32_16x16x32_bf16 v[88:91], v[128:131], v[176:179], v[88:91]
	s_waitcnt lgkmcnt(1)
	v_mfma_f32_16x16x32_bf16 v[76:79], v[104:107], v[220:223], v[76:79]
	v_mfma_f32_16x16x32_bf16 v[72:75], v[128:131], v[220:223], v[72:75]
	v_mfma_f32_16x16x32_bf16 v[136:139], v[116:119], v[164:167], v[136:139]
	v_mfma_f32_16x16x32_bf16 v[132:135], v[140:143], v[164:167], v[132:135]
	v_mfma_f32_16x16x32_bf16 v[112:115], v[116:119], v[172:175], v[112:115]
	v_mfma_f32_16x16x32_bf16 v[108:111], v[140:143], v[172:175], v[108:111]
	v_mfma_f32_16x16x32_bf16 v[92:95], v[116:119], v[180:183], v[92:95]
	v_mfma_f32_16x16x32_bf16 v[88:91], v[140:143], v[180:183], v[88:91]
	s_waitcnt lgkmcnt(0)
	v_mfma_f32_16x16x32_bf16 v[76:79], v[116:119], v[224:227], v[76:79]
	v_mfma_f32_16x16x32_bf16 v[72:75], v[140:143], v[224:227], v[72:75]
	s_setprio 0
	s_setprio 1
	v_mfma_f32_16x16x32_bf16 v[124:127], v[144:147], v[160:163], v[124:127]
	v_mfma_f32_16x16x32_bf16 v[120:123], v[152:155], v[160:163], v[120:123]
	v_mfma_f32_16x16x32_bf16 v[100:103], v[144:147], v[168:171], v[100:103]
	v_mfma_f32_16x16x32_bf16 v[96:99], v[152:155], v[168:171], v[96:99]
	v_mfma_f32_16x16x32_bf16 v[84:87], v[144:147], v[176:179], v[84:87]
	v_mfma_f32_16x16x32_bf16 v[80:83], v[152:155], v[176:179], v[80:83]
	v_mfma_f32_16x16x32_bf16 v[68:71], v[144:147], v[220:223], v[68:71]
	v_mfma_f32_16x16x32_bf16 v[64:67], v[152:155], v[220:223], v[64:67]
	v_mfma_f32_16x16x32_bf16 v[124:127], v[148:151], v[164:167], v[124:127]
	v_mfma_f32_16x16x32_bf16 v[120:123], v[156:159], v[164:167], v[120:123]
	v_mfma_f32_16x16x32_bf16 v[100:103], v[148:151], v[172:175], v[100:103]
	v_mfma_f32_16x16x32_bf16 v[96:99], v[156:159], v[172:175], v[96:99]
	v_mfma_f32_16x16x32_bf16 v[84:87], v[148:151], v[180:183], v[84:87]
	v_mfma_f32_16x16x32_bf16 v[80:83], v[156:159], v[180:183], v[80:83]
	v_mfma_f32_16x16x32_bf16 v[68:71], v[148:151], v[224:227], v[68:71]
	v_mfma_f32_16x16x32_bf16 v[64:67], v[156:159], v[224:227], v[64:67]
	s_setprio 0
	s_barrier
	ds_read_b128 v[160:163], v215 offset:16384
	ds_read_b128 v[164:167], v215 offset:17408
	ds_read_b128 v[168:171], v215 offset:18432
	ds_read_b128 v[172:175], v215 offset:19456
	ds_read_b128 v[176:179], v215 offset:20480
	ds_read_b128 v[180:183], v215 offset:21504
	ds_read_b128 v[220:223], v215 offset:22528
	ds_read_b128 v[224:227], v215 offset:23552
	s_mov_b32 m0, s52
	s_nop 0
	global_load_lds_dwordx4 v201, s[46:47]
	s_add_u32 s76, s46, 0x100000
	s_mov_b32 m0, s53
	s_nop 0
	global_load_lds_dwordx4 v213, s[46:47]
	s_addc_u32 s77, s47, 0
	s_mov_b32 m0, s54
	s_nop 0
	global_load_lds_dwordx4 v201, s[76:77]
	s_nop 0
	s_mov_b32 m0, s55
	s_nop 0
	global_load_lds_dwordx4 v213, s[76:77]
	s_nop 0
	s_nop 0
	s_waitcnt vmcnt(6)
	s_waitcnt lgkmcnt(0)
	s_barrier
; #define PG8_STAGE(bufoff, gbase, voff) do { const unsigned long long gb_ = (unsigned long long)(gbase); _Pragma("unroll") for (int _i = 0; _i < 2; ++_i) { unsigned keep_; \
;         asm volatile("s_mov_b32 m0, %2\n\ts_nop 0\n\tglobal_load_lds_dwordx4 %0, %1" : : "v"((voff)[_i]), "s"(gb_), "s"((unsigned)(size_t)(lds + (bufoff) + ldsw + _i * 8192)) : "memory", "m0"); (void)keep_; } } while (0)
; #define PG8_LDA(dst, b, h) do { _Pragma("unroll") for (int m = 0; m < 4; ++m) _Pragma("unroll") for (int k = 0; k < 2; ++k) dst[m][k] = *(const PG8_LAS bf16x8*)(lds + PG8_SA(b, h) + aoff + m * 2048 + k * 1024); } while (0)
; #define PG8_LDB(dst, b, h) do { _Pragma("unroll") for (int n = 0; n < 2; ++n) _Pragma("unroll") for (int k = 0; k < 2; ++k) dst[n][k] = *(const PG8_LAS bf16x8*)(lds + PG8_SB(b, h) + boff + n * 2048 + k * 1024); } while (0)
; #define PG8_MMA(ai, bj, At, Bt) do { __builtin_amdgcn_s_setprio(1); _Pragma("unroll") for (int m = 0; m < 4; ++m) _Pragma("unroll") for (int n = 0; n < 2; ++n) _Pragma("unroll") for (int k = 0; k < 2; ++k) \
;         acc[ai][bj][m][n] = __builtin_amdgcn_mfma_f32_16x16x32_bf16(Bt[n][k], At[m][k], acc[ai][bj][m][n], 0, 0, 0); __builtin_amdgcn_s_setprio(0); } while (0)
; #define PG8_WAIT_V(n) asm volatile("s_waitcnt vmcnt(" #n ")" ::: "memory")
; #define PG8_WAIT_L(n) asm volatile("s_waitcnt lgkmcnt(" #n ")" ::: "memory")
; #define PG8_BAR __builtin_amdgcn_s_barrier()
; #define PG8_SCHED __builtin_amdgcn_sched_barrier(0)
; template <class Epi, class Sched, bool ALIGN_EPI = false, bool SP2 = false>
; __device__ __forceinline__ void gemm_phase(PG8_LAS unsigned char* lds, const Gemm g, const Sched& S, const Epi& E) {
;     ...
;             PG8_WAIT_V(8); PG8_WAIT_L(0); PG8_BAR; PG8_MMA(1, 0, At, B0); PG8_MMA(1, 1, At, B1); PG8_BAR; PG8_SCHED;
;             PG8_LDB(B0, 1, 0); PG8_LDB(B1, 1, 1); PG8_SCHED; PG8_LDA(At, 1, 0); PG8_STAGE(PG8_SA(0, 1), a2 + hstepA, voffA);
	s_setprio 1
	s_waitcnt lgkmcnt(7)
	v_mfma_f32_16x16x32_bf16 v[60:63], v[104:107], v[160:163], v[60:63]
	v_mfma_f32_16x16x32_bf16 v[56:59], v[128:131], v[160:163], v[56:59]
	s_waitcnt lgkmcnt(5)
	v_mfma_f32_16x16x32_bf16 v[44:47], v[104:107], v[168:171], v[44:47]
	v_mfma_f32_16x16x32_bf16 v[40:43], v[128:131], v[168:171], v[40:43]
	s_waitcnt lgkmcnt(3)
	v_mfma_f32_16x16x32_bf16 v[28:31], v[104:107], v[176:179], v[28:31]
	v_mfma_f32_16x16x32_bf16 v[24:27], v[128:131], v[176:179], v[24:27]
	s_waitcnt lgkmcnt(1)
	v_mfma_f32_16x16x32_bf16 v[12:15], v[104:107], v[220:223], v[12:15]
	v_mfma_f32_16x16x32_bf16 v[8:11], v[128:131], v[220:223], v[8:11]
	v_mfma_f32_16x16x32_bf16 v[60:63], v[116:119], v[164:167], v[60:63]
	v_mfma_f32_16x16x32_bf16 v[56:59], v[140:143], v[164:167], v[56:59]
	v_mfma_f32_16x16x32_bf16 v[44:47], v[116:119], v[172:175], v[44:47]
	v_mfma_f32_16x16x32_bf16 v[40:43], v[140:143], v[172:175], v[40:43]
	v_mfma_f32_16x16x32_bf16 v[28:31], v[116:119], v[180:183], v[28:31]
	v_mfma_f32_16x16x32_bf16 v[24:27], v[140:143], v[180:183], v[24:27]
	s_waitcnt lgkmcnt(0)
	v_mfma_f32_16x16x32_bf16 v[12:15], v[116:119], v[224:227], v[12:15]
	v_mfma_f32_16x16x32_bf16 v[8:11], v[140:143], v[224:227], v[8:11]
	s_setprio 0
	s_setprio 1
	v_mfma_f32_16x16x32_bf16 v[52:55], v[144:147], v[160:163], v[52:55]
	v_mfma_f32_16x16x32_bf16 v[48:51], v[152:155], v[160:163], v[48:51]
	v_mfma_f32_16x16x32_bf16 v[36:39], v[144:147], v[168:171], v[36:39]
	v_mfma_f32_16x16x32_bf16 v[32:35], v[152:155], v[168:171], v[32:35]
	v_mfma_f32_16x16x32_bf16 v[20:23], v[144:147], v[176:179], v[20:23]
	v_mfma_f32_16x16x32_bf16 v[16:19], v[152:155], v[176:179], v[16:19]
	v_mfma_f32_16x16x32_bf16 v[4:7], v[144:147], v[220:223], v[4:7]
	v_mfma_f32_16x16x32_bf16 v[0:3], v[152:155], v[220:223], v[0:3]
	v_mfma_f32_16x16x32_bf16 v[52:55], v[148:151], v[164:167], v[52:55]
	v_mfma_f32_16x16x32_bf16 v[48:51], v[156:159], v[164:167], v[48:51]
	v_mfma_f32_16x16x32_bf16 v[36:39], v[148:151], v[172:175], v[36:39]
	v_mfma_f32_16x16x32_bf16 v[32:35], v[156:159], v[172:175], v[32:35]
	v_mfma_f32_16x16x32_bf16 v[20:23], v[148:151], v[180:183], v[20:23]
	v_mfma_f32_16x16x32_bf16 v[16:19], v[156:159], v[180:183], v[16:19]
	v_mfma_f32_16x16x32_bf16 v[4:7], v[148:151], v[224:227], v[4:7]
	v_mfma_f32_16x16x32_bf16 v[0:3], v[156:159], v[224:227], v[0:3]
	s_setprio 0
	s_barrier
	ds_read_b128 v[104:107], v216
	ds_read_b128 v[116:119], v216 offset:1024
	ds_read_b128 v[128:131], v216 offset:2048
	ds_read_b128 v[140:143], v216 offset:3072
	ds_read_b128 v[144:147], v217
	ds_read_b128 v[148:151], v217 offset:1024
	ds_read_b128 v[152:155], v217 offset:2048
	ds_read_b128 v[156:159], v217 offset:3072
	ds_read_b128 v[160:163], v215 offset:32768
	ds_read_b128 v[164:167], v215 offset:33792
	ds_read_b128 v[168:171], v215 offset:34816
	ds_read_b128 v[172:175], v215 offset:35840
	ds_read_b128 v[176:179], v215 offset:36864
	ds_read_b128 v[180:183], v215 offset:37888
	ds_read_b128 v[220:223], v215 offset:38912
	ds_read_b128 v[224:227], v215 offset:39936
	s_mov_b32 m0, s35
	s_nop 0
	global_load_lds_dwordx4 v187, s[48:49]
	s_nop 0
	s_mov_b32 m0, s56
	s_nop 0
	global_load_lds_dwordx4 v212, s[48:49]
	s_nop 0
	s_add_u32 s48, s48, 0x10000
	s_addc_u32 s49, s49, 0
	s_mov_b32 m0, s57
	s_nop 0
	global_load_lds_dwordx4 v187, s[48:49]
	s_nop 0
	s_mov_b32 m0, s58
	s_nop 0
	global_load_lds_dwordx4 v212, s[48:49]
	s_waitcnt vmcnt(8)
	s_waitcnt lgkmcnt(0)
	s_barrier
; #define PG8_STAGE(bufoff, gbase, voff) do { const unsigned long long gb_ = (unsigned long long)(gbase); _Pragma("unroll") for (int _i = 0; _i < 2; ++_i) { unsigned keep_; \
;         asm volatile("s_mov_b32 m0, %2\n\ts_nop 0\n\tglobal_load_lds_dwordx4 %0, %1" : : "v"((voff)[_i]), "s"(gb_), "s"((unsigned)(size_t)(lds + (bufoff) + ldsw + _i * 8192)) : "memory", "m0"); (void)keep_; } } while (0)
; #define PG8_LDA(dst, b, h) do { _Pragma("unroll") for (int m = 0; m < 4; ++m) _Pragma("unroll") for (int k = 0; k < 2; ++k) dst[m][k] = *(const PG8_LAS bf16x8*)(lds + PG8_SA(b, h) + aoff + m * 2048 + k * 1024); } while (0)
; #define PG8_MMA(ai, bj, At, Bt) do { __builtin_amdgcn_s_setprio(1); _Pragma("unroll") for (int m = 0; m < 4; ++m) _Pragma("unroll") for (int n = 0; n < 2; ++n) _Pragma("unroll") for (int k = 0; k < 2; ++k) \
;         acc[ai][bj][m][n] = __builtin_amdgcn_mfma_f32_16x16x32_bf16(Bt[n][k], At[m][k], acc[ai][bj][m][n], 0, 0, 0); __builtin_amdgcn_s_setprio(0); } while (0)
; #define PG8_WAIT_V(n) asm volatile("s_waitcnt vmcnt(" #n ")" ::: "memory")
; #define PG8_WAIT_L(n) asm volatile("s_waitcnt lgkmcnt(" #n ")" ::: "memory")
; #define PG8_BAR __builtin_amdgcn_s_barrier()
; #define PG8_SCHED __builtin_amdgcn_sched_barrier(0)
; template <class Epi, class Sched, bool ALIGN_EPI = false, bool SP2 = false>
; __device__ __forceinline__ void gemm_phase(PG8_LAS unsigned char* lds, const Gemm g, const Sched& S, const Epi& E) {
;     ...
;             PG8_WAIT_V(8); PG8_WAIT_L(0); PG8_BAR; PG8_MMA(0, 0, At, B0); PG8_MMA(0, 1, At, B1); PG8_BAR; PG8_SCHED;
;             PG8_LDA(At, 1, 1); PG8_STAGE(PG8_SB(1, 0), b3, voffB); PG8_STAGE(PG8_SB(1, 1), b3 + hstepB, voffB); PG8_STAGE(PG8_SA(1, 0), a3, voffA);
;             PG8_WAIT_V(8); PG8_WAIT_L(0); PG8_BAR; PG8_MMA(1, 0, At, B0); PG8_MMA(1, 1, At, B1); PG8_BAR; PG8_SCHED;
	s_setprio 1
	s_waitcnt lgkmcnt(7)
	v_mfma_f32_16x16x32_bf16 v[136:139], v[104:107], v[160:163], v[136:139]
	v_mfma_f32_16x16x32_bf16 v[132:135], v[128:131], v[160:163], v[132:135]
	s_waitcnt lgkmcnt(5)
	v_mfma_f32_16x16x32_bf16 v[112:115], v[104:107], v[168:171], v[112:115]
	v_mfma_f32_16x16x32_bf16 v[108:111], v[128:131], v[168:171], v[108:111]
	s_waitcnt lgkmcnt(3)
	v_mfma_f32_16x16x32_bf16 v[92:95], v[104:107], v[176:179], v[92:95]
	v_mfma_f32_16x16x32_bf16 v[88:91], v[128:131], v[176:179], v[88:91]
	s_waitcnt lgkmcnt(1)
	v_mfma_f32_16x16x32_bf16 v[76:79], v[104:107], v[220:223], v[76:79]
	v_mfma_f32_16x16x32_bf16 v[72:75], v[128:131], v[220:223], v[72:75]
	v_mfma_f32_16x16x32_bf16 v[136:139], v[116:119], v[164:167], v[136:139]
	v_mfma_f32_16x16x32_bf16 v[132:135], v[140:143], v[164:167], v[132:135]
	v_mfma_f32_16x16x32_bf16 v[112:115], v[116:119], v[172:175], v[112:115]
	v_mfma_f32_16x16x32_bf16 v[108:111], v[140:143], v[172:175], v[108:111]
	v_mfma_f32_16x16x32_bf16 v[92:95], v[116:119], v[180:183], v[92:95]
	v_mfma_f32_16x16x32_bf16 v[88:91], v[140:143], v[180:183], v[88:91]
	s_waitcnt lgkmcnt(0)
	v_mfma_f32_16x16x32_bf16 v[76:79], v[116:119], v[224:227], v[76:79]
	v_mfma_f32_16x16x32_bf16 v[72:75], v[140:143], v[224:227], v[72:75]
	s_setprio 0
	s_setprio 1
	v_mfma_f32_16x16x32_bf16 v[124:127], v[144:147], v[160:163], v[124:127]
	v_mfma_f32_16x16x32_bf16 v[120:123], v[152:155], v[160:163], v[120:123]
	v_mfma_f32_16x16x32_bf16 v[100:103], v[144:147], v[168:171], v[100:103]
	v_mfma_f32_16x16x32_bf16 v[96:99], v[152:155], v[168:171], v[96:99]
	v_mfma_f32_16x16x32_bf16 v[84:87], v[144:147], v[176:179], v[84:87]
	v_mfma_f32_16x16x32_bf16 v[80:83], v[152:155], v[176:179], v[80:83]
	v_mfma_f32_16x16x32_bf16 v[68:71], v[144:147], v[220:223], v[68:71]
	v_mfma_f32_16x16x32_bf16 v[64:67], v[152:155], v[220:223], v[64:67]
	v_mfma_f32_16x16x32_bf16 v[124:127], v[148:151], v[164:167], v[124:127]
	v_mfma_f32_16x16x32_bf16 v[120:123], v[156:159], v[164:167], v[120:123]
	v_mfma_f32_16x16x32_bf16 v[100:103], v[148:151], v[172:175], v[100:103]
	v_mfma_f32_16x16x32_bf16 v[96:99], v[156:159], v[172:175], v[96:99]
	v_mfma_f32_16x16x32_bf16 v[84:87], v[148:151], v[180:183], v[84:87]
	v_mfma_f32_16x16x32_bf16 v[80:83], v[156:159], v[180:183], v[80:83]
	v_mfma_f32_16x16x32_bf16 v[68:71], v[148:151], v[224:227], v[68:71]
	v_mfma_f32_16x16x32_bf16 v[64:67], v[156:159], v[224:227], v[64:67]
	s_setprio 0
	s_barrier
	ds_read_b128 v[160:163], v215 offset:49152
	ds_read_b128 v[164:167], v215 offset:50176
	ds_read_b128 v[168:171], v215 offset:51200
	ds_read_b128 v[172:175], v215 offset:52224
	ds_read_b128 v[176:179], v215 offset:53248
	ds_read_b128 v[180:183], v215 offset:54272
	ds_read_b128 v[220:223], v215 offset:55296
	ds_read_b128 v[224:227], v215 offset:56320
	s_add_u32 s48, s46, 0x80
	s_addc_u32 s49, s47, 0
	s_mov_b32 m0, s60
	s_nop 0
	global_load_lds_dwordx4 v201, s[48:49]
	s_add_u32 s46, s46, 0x100080
	s_mov_b32 m0, s61
	s_nop 0
	global_load_lds_dwordx4 v213, s[48:49]
	s_addc_u32 s47, s47, 0
	s_mov_b32 m0, s64
	s_nop 0
	global_load_lds_dwordx4 v201, s[46:47]
	s_nop 0
	s_mov_b32 m0, s65
	s_nop 0
	global_load_lds_dwordx4 v213, s[46:47]
	s_nop 0
	s_nop 0
	s_waitcnt vmcnt(6)
	s_waitcnt lgkmcnt(0)
	s_barrier
	s_setprio 1
	s_waitcnt lgkmcnt(7)
	v_mfma_f32_16x16x32_bf16 v[60:63], v[104:107], v[160:163], v[60:63]
	v_mfma_f32_16x16x32_bf16 v[56:59], v[128:131], v[160:163], v[56:59]
	s_waitcnt lgkmcnt(5)
	v_mfma_f32_16x16x32_bf16 v[44:47], v[104:107], v[168:171], v[44:47]
	v_mfma_f32_16x16x32_bf16 v[40:43], v[128:131], v[168:171], v[40:43]
	s_waitcnt lgkmcnt(3)
	v_mfma_f32_16x16x32_bf16 v[28:31], v[104:107], v[176:179], v[28:31]
	v_mfma_f32_16x16x32_bf16 v[24:27], v[128:131], v[176:179], v[24:27]
	s_waitcnt lgkmcnt(1)
	v_mfma_f32_16x16x32_bf16 v[12:15], v[104:107], v[220:223], v[12:15]
	v_mfma_f32_16x16x32_bf16 v[8:11], v[128:131], v[220:223], v[8:11]
	v_mfma_f32_16x16x32_bf16 v[60:63], v[116:119], v[164:167], v[60:63]
	v_mfma_f32_16x16x32_bf16 v[56:59], v[140:143], v[164:167], v[56:59]
	v_mfma_f32_16x16x32_bf16 v[44:47], v[116:119], v[172:175], v[44:47]
	v_mfma_f32_16x16x32_bf16 v[40:43], v[140:143], v[172:175], v[40:43]
	v_mfma_f32_16x16x32_bf16 v[28:31], v[116:119], v[180:183], v[28:31]
	v_mfma_f32_16x16x32_bf16 v[24:27], v[140:143], v[180:183], v[24:27]
	s_waitcnt lgkmcnt(0)
	v_mfma_f32_16x16x32_bf16 v[12:15], v[116:119], v[224:227], v[12:15]
	v_mfma_f32_16x16x32_bf16 v[8:11], v[140:143], v[224:227], v[8:11]
	s_setprio 0
	s_setprio 1
	v_mfma_f32_16x16x32_bf16 v[52:55], v[144:147], v[160:163], v[52:55]
	v_mfma_f32_16x16x32_bf16 v[48:51], v[152:155], v[160:163], v[48:51]
	v_mfma_f32_16x16x32_bf16 v[36:39], v[144:147], v[168:171], v[36:39]
	v_mfma_f32_16x16x32_bf16 v[32:35], v[152:155], v[168:171], v[32:35]
	v_mfma_f32_16x16x32_bf16 v[20:23], v[144:147], v[176:179], v[20:23]
	v_mfma_f32_16x16x32_bf16 v[16:19], v[152:155], v[176:179], v[16:19]
	v_mfma_f32_16x16x32_bf16 v[4:7], v[144:147], v[220:223], v[4:7]
	v_mfma_f32_16x16x32_bf16 v[0:3], v[152:155], v[220:223], v[0:3]
	v_mfma_f32_16x16x32_bf16 v[52:55], v[148:151], v[164:167], v[52:55]
	v_mfma_f32_16x16x32_bf16 v[48:51], v[156:159], v[164:167], v[48:51]
	v_mfma_f32_16x16x32_bf16 v[36:39], v[148:151], v[172:175], v[36:39]
	v_mfma_f32_16x16x32_bf16 v[32:35], v[156:159], v[172:175], v[32:35]
	v_mfma_f32_16x16x32_bf16 v[20:23], v[148:151], v[180:183], v[20:23]
	v_mfma_f32_16x16x32_bf16 v[16:19], v[156:159], v[180:183], v[16:19]
	v_mfma_f32_16x16x32_bf16 v[4:7], v[148:151], v[224:227], v[4:7]
	v_mfma_f32_16x16x32_bf16 v[0:3], v[156:159], v[224:227], v[0:3]
	s_setprio 0
	s_barrier
	s_add_u32 s42, s42, 0x100
	s_addc_u32 s43, s43, 0
	s_cmp_gt_u32 s72, 61
	s_mov_b32 s44, s72
	s_cbranch_scc0 .LBB0_840
	s_and_b64 vcc, exec, s[22:23]
	s_cbranch_vccz .LBB0_843
	s_barrier

; #define PG8_STAGE(bufoff, gbase, voff) do { const unsigned long long gb_ = (unsigned long long)(gbase); _Pragma("unroll") for (int _i = 0; _i < 2; ++_i) { unsigned keep_; \
;         asm volatile("s_mov_b32 m0, %2\n\ts_nop 0\n\tglobal_load_lds_dwordx4 %0, %1" : : "v"((voff)[_i]), "s"(gb_), "s"((unsigned)(size_t)(lds + (bufoff) + ldsw + _i * 8192)) : "memory", "m0"); (void)keep_; } } while (0)
; #define PG8_LDA(dst, b, h) do { _Pragma("unroll") for (int m = 0; m < 4; ++m) _Pragma("unroll") for (int k = 0; k < 2; ++k) dst[m][k] = *(const PG8_LAS bf16x8*)(lds + PG8_SA(b, h) + aoff + m * 2048 + k * 1024); } while (0)
; #define PG8_LDB(dst, b, h) do { _Pragma("unroll") for (int n = 0; n < 2; ++n) _Pragma("unroll") for (int k = 0; k < 2; ++k) dst[n][k] = *(const PG8_LAS bf16x8*)(lds + PG8_SB(b, h) + boff + n * 2048 + k * 1024); } while (0)
; #define PG8_MMA(ai, bj, At, Bt) do { __builtin_amdgcn_s_setprio(1); _Pragma("unroll") for (int m = 0; m < 4; ++m) _Pragma("unroll") for (int n = 0; n < 2; ++n) _Pragma("unroll") for (int k = 0; k < 2; ++k) \
;         acc[ai][bj][m][n] = __builtin_amdgcn_mfma_f32_16x16x32_bf16(Bt[n][k], At[m][k], acc[ai][bj][m][n], 0, 0, 0); __builtin_amdgcn_s_setprio(0); } while (0)
; #define PG8_WAIT_V(n) asm volatile("s_waitcnt vmcnt(" #n ")" ::: "memory")
; #define PG8_BAR __builtin_amdgcn_s_barrier()
; template <class Epi, class Sched, bool ALIGN_EPI = false, bool SP2 = false>
; __device__ __forceinline__ void gemm_phase(PG8_LAS unsigned char* lds, const Gemm g, const Sched& S, const Epi& E) {
;     ...
;         for (int t = 0; t < nt; t += 2) {
;             const bool last = (t == nt - 2);
;     ...
;             const char* a1 = cA + PG8_KOFFA(t + 1);
;             const char* a2 = last ? nA : cA + PG8_KOFFA(t + 2); const char* b2 = last ? nB : cB + (size_t)(t + 2) * kstep;
;             const char* a3 = last ? nA + kstep : cA + PG8_KOFFA(t + 3); const char* b3 = b2 + kstep;
;     ...
;             if (last && has_next) S.a_ready(nxt);
;             if constexpr (SP2) {
;             PG8_LDB(B0, 0, 0); PG8_LDB(B1, 0, 1); PG8_SCHED; PG8_LDA(At, 0, 0); PG8_STAGE(PG8_SA(1, 1), a1 + hstepA, voffA);
;             PG8_WAIT_V(8); PG8_WAIT_L(0); PG8_BAR; PG8_MMA(0, 0, At, B0); PG8_MMA(0, 1, At, B1); PG8_BAR; PG8_SCHED;
;             PG8_LDA(At, 0, 1); PG8_STAGE(PG8_SB(0, 0), b2, voffB); PG8_STAGE(PG8_SB(0, 1), b2 + hstepB, voffB); PG8_STAGE(PG8_SA(0, 0), a2, voffA);
.LBB0_953:
	s_add_i32 s37, s71, 0xfffe8000
	s_and_b32 s36, s34, 0x100
	s_and_b32 s37, s37, 0xe0000
	s_or_b32 s36, s36, s37
	s_add_u32 s72, s8, s36
	s_addc_u32 s73, s9, 0
	s_add_u32 s36, s34, 0x100
	s_addc_u32 s37, s35, 0
	s_add_i32 s39, s71, 0xffff8000
	s_and_b32 s38, s36, 0x100
	s_and_b32 s39, s39, 0x1e0000
	s_or_b32 s38, s39, s38
	ds_read_b128 v[156:159], v177
	ds_read_b128 v[184:187], v177 offset:1024
	ds_read_b128 v[188:191], v177 offset:2048
	ds_read_b128 v[192:195], v177 offset:3072
	ds_read_b128 v[196:199], v178
	ds_read_b128 v[202:205], v178 offset:1024
	ds_read_b128 v[206:209], v178 offset:2048
	ds_read_b128 v[210:213], v178 offset:3072
	s_add_u32 s38, s8, s38
	s_addc_u32 s39, s9, 0
	s_add_u32 s76, s68, s34
	s_addc_u32 s35, s69, s35
	s_add_i32 s40, s34, 0x180
	s_and_b32 s40, s40, 0x180
	s_and_b32 s41, s71, 0x1e0000
	s_or_b32 s40, s41, s40
	s_add_u32 s77, s8, s40
	s_addc_u32 s78, s9, 0
	s_cmpk_eq_i32 s34, 0xf00
	s_cselect_b32 s41, s0, s39
	s_cselect_b32 s39, s21, s35
	s_cselect_b32 s35, s67, s78
	s_cselect_b32 s34, s29, s77
	s_cselect_b32 s40, s1, s38
	s_cselect_b32 s38, s23, s76
	ds_read_b128 v[214:217], v179
	ds_read_b128 v[218:221], v179 offset:1024
	ds_read_b128 v[222:225], v179 offset:2048
	ds_read_b128 v[226:229], v179 offset:3072
	ds_read_b128 v[230:233], v179 offset:4096
	ds_read_b128 v[234:237], v179 offset:5120
	ds_read_b128 v[238:241], v179 offset:6144
	ds_read_b128 v[242:245], v179 offset:7168
	s_add_u32 s72, s72, 0x10080
	s_addc_u32 s73, s73, 0
	s_sub_u32 s98, s72, 0x10000
	s_subb_u32 s99, s73, 0
	s_mov_b32 m0, s57
	s_nop 0
	global_load_lds_dwordx4 v161, s[98:99]
	s_nop 0
	s_mov_b32 m0, s58
	s_nop 0
	global_load_lds_dwordx4 v163, s[98:99]
	s_nop 0
	s_mov_b32 m0, s61
	s_nop 0
	global_load_lds_dwordx4 v161, s[72:73]
	s_nop 0
	s_mov_b32 m0, s62
	s_nop 0
	global_load_lds_dwordx4 v163, s[72:73]
	s_waitcnt vmcnt(8)
	s_waitcnt lgkmcnt(0)
	s_barrier
	s_setprio 1
	s_waitcnt lgkmcnt(7)
	v_mfma_f32_16x16x32_bf16 v[124:127], v[156:159], v[214:217], v[124:127]
	v_mfma_f32_16x16x32_bf16 v[116:119], v[188:191], v[214:217], v[116:119]
	s_waitcnt lgkmcnt(5)
	v_mfma_f32_16x16x32_bf16 v[108:111], v[156:159], v[222:225], v[108:111]
	v_mfma_f32_16x16x32_bf16 v[100:103], v[188:191], v[222:225], v[100:103]
	s_waitcnt lgkmcnt(3)
	v_mfma_f32_16x16x32_bf16 v[92:95], v[156:159], v[230:233], v[92:95]
	v_mfma_f32_16x16x32_bf16 v[84:87], v[188:191], v[230:233], v[84:87]
	s_waitcnt lgkmcnt(1)
	v_mfma_f32_16x16x32_bf16 v[76:79], v[156:159], v[238:241], v[76:79]
	v_mfma_f32_16x16x32_bf16 v[68:71], v[188:191], v[238:241], v[68:71]
	v_mfma_f32_16x16x32_bf16 v[124:127], v[184:187], v[218:221], v[124:127]
	v_mfma_f32_16x16x32_bf16 v[116:119], v[192:195], v[218:221], v[116:119]
	v_mfma_f32_16x16x32_bf16 v[108:111], v[184:187], v[226:229], v[108:111]
	v_mfma_f32_16x16x32_bf16 v[100:103], v[192:195], v[226:229], v[100:103]
	v_mfma_f32_16x16x32_bf16 v[92:95], v[184:187], v[234:237], v[92:95]
	v_mfma_f32_16x16x32_bf16 v[84:87], v[192:195], v[234:237], v[84:87]
	s_waitcnt lgkmcnt(0)
	v_mfma_f32_16x16x32_bf16 v[76:79], v[184:187], v[242:245], v[76:79]
	v_mfma_f32_16x16x32_bf16 v[68:71], v[192:195], v[242:245], v[68:71]
	s_setprio 0
	s_setprio 1
	v_mfma_f32_16x16x32_bf16 v[120:123], v[196:199], v[214:217], v[120:123]
	v_mfma_f32_16x16x32_bf16 v[112:115], v[206:209], v[214:217], v[112:115]
	v_mfma_f32_16x16x32_bf16 v[104:107], v[196:199], v[222:225], v[104:107]
	v_mfma_f32_16x16x32_bf16 v[96:99], v[206:209], v[222:225], v[96:99]
	v_mfma_f32_16x16x32_bf16 v[88:91], v[196:199], v[230:233], v[88:91]
	v_mfma_f32_16x16x32_bf16 v[80:83], v[206:209], v[230:233], v[80:83]
	v_mfma_f32_16x16x32_bf16 v[72:75], v[196:199], v[238:241], v[72:75]
	v_mfma_f32_16x16x32_bf16 v[64:67], v[206:209], v[238:241], v[64:67]
	v_mfma_f32_16x16x32_bf16 v[120:123], v[202:205], v[218:221], v[120:123]
	v_mfma_f32_16x16x32_bf16 v[112:115], v[210:213], v[218:221], v[112:115]
	v_mfma_f32_16x16x32_bf16 v[104:107], v[202:205], v[226:229], v[104:107]
	v_mfma_f32_16x16x32_bf16 v[96:99], v[210:213], v[226:229], v[96:99]
	v_mfma_f32_16x16x32_bf16 v[88:91], v[202:205], v[234:237], v[88:91]
	v_mfma_f32_16x16x32_bf16 v[80:83], v[210:213], v[234:237], v[80:83]
	v_mfma_f32_16x16x32_bf16 v[72:75], v[202:205], v[242:245], v[72:75]
	v_mfma_f32_16x16x32_bf16 v[64:67], v[210:213], v[242:245], v[64:67]
	s_setprio 0
	s_barrier
	ds_read_b128 v[214:217], v179 offset:16384
	ds_read_b128 v[218:221], v179 offset:17408
	ds_read_b128 v[222:225], v179 offset:18432
	ds_read_b128 v[226:229], v179 offset:19456
	ds_read_b128 v[230:233], v179 offset:20480
	ds_read_b128 v[234:237], v179 offset:21504
	ds_read_b128 v[238:241], v179 offset:22528
	ds_read_b128 v[242:245], v179 offset:23552
	s_mov_b32 m0, s45
	s_nop 0
	global_load_lds_dwordx4 v175, s[38:39]
	s_add_u32 s72, s38, 0x80000
	s_mov_b32 m0, s46
	s_nop 0
	global_load_lds_dwordx4 v176, s[38:39]
	s_addc_u32 s73, s39, 0
	s_mov_b32 m0, s47
	s_nop 0
	global_load_lds_dwordx4 v175, s[72:73]
	s_nop 0
	s_mov_b32 m0, s48
	s_nop 0
	global_load_lds_dwordx4 v176, s[72:73]
	s_nop 0
	s_nop 0
	s_waitcnt vmcnt(6)
	s_waitcnt lgkmcnt(0)
	s_barrier
; #define PG8_STAGE(bufoff, gbase, voff) do { const unsigned long long gb_ = (unsigned long long)(gbase); _Pragma("unroll") for (int _i = 0; _i < 2; ++_i) { unsigned keep_; \
;         asm volatile("s_mov_b32 m0, %2\n\ts_nop 0\n\tglobal_load_lds_dwordx4 %0, %1" : : "v"((voff)[_i]), "s"(gb_), "s"((unsigned)(size_t)(lds + (bufoff) + ldsw + _i * 8192)) : "memory", "m0"); (void)keep_; } } while (0)
; #define PG8_LDA(dst, b, h) do { _Pragma("unroll") for (int m = 0; m < 4; ++m) _Pragma("unroll") for (int k = 0; k < 2; ++k) dst[m][k] = *(const PG8_LAS bf16x8*)(lds + PG8_SA(b, h) + aoff + m * 2048 + k * 1024); } while (0)
; #define PG8_LDB(dst, b, h) do { _Pragma("unroll") for (int n = 0; n < 2; ++n) _Pragma("unroll") for (int k = 0; k < 2; ++k) dst[n][k] = *(const PG8_LAS bf16x8*)(lds + PG8_SB(b, h) + boff + n * 2048 + k * 1024); } while (0)
; #define PG8_MMA(ai, bj, At, Bt) do { __builtin_amdgcn_s_setprio(1); _Pragma("unroll") for (int m = 0; m < 4; ++m) _Pragma("unroll") for (int n = 0; n < 2; ++n) _Pragma("unroll") for (int k = 0; k < 2; ++k) \
;         acc[ai][bj][m][n] = __builtin_amdgcn_mfma_f32_16x16x32_bf16(Bt[n][k], At[m][k], acc[ai][bj][m][n], 0, 0, 0); __builtin_amdgcn_s_setprio(0); } while (0)
; #define PG8_WAIT_V(n) asm volatile("s_waitcnt vmcnt(" #n ")" ::: "memory")
; #define PG8_WAIT_L(n) asm volatile("s_waitcnt lgkmcnt(" #n ")" ::: "memory")
; #define PG8_BAR __builtin_amdgcn_s_barrier()
; #define PG8_SCHED __builtin_amdgcn_sched_barrier(0)
; template <class Epi, class Sched, bool ALIGN_EPI = false, bool SP2 = false>
; __device__ __forceinline__ void gemm_phase(PG8_LAS unsigned char* lds, const Gemm g, const Sched& S, const Epi& E) {
;     ...
;             PG8_WAIT_V(8); PG8_WAIT_L(0); PG8_BAR; PG8_MMA(1, 0, At, B0); PG8_MMA(1, 1, At, B1); PG8_BAR; PG8_SCHED;
;             PG8_LDB(B0, 1, 0); PG8_LDB(B1, 1, 1); PG8_SCHED; PG8_LDA(At, 1, 0); PG8_STAGE(PG8_SA(0, 1), a2 + hstepA, voffA);
	s_setprio 1
	s_waitcnt lgkmcnt(7)
	v_mfma_f32_16x16x32_bf16 v[60:63], v[156:159], v[214:217], v[60:63]
	v_mfma_f32_16x16x32_bf16 v[52:55], v[188:191], v[214:217], v[52:55]
	s_waitcnt lgkmcnt(5)
	v_mfma_f32_16x16x32_bf16 v[44:47], v[156:159], v[222:225], v[44:47]
	v_mfma_f32_16x16x32_bf16 v[36:39], v[188:191], v[222:225], v[36:39]
	s_waitcnt lgkmcnt(3)
	v_mfma_f32_16x16x32_bf16 v[28:31], v[156:159], v[230:233], v[28:31]
	v_mfma_f32_16x16x32_bf16 v[20:23], v[188:191], v[230:233], v[20:23]
	s_waitcnt lgkmcnt(1)
	v_mfma_f32_16x16x32_bf16 v[12:15], v[156:159], v[238:241], v[12:15]
	v_mfma_f32_16x16x32_bf16 v[4:7], v[188:191], v[238:241], v[4:7]
	v_mfma_f32_16x16x32_bf16 v[60:63], v[184:187], v[218:221], v[60:63]
	v_mfma_f32_16x16x32_bf16 v[52:55], v[192:195], v[218:221], v[52:55]
	v_mfma_f32_16x16x32_bf16 v[44:47], v[184:187], v[226:229], v[44:47]
	v_mfma_f32_16x16x32_bf16 v[36:39], v[192:195], v[226:229], v[36:39]
	v_mfma_f32_16x16x32_bf16 v[28:31], v[184:187], v[234:237], v[28:31]
	v_mfma_f32_16x16x32_bf16 v[20:23], v[192:195], v[234:237], v[20:23]
	s_waitcnt lgkmcnt(0)
	v_mfma_f32_16x16x32_bf16 v[12:15], v[184:187], v[242:245], v[12:15]
	v_mfma_f32_16x16x32_bf16 v[4:7], v[192:195], v[242:245], v[4:7]
	s_setprio 0
	s_setprio 1
	v_mfma_f32_16x16x32_bf16 v[56:59], v[196:199], v[214:217], v[56:59]
	v_mfma_f32_16x16x32_bf16 v[48:51], v[206:209], v[214:217], v[48:51]
	v_mfma_f32_16x16x32_bf16 v[40:43], v[196:199], v[222:225], v[40:43]
	v_mfma_f32_16x16x32_bf16 v[32:35], v[206:209], v[222:225], v[32:35]
	v_mfma_f32_16x16x32_bf16 v[24:27], v[196:199], v[230:233], v[24:27]
	v_mfma_f32_16x16x32_bf16 v[16:19], v[206:209], v[230:233], v[16:19]
	v_mfma_f32_16x16x32_bf16 v[8:11], v[196:199], v[238:241], v[8:11]
	v_mfma_f32_16x16x32_bf16 v[0:3], v[206:209], v[238:241], v[0:3]
	v_mfma_f32_16x16x32_bf16 v[56:59], v[202:205], v[218:221], v[56:59]
	v_mfma_f32_16x16x32_bf16 v[48:51], v[210:213], v[218:221], v[48:51]
	v_mfma_f32_16x16x32_bf16 v[40:43], v[202:205], v[226:229], v[40:43]
	v_mfma_f32_16x16x32_bf16 v[32:35], v[210:213], v[226:229], v[32:35]
	v_mfma_f32_16x16x32_bf16 v[24:27], v[202:205], v[234:237], v[24:27]
	v_mfma_f32_16x16x32_bf16 v[16:19], v[210:213], v[234:237], v[16:19]
	v_mfma_f32_16x16x32_bf16 v[8:11], v[202:205], v[242:245], v[8:11]
	v_mfma_f32_16x16x32_bf16 v[0:3], v[210:213], v[242:245], v[0:3]
	s_setprio 0
	s_barrier
	ds_read_b128 v[156:159], v180
	ds_read_b128 v[184:187], v180 offset:1024
	ds_read_b128 v[188:191], v180 offset:2048
	ds_read_b128 v[192:195], v180 offset:3072
	ds_read_b128 v[196:199], v181
	ds_read_b128 v[202:205], v181 offset:1024
	ds_read_b128 v[206:209], v181 offset:2048
	ds_read_b128 v[210:213], v181 offset:3072
	ds_read_b128 v[214:217], v179 offset:32768
	ds_read_b128 v[218:221], v179 offset:33792
	ds_read_b128 v[222:225], v179 offset:34816
	ds_read_b128 v[226:229], v179 offset:35840
	ds_read_b128 v[230:233], v179 offset:36864
	ds_read_b128 v[234:237], v179 offset:37888
	ds_read_b128 v[238:241], v179 offset:38912
	ds_read_b128 v[242:245], v179 offset:39936
	s_mov_b32 m0, s31
	s_nop 0
	global_load_lds_dwordx4 v161, s[40:41]
	s_nop 0
	s_mov_b32 m0, s49
	s_nop 0
	global_load_lds_dwordx4 v163, s[40:41]
	s_nop 0
	s_add_u32 s40, s40, 0x10000
	s_addc_u32 s41, s41, 0
	s_mov_b32 m0, s50
	s_nop 0
	global_load_lds_dwordx4 v161, s[40:41]
	s_nop 0
	s_mov_b32 m0, s51
	s_nop 0
	global_load_lds_dwordx4 v163, s[40:41]
	s_waitcnt vmcnt(8)
	s_waitcnt lgkmcnt(0)
	s_barrier
; #define PG8_STAGE(bufoff, gbase, voff) do { const unsigned long long gb_ = (unsigned long long)(gbase); _Pragma("unroll") for (int _i = 0; _i < 2; ++_i) { unsigned keep_; \
;         asm volatile("s_mov_b32 m0, %2\n\ts_nop 0\n\tglobal_load_lds_dwordx4 %0, %1" : : "v"((voff)[_i]), "s"(gb_), "s"((unsigned)(size_t)(lds + (bufoff) + ldsw + _i * 8192)) : "memory", "m0"); (void)keep_; } } while (0)
; #define PG8_LDA(dst, b, h) do { _Pragma("unroll") for (int m = 0; m < 4; ++m) _Pragma("unroll") for (int k = 0; k < 2; ++k) dst[m][k] = *(const PG8_LAS bf16x8*)(lds + PG8_SA(b, h) + aoff + m * 2048 + k * 1024); } while (0)
; #define PG8_MMA(ai, bj, At, Bt) do { __builtin_amdgcn_s_setprio(1); _Pragma("unroll") for (int m = 0; m < 4; ++m) _Pragma("unroll") for (int n = 0; n < 2; ++n) _Pragma("unroll") for (int k = 0; k < 2; ++k) \
;         acc[ai][bj][m][n] = __builtin_amdgcn_mfma_f32_16x16x32_bf16(Bt[n][k], At[m][k], acc[ai][bj][m][n], 0, 0, 0); __builtin_amdgcn_s_setprio(0); } while (0)
; #define PG8_WAIT_V(n) asm volatile("s_waitcnt vmcnt(" #n ")" ::: "memory")
; #define PG8_WAIT_L(n) asm volatile("s_waitcnt lgkmcnt(" #n ")" ::: "memory")
; #define PG8_BAR __builtin_amdgcn_s_barrier()
; #define PG8_SCHED __builtin_amdgcn_sched_barrier(0)
; template <class Epi, class Sched, bool ALIGN_EPI = false, bool SP2 = false>
; __device__ __forceinline__ void gemm_phase(PG8_LAS unsigned char* lds, const Gemm g, const Sched& S, const Epi& E) {
;     ...
;             PG8_WAIT_V(8); PG8_WAIT_L(0); PG8_BAR; PG8_MMA(0, 0, At, B0); PG8_MMA(0, 1, At, B1); PG8_BAR; PG8_SCHED;
;             PG8_LDA(At, 1, 1); PG8_STAGE(PG8_SB(1, 0), b3, voffB); PG8_STAGE(PG8_SB(1, 1), b3 + hstepB, voffB); PG8_STAGE(PG8_SA(1, 0), a3, voffA);
;             PG8_WAIT_V(8); PG8_WAIT_L(0); PG8_BAR; PG8_MMA(1, 0, At, B0); PG8_MMA(1, 1, At, B1); PG8_BAR; PG8_SCHED;
	s_setprio 1
	s_waitcnt lgkmcnt(7)
	v_mfma_f32_16x16x32_bf16 v[124:127], v[156:159], v[214:217], v[124:127]
	v_mfma_f32_16x16x32_bf16 v[116:119], v[188:191], v[214:217], v[116:119]
	s_waitcnt lgkmcnt(5)
	v_mfma_f32_16x16x32_bf16 v[108:111], v[156:159], v[222:225], v[108:111]
	v_mfma_f32_16x16x32_bf16 v[100:103], v[188:191], v[222:225], v[100:103]
	s_waitcnt lgkmcnt(3)
	v_mfma_f32_16x16x32_bf16 v[92:95], v[156:159], v[230:233], v[92:95]
	v_mfma_f32_16x16x32_bf16 v[84:87], v[188:191], v[230:233], v[84:87]
	s_waitcnt lgkmcnt(1)
	v_mfma_f32_16x16x32_bf16 v[76:79], v[156:159], v[238:241], v[76:79]
	v_mfma_f32_16x16x32_bf16 v[68:71], v[188:191], v[238:241], v[68:71]
	v_mfma_f32_16x16x32_bf16 v[124:127], v[184:187], v[218:221], v[124:127]
	v_mfma_f32_16x16x32_bf16 v[116:119], v[192:195], v[218:221], v[116:119]
	v_mfma_f32_16x16x32_bf16 v[108:111], v[184:187], v[226:229], v[108:111]
	v_mfma_f32_16x16x32_bf16 v[100:103], v[192:195], v[226:229], v[100:103]
	v_mfma_f32_16x16x32_bf16 v[92:95], v[184:187], v[234:237], v[92:95]
	v_mfma_f32_16x16x32_bf16 v[84:87], v[192:195], v[234:237], v[84:87]
	s_waitcnt lgkmcnt(0)
	v_mfma_f32_16x16x32_bf16 v[76:79], v[184:187], v[242:245], v[76:79]
	v_mfma_f32_16x16x32_bf16 v[68:71], v[192:195], v[242:245], v[68:71]
	s_setprio 0
	s_setprio 1
	v_mfma_f32_16x16x32_bf16 v[120:123], v[196:199], v[214:217], v[120:123]
	v_mfma_f32_16x16x32_bf16 v[112:115], v[206:209], v[214:217], v[112:115]
	v_mfma_f32_16x16x32_bf16 v[104:107], v[196:199], v[222:225], v[104:107]
	v_mfma_f32_16x16x32_bf16 v[96:99], v[206:209], v[222:225], v[96:99]
	v_mfma_f32_16x16x32_bf16 v[88:91], v[196:199], v[230:233], v[88:91]
	v_mfma_f32_16x16x32_bf16 v[80:83], v[206:209], v[230:233], v[80:83]
	v_mfma_f32_16x16x32_bf16 v[72:75], v[196:199], v[238:241], v[72:75]
	v_mfma_f32_16x16x32_bf16 v[64:67], v[206:209], v[238:241], v[64:67]
	v_mfma_f32_16x16x32_bf16 v[120:123], v[202:205], v[218:221], v[120:123]
	v_mfma_f32_16x16x32_bf16 v[112:115], v[210:213], v[218:221], v[112:115]
	v_mfma_f32_16x16x32_bf16 v[104:107], v[202:205], v[226:229], v[104:107]
	v_mfma_f32_16x16x32_bf16 v[96:99], v[210:213], v[226:229], v[96:99]
	v_mfma_f32_16x16x32_bf16 v[88:91], v[202:205], v[234:237], v[88:91]
	v_mfma_f32_16x16x32_bf16 v[80:83], v[210:213], v[234:237], v[80:83]
	v_mfma_f32_16x16x32_bf16 v[72:75], v[202:205], v[242:245], v[72:75]
	v_mfma_f32_16x16x32_bf16 v[64:67], v[210:213], v[242:245], v[64:67]
	s_setprio 0
	s_barrier
	ds_read_b128 v[214:217], v179 offset:49152
	ds_read_b128 v[218:221], v179 offset:50176
	ds_read_b128 v[222:225], v179 offset:51200
	ds_read_b128 v[226:229], v179 offset:52224
	ds_read_b128 v[230:233], v179 offset:53248
	ds_read_b128 v[234:237], v179 offset:54272
	ds_read_b128 v[238:241], v179 offset:55296
	ds_read_b128 v[242:245], v179 offset:56320
	s_add_u32 s40, s38, 0x80
	s_addc_u32 s41, s39, 0
	s_mov_b32 m0, s55
	s_nop 0
	global_load_lds_dwordx4 v175, s[40:41]
	s_add_u32 s38, s38, 0x80080
	s_mov_b32 m0, s56
	s_nop 0
	global_load_lds_dwordx4 v176, s[40:41]
	s_addc_u32 s39, s39, 0
	s_mov_b32 m0, s59
	s_nop 0
	global_load_lds_dwordx4 v175, s[38:39]
	s_nop 0
	s_mov_b32 m0, s60
	s_nop 0
	global_load_lds_dwordx4 v176, s[38:39]
	s_nop 0
	s_nop 0
	s_waitcnt vmcnt(6)
	s_waitcnt lgkmcnt(0)
	s_barrier
	s_setprio 1
	s_waitcnt lgkmcnt(7)
	v_mfma_f32_16x16x32_bf16 v[60:63], v[156:159], v[214:217], v[60:63]
	v_mfma_f32_16x16x32_bf16 v[52:55], v[188:191], v[214:217], v[52:55]
	s_waitcnt lgkmcnt(5)
	v_mfma_f32_16x16x32_bf16 v[44:47], v[156:159], v[222:225], v[44:47]
	v_mfma_f32_16x16x32_bf16 v[36:39], v[188:191], v[222:225], v[36:39]
	s_waitcnt lgkmcnt(3)
	v_mfma_f32_16x16x32_bf16 v[28:31], v[156:159], v[230:233], v[28:31]
	v_mfma_f32_16x16x32_bf16 v[20:23], v[188:191], v[230:233], v[20:23]
	s_waitcnt lgkmcnt(1)
	v_mfma_f32_16x16x32_bf16 v[12:15], v[156:159], v[238:241], v[12:15]
	v_mfma_f32_16x16x32_bf16 v[4:7], v[188:191], v[238:241], v[4:7]
	v_mfma_f32_16x16x32_bf16 v[60:63], v[184:187], v[218:221], v[60:63]
	v_mfma_f32_16x16x32_bf16 v[52:55], v[192:195], v[218:221], v[52:55]
	v_mfma_f32_16x16x32_bf16 v[44:47], v[184:187], v[226:229], v[44:47]
	v_mfma_f32_16x16x32_bf16 v[36:39], v[192:195], v[226:229], v[36:39]
	v_mfma_f32_16x16x32_bf16 v[28:31], v[184:187], v[234:237], v[28:31]
	v_mfma_f32_16x16x32_bf16 v[20:23], v[192:195], v[234:237], v[20:23]
	s_waitcnt lgkmcnt(0)
	v_mfma_f32_16x16x32_bf16 v[12:15], v[184:187], v[242:245], v[12:15]
	v_mfma_f32_16x16x32_bf16 v[4:7], v[192:195], v[242:245], v[4:7]
	s_setprio 0
	s_setprio 1
	v_mfma_f32_16x16x32_bf16 v[56:59], v[196:199], v[214:217], v[56:59]
	v_mfma_f32_16x16x32_bf16 v[48:51], v[206:209], v[214:217], v[48:51]
	v_mfma_f32_16x16x32_bf16 v[40:43], v[196:199], v[222:225], v[40:43]
	v_mfma_f32_16x16x32_bf16 v[32:35], v[206:209], v[222:225], v[32:35]
	v_mfma_f32_16x16x32_bf16 v[24:27], v[196:199], v[230:233], v[24:27]
	v_mfma_f32_16x16x32_bf16 v[16:19], v[206:209], v[230:233], v[16:19]
	v_mfma_f32_16x16x32_bf16 v[8:11], v[196:199], v[238:241], v[8:11]
	v_mfma_f32_16x16x32_bf16 v[0:3], v[206:209], v[238:241], v[0:3]
	v_mfma_f32_16x16x32_bf16 v[56:59], v[202:205], v[218:221], v[56:59]
	v_mfma_f32_16x16x32_bf16 v[48:51], v[210:213], v[218:221], v[48:51]
	v_mfma_f32_16x16x32_bf16 v[40:43], v[202:205], v[226:229], v[40:43]
	v_mfma_f32_16x16x32_bf16 v[32:35], v[210:213], v[226:229], v[32:35]
	v_mfma_f32_16x16x32_bf16 v[24:27], v[202:205], v[234:237], v[24:27]
	v_mfma_f32_16x16x32_bf16 v[16:19], v[210:213], v[234:237], v[16:19]
	v_mfma_f32_16x16x32_bf16 v[8:11], v[202:205], v[242:245], v[8:11]
	v_mfma_f32_16x16x32_bf16 v[0:3], v[210:213], v[242:245], v[0:3]
	s_setprio 0
	s_barrier
	s_add_i32 s70, s70, 2
	s_add_i32 s71, s71, 0x10000
	s_cmp_gt_u32 s70, 29
	s_mov_b64 s[34:35], s[36:37]
	s_cbranch_scc0 .LBB0_953
	s_and_b64 vcc, exec, s[18:19]
	s_cbranch_vccz .LBB0_956
	s_barrier

; #define PG8_STAGE(bufoff, gbase, voff) do { const unsigned long long gb_ = (unsigned long long)(gbase); _Pragma("unroll") for (int _i = 0; _i < 2; ++_i) { unsigned keep_; \
;         asm volatile("s_mov_b32 m0, %2\n\ts_nop 0\n\tglobal_load_lds_dwordx4 %0, %1" : : "v"((voff)[_i]), "s"(gb_), "s"((unsigned)(size_t)(lds + (bufoff) + ldsw + _i * 8192)) : "memory", "m0"); (void)keep_; } } while (0)
; #define PG8_LDA(dst, b, h) do { _Pragma("unroll") for (int m = 0; m < 4; ++m) _Pragma("unroll") for (int k = 0; k < 2; ++k) dst[m][k] = *(const PG8_LAS bf16x8*)(lds + PG8_SA(b, h) + aoff + m * 2048 + k * 1024); } while (0)
; #define PG8_LDB(dst, b, h) do { _Pragma("unroll") for (int n = 0; n < 2; ++n) _Pragma("unroll") for (int k = 0; k < 2; ++k) dst[n][k] = *(const PG8_LAS bf16x8*)(lds + PG8_SB(b, h) + boff + n * 2048 + k * 1024); } while (0)
; #define PG8_MMA(ai, bj, At, Bt) do { __builtin_amdgcn_s_setprio(1); _Pragma("unroll") for (int m = 0; m < 4; ++m) _Pragma("unroll") for (int n = 0; n < 2; ++n) _Pragma("unroll") for (int k = 0; k < 2; ++k) \
;         acc[ai][bj][m][n] = __builtin_amdgcn_mfma_f32_16x16x32_bf16(Bt[n][k], At[m][k], acc[ai][bj][m][n], 0, 0, 0); __builtin_amdgcn_s_setprio(0); } while (0)
; template <class Epi, class Sched, bool ALIGN_EPI = false, bool SP2 = false>
; __device__ __forceinline__ void gemm_phase(PG8_LAS unsigned char* lds, const Gemm g, const Sched& S, const Epi& E) {
;     ...
;         for (int t = 0; t < nt; t += 2) {
;             const bool last = (t == nt - 2);
;     ...
;             const char* a1 = cA + PG8_KOFFA(t + 1);
;             const char* a2 = last ? nA : cA + PG8_KOFFA(t + 2); const char* b2 = last ? nB : cB + (size_t)(t + 2) * kstep;
;             const char* a3 = last ? nA + kstep : cA + PG8_KOFFA(t + 3); const char* b3 = b2 + kstep;
;     ...
;             if (last && has_next) S.a_ready(nxt);
;             if constexpr (SP2) {
;             PG8_LDB(B0, 0, 0); PG8_LDB(B1, 0, 1); PG8_SCHED; PG8_LDA(At, 0, 0); PG8_STAGE(PG8_SA(1, 1), a1 + hstepA, voffA);
;             PG8_WAIT_V(8); PG8_WAIT_L(0); PG8_BAR; PG8_MMA(0, 0, At, B0); PG8_MMA(0, 1, At, B1); PG8_BAR; PG8_SCHED;
;             PG8_LDA(At, 0, 1); PG8_STAGE(PG8_SB(0, 0), b2, voffB); PG8_STAGE(PG8_SB(0, 1), b2 + hstepB, voffB); PG8_STAGE(PG8_SA(0, 0), a2, voffA);
;             PG8_WAIT_V(8); PG8_WAIT_L(0); PG8_BAR; PG8_MMA(1, 0, At, B0); PG8_MMA(1, 1, At, B1); PG8_BAR; PG8_SCHED;
.LBB0_1114:
	ds_read_b128 v[104:107], v185
	ds_read_b128 v[108:111], v185 offset:1024
	ds_read_b128 v[124:127], v185 offset:2048
	ds_read_b128 v[140:143], v185 offset:3072
	ds_read_b128 v[144:147], v214
	ds_read_b128 v[148:151], v214 offset:1024
	ds_read_b128 v[152:155], v214 offset:2048
	ds_read_b128 v[156:159], v214 offset:3072
	s_cmpk_eq_i32 s66, 0x54
	s_cselect_b32 s36, s10, s0
	s_cselect_b32 s37, s11, s1
	s_cselect_b32 s35, s27, s65
	s_cselect_b32 s34, s26, s64
	s_add_u32 s30, s36, 0x80
	s_addc_u32 s31, s37, 0
	ds_read_b128 v[160:163], v215
	ds_read_b128 v[164:167], v215 offset:1024
	ds_read_b128 v[168:171], v215 offset:2048
	ds_read_b128 v[172:175], v215 offset:3072
	ds_read_b128 v[176:179], v215 offset:4096
	ds_read_b128 v[180:183], v215 offset:5120
	ds_read_b128 v[220:223], v215 offset:6144
	ds_read_b128 v[224:227], v215 offset:7168
	s_sub_u32 s98, s28, 0x8000
	s_subb_u32 s99, s29, 0
	s_mov_b32 m0, s52
	s_nop 0
	global_load_lds_dwordx4 v187, s[98:99]
	s_nop 0
	s_mov_b32 m0, s53
	s_nop 0
	global_load_lds_dwordx4 v212, s[98:99]
	s_nop 0
	s_mov_b32 m0, s56
	s_nop 0
	global_load_lds_dwordx4 v187, s[28:29]
	s_nop 0
	s_mov_b32 m0, s57
	s_nop 0
	global_load_lds_dwordx4 v212, s[28:29]
	s_waitcnt vmcnt(8)
	s_waitcnt lgkmcnt(0)
	s_barrier
	s_setprio 1
	s_waitcnt lgkmcnt(7)
	v_mfma_f32_16x16x32_bf16 v[136:139], v[104:107], v[160:163], v[136:139]
	v_mfma_f32_16x16x32_bf16 v[132:135], v[124:127], v[160:163], v[132:135]
	s_waitcnt lgkmcnt(5)
	v_mfma_f32_16x16x32_bf16 v[116:119], v[104:107], v[168:171], v[116:119]
	v_mfma_f32_16x16x32_bf16 v[112:115], v[124:127], v[168:171], v[112:115]
	s_waitcnt lgkmcnt(3)
	v_mfma_f32_16x16x32_bf16 v[92:95], v[104:107], v[176:179], v[92:95]
	v_mfma_f32_16x16x32_bf16 v[88:91], v[124:127], v[176:179], v[88:91]
	s_waitcnt lgkmcnt(1)
	v_mfma_f32_16x16x32_bf16 v[76:79], v[104:107], v[220:223], v[76:79]
	v_mfma_f32_16x16x32_bf16 v[72:75], v[124:127], v[220:223], v[72:75]
	v_mfma_f32_16x16x32_bf16 v[136:139], v[108:111], v[164:167], v[136:139]
	v_mfma_f32_16x16x32_bf16 v[132:135], v[140:143], v[164:167], v[132:135]
	v_mfma_f32_16x16x32_bf16 v[116:119], v[108:111], v[172:175], v[116:119]
	v_mfma_f32_16x16x32_bf16 v[112:115], v[140:143], v[172:175], v[112:115]
	v_mfma_f32_16x16x32_bf16 v[92:95], v[108:111], v[180:183], v[92:95]
	v_mfma_f32_16x16x32_bf16 v[88:91], v[140:143], v[180:183], v[88:91]
	s_waitcnt lgkmcnt(0)
	v_mfma_f32_16x16x32_bf16 v[76:79], v[108:111], v[224:227], v[76:79]
	v_mfma_f32_16x16x32_bf16 v[72:75], v[140:143], v[224:227], v[72:75]
	s_setprio 0
	s_setprio 1
	v_mfma_f32_16x16x32_bf16 v[128:131], v[144:147], v[160:163], v[128:131]
	v_mfma_f32_16x16x32_bf16 v[120:123], v[152:155], v[160:163], v[120:123]
	v_mfma_f32_16x16x32_bf16 v[100:103], v[144:147], v[168:171], v[100:103]
	v_mfma_f32_16x16x32_bf16 v[96:99], v[152:155], v[168:171], v[96:99]
	v_mfma_f32_16x16x32_bf16 v[84:87], v[144:147], v[176:179], v[84:87]
	v_mfma_f32_16x16x32_bf16 v[80:83], v[152:155], v[176:179], v[80:83]
	v_mfma_f32_16x16x32_bf16 v[68:71], v[144:147], v[220:223], v[68:71]
	v_mfma_f32_16x16x32_bf16 v[64:67], v[152:155], v[220:223], v[64:67]
	v_mfma_f32_16x16x32_bf16 v[128:131], v[148:151], v[164:167], v[128:131]
	v_mfma_f32_16x16x32_bf16 v[120:123], v[156:159], v[164:167], v[120:123]
	v_mfma_f32_16x16x32_bf16 v[100:103], v[148:151], v[172:175], v[100:103]
	v_mfma_f32_16x16x32_bf16 v[96:99], v[156:159], v[172:175], v[96:99]
	v_mfma_f32_16x16x32_bf16 v[84:87], v[148:151], v[180:183], v[84:87]
	v_mfma_f32_16x16x32_bf16 v[80:83], v[156:159], v[180:183], v[80:83]
	v_mfma_f32_16x16x32_bf16 v[68:71], v[148:151], v[224:227], v[68:71]
	v_mfma_f32_16x16x32_bf16 v[64:67], v[156:159], v[224:227], v[64:67]
	s_setprio 0
	s_barrier
	ds_read_b128 v[160:163], v215 offset:16384
	ds_read_b128 v[164:167], v215 offset:17408
	ds_read_b128 v[168:171], v215 offset:18432
	ds_read_b128 v[172:175], v215 offset:19456
	ds_read_b128 v[176:179], v215 offset:20480
	ds_read_b128 v[180:183], v215 offset:21504
	ds_read_b128 v[220:223], v215 offset:22528
	ds_read_b128 v[224:227], v215 offset:23552
	s_mov_b32 m0, s42
	s_nop 0
	global_load_lds_dwordx4 v201, s[34:35]
	s_add_u32 s68, s34, 0x160000
	s_mov_b32 m0, s43
	s_nop 0
	global_load_lds_dwordx4 v213, s[34:35]
	s_addc_u32 s69, s35, 0
	s_mov_b32 m0, s44
	s_nop 0
	global_load_lds_dwordx4 v201, s[68:69]
	s_nop 0
	s_mov_b32 m0, s45
	s_nop 0
	global_load_lds_dwordx4 v213, s[68:69]
	s_nop 0
	s_nop 0
	s_waitcnt vmcnt(6)
	s_waitcnt lgkmcnt(0)
	s_barrier
	s_setprio 1
	s_waitcnt lgkmcnt(7)
	v_mfma_f32_16x16x32_bf16 v[60:63], v[104:107], v[160:163], v[60:63]
	v_mfma_f32_16x16x32_bf16 v[56:59], v[124:127], v[160:163], v[56:59]
	s_waitcnt lgkmcnt(5)
	v_mfma_f32_16x16x32_bf16 v[44:47], v[104:107], v[168:171], v[44:47]
	v_mfma_f32_16x16x32_bf16 v[40:43], v[124:127], v[168:171], v[40:43]
	s_waitcnt lgkmcnt(3)
	v_mfma_f32_16x16x32_bf16 v[28:31], v[104:107], v[176:179], v[28:31]
	v_mfma_f32_16x16x32_bf16 v[24:27], v[124:127], v[176:179], v[24:27]
	s_waitcnt lgkmcnt(1)
	v_mfma_f32_16x16x32_bf16 v[12:15], v[104:107], v[220:223], v[12:15]
	v_mfma_f32_16x16x32_bf16 v[8:11], v[124:127], v[220:223], v[8:11]
	v_mfma_f32_16x16x32_bf16 v[60:63], v[108:111], v[164:167], v[60:63]
	v_mfma_f32_16x16x32_bf16 v[56:59], v[140:143], v[164:167], v[56:59]
	v_mfma_f32_16x16x32_bf16 v[44:47], v[108:111], v[172:175], v[44:47]
	v_mfma_f32_16x16x32_bf16 v[40:43], v[140:143], v[172:175], v[40:43]
	v_mfma_f32_16x16x32_bf16 v[28:31], v[108:111], v[180:183], v[28:31]
	v_mfma_f32_16x16x32_bf16 v[24:27], v[140:143], v[180:183], v[24:27]
	s_waitcnt lgkmcnt(0)
	v_mfma_f32_16x16x32_bf16 v[12:15], v[108:111], v[224:227], v[12:15]
	v_mfma_f32_16x16x32_bf16 v[8:11], v[140:143], v[224:227], v[8:11]
	s_setprio 0
	s_setprio 1
	v_mfma_f32_16x16x32_bf16 v[52:55], v[144:147], v[160:163], v[52:55]
	v_mfma_f32_16x16x32_bf16 v[48:51], v[152:155], v[160:163], v[48:51]
	v_mfma_f32_16x16x32_bf16 v[36:39], v[144:147], v[168:171], v[36:39]
	v_mfma_f32_16x16x32_bf16 v[32:35], v[152:155], v[168:171], v[32:35]
	v_mfma_f32_16x16x32_bf16 v[20:23], v[144:147], v[176:179], v[20:23]
	v_mfma_f32_16x16x32_bf16 v[16:19], v[152:155], v[176:179], v[16:19]
	v_mfma_f32_16x16x32_bf16 v[4:7], v[144:147], v[220:223], v[4:7]
	v_mfma_f32_16x16x32_bf16 v[0:3], v[152:155], v[220:223], v[0:3]
	v_mfma_f32_16x16x32_bf16 v[52:55], v[148:151], v[164:167], v[52:55]
	v_mfma_f32_16x16x32_bf16 v[48:51], v[156:159], v[164:167], v[48:51]
	v_mfma_f32_16x16x32_bf16 v[36:39], v[148:151], v[172:175], v[36:39]
	v_mfma_f32_16x16x32_bf16 v[32:35], v[156:159], v[172:175], v[32:35]
	v_mfma_f32_16x16x32_bf16 v[20:23], v[148:151], v[180:183], v[20:23]
	v_mfma_f32_16x16x32_bf16 v[16:19], v[156:159], v[180:183], v[16:19]
	v_mfma_f32_16x16x32_bf16 v[4:7], v[148:151], v[224:227], v[4:7]
	v_mfma_f32_16x16x32_bf16 v[0:3], v[156:159], v[224:227], v[0:3]
	s_setprio 0
	s_barrier
; #define PG8_STAGE(bufoff, gbase, voff) do { const unsigned long long gb_ = (unsigned long long)(gbase); _Pragma("unroll") for (int _i = 0; _i < 2; ++_i) { unsigned keep_; \
;         asm volatile("s_mov_b32 m0, %2\n\ts_nop 0\n\tglobal_load_lds_dwordx4 %0, %1" : : "v"((voff)[_i]), "s"(gb_), "s"((unsigned)(size_t)(lds + (bufoff) + ldsw + _i * 8192)) : "memory", "m0"); (void)keep_; } } while (0)
; #define PG8_LDA(dst, b, h) do { _Pragma("unroll") for (int m = 0; m < 4; ++m) _Pragma("unroll") for (int k = 0; k < 2; ++k) dst[m][k] = *(const PG8_LAS bf16x8*)(lds + PG8_SA(b, h) + aoff + m * 2048 + k * 1024); } while (0)
; #define PG8_LDB(dst, b, h) do { _Pragma("unroll") for (int n = 0; n < 2; ++n) _Pragma("unroll") for (int k = 0; k < 2; ++k) dst[n][k] = *(const PG8_LAS bf16x8*)(lds + PG8_SB(b, h) + boff + n * 2048 + k * 1024); } while (0)
; #define PG8_MMA(ai, bj, At, Bt) do { __builtin_amdgcn_s_setprio(1); _Pragma("unroll") for (int m = 0; m < 4; ++m) _Pragma("unroll") for (int n = 0; n < 2; ++n) _Pragma("unroll") for (int k = 0; k < 2; ++k) \
;         acc[ai][bj][m][n] = __builtin_amdgcn_mfma_f32_16x16x32_bf16(Bt[n][k], At[m][k], acc[ai][bj][m][n], 0, 0, 0); __builtin_amdgcn_s_setprio(0); } while (0)
; #define PG8_WAIT_V(n) asm volatile("s_waitcnt vmcnt(" #n ")" ::: "memory")
; #define PG8_WAIT_L(n) asm volatile("s_waitcnt lgkmcnt(" #n ")" ::: "memory")
; #define PG8_BAR __builtin_amdgcn_s_barrier()
; #define PG8_SCHED __builtin_amdgcn_sched_barrier(0)
; template <class Epi, class Sched, bool ALIGN_EPI = false, bool SP2 = false>
; __device__ __forceinline__ void gemm_phase(PG8_LAS unsigned char* lds, const Gemm g, const Sched& S, const Epi& E) {
;     ...
;             PG8_LDB(B0, 1, 0); PG8_LDB(B1, 1, 1); PG8_SCHED; PG8_LDA(At, 1, 0); PG8_STAGE(PG8_SA(0, 1), a2 + hstepA, voffA);
;             PG8_WAIT_V(8); PG8_WAIT_L(0); PG8_BAR; PG8_MMA(0, 0, At, B0); PG8_MMA(0, 1, At, B1); PG8_BAR; PG8_SCHED;
;             PG8_LDA(At, 1, 1); PG8_STAGE(PG8_SB(1, 0), b3, voffB); PG8_STAGE(PG8_SB(1, 1), b3 + hstepB, voffB); PG8_STAGE(PG8_SA(1, 0), a3, voffA);
;             PG8_WAIT_V(8); PG8_WAIT_L(0); PG8_BAR; PG8_MMA(1, 0, At, B0); PG8_MMA(1, 1, At, B1); PG8_BAR; PG8_SCHED;
	ds_read_b128 v[104:107], v216
	ds_read_b128 v[108:111], v216 offset:1024
	ds_read_b128 v[124:127], v216 offset:2048
	ds_read_b128 v[140:143], v216 offset:3072
	ds_read_b128 v[144:147], v217
	ds_read_b128 v[148:151], v217 offset:1024
	ds_read_b128 v[152:155], v217 offset:2048
	ds_read_b128 v[156:159], v217 offset:3072
	ds_read_b128 v[160:163], v215 offset:32768
	ds_read_b128 v[164:167], v215 offset:33792
	ds_read_b128 v[168:171], v215 offset:34816
	ds_read_b128 v[172:175], v215 offset:35840
	ds_read_b128 v[176:179], v215 offset:36864
	ds_read_b128 v[180:183], v215 offset:37888
	ds_read_b128 v[220:223], v215 offset:38912
	ds_read_b128 v[224:227], v215 offset:39936
	s_mov_b32 m0, s41
	s_nop 0
	global_load_lds_dwordx4 v187, s[36:37]
	s_nop 0
	s_mov_b32 m0, s46
	s_nop 0
	global_load_lds_dwordx4 v212, s[36:37]
	s_nop 0
	s_add_u32 s36, s36, 0x8000
	s_addc_u32 s37, s37, 0
	s_mov_b32 m0, s47
	s_nop 0
	global_load_lds_dwordx4 v187, s[36:37]
	s_nop 0
	s_mov_b32 m0, s48
	s_nop 0
	global_load_lds_dwordx4 v212, s[36:37]
	s_waitcnt vmcnt(8)
	s_waitcnt lgkmcnt(0)
	s_barrier
	s_setprio 1
	s_waitcnt lgkmcnt(7)
	v_mfma_f32_16x16x32_bf16 v[136:139], v[104:107], v[160:163], v[136:139]
	v_mfma_f32_16x16x32_bf16 v[132:135], v[124:127], v[160:163], v[132:135]
	s_waitcnt lgkmcnt(5)
	v_mfma_f32_16x16x32_bf16 v[116:119], v[104:107], v[168:171], v[116:119]
	v_mfma_f32_16x16x32_bf16 v[112:115], v[124:127], v[168:171], v[112:115]
	s_waitcnt lgkmcnt(3)
	v_mfma_f32_16x16x32_bf16 v[92:95], v[104:107], v[176:179], v[92:95]
	v_mfma_f32_16x16x32_bf16 v[88:91], v[124:127], v[176:179], v[88:91]
	s_waitcnt lgkmcnt(1)
	v_mfma_f32_16x16x32_bf16 v[76:79], v[104:107], v[220:223], v[76:79]
	v_mfma_f32_16x16x32_bf16 v[72:75], v[124:127], v[220:223], v[72:75]
	v_mfma_f32_16x16x32_bf16 v[136:139], v[108:111], v[164:167], v[136:139]
	v_mfma_f32_16x16x32_bf16 v[132:135], v[140:143], v[164:167], v[132:135]
	v_mfma_f32_16x16x32_bf16 v[116:119], v[108:111], v[172:175], v[116:119]
	v_mfma_f32_16x16x32_bf16 v[112:115], v[140:143], v[172:175], v[112:115]
	v_mfma_f32_16x16x32_bf16 v[92:95], v[108:111], v[180:183], v[92:95]
	v_mfma_f32_16x16x32_bf16 v[88:91], v[140:143], v[180:183], v[88:91]
	s_waitcnt lgkmcnt(0)
	v_mfma_f32_16x16x32_bf16 v[76:79], v[108:111], v[224:227], v[76:79]
	v_mfma_f32_16x16x32_bf16 v[72:75], v[140:143], v[224:227], v[72:75]
	s_setprio 0
	s_setprio 1
	v_mfma_f32_16x16x32_bf16 v[128:131], v[144:147], v[160:163], v[128:131]
	v_mfma_f32_16x16x32_bf16 v[120:123], v[152:155], v[160:163], v[120:123]
	v_mfma_f32_16x16x32_bf16 v[100:103], v[144:147], v[168:171], v[100:103]
	v_mfma_f32_16x16x32_bf16 v[96:99], v[152:155], v[168:171], v[96:99]
	v_mfma_f32_16x16x32_bf16 v[84:87], v[144:147], v[176:179], v[84:87]
	v_mfma_f32_16x16x32_bf16 v[80:83], v[152:155], v[176:179], v[80:83]
	v_mfma_f32_16x16x32_bf16 v[68:71], v[144:147], v[220:223], v[68:71]
	v_mfma_f32_16x16x32_bf16 v[64:67], v[152:155], v[220:223], v[64:67]
	v_mfma_f32_16x16x32_bf16 v[128:131], v[148:151], v[164:167], v[128:131]
	v_mfma_f32_16x16x32_bf16 v[120:123], v[156:159], v[164:167], v[120:123]
	v_mfma_f32_16x16x32_bf16 v[100:103], v[148:151], v[172:175], v[100:103]
	v_mfma_f32_16x16x32_bf16 v[96:99], v[156:159], v[172:175], v[96:99]
	v_mfma_f32_16x16x32_bf16 v[84:87], v[148:151], v[180:183], v[84:87]
	v_mfma_f32_16x16x32_bf16 v[80:83], v[156:159], v[180:183], v[80:83]
	v_mfma_f32_16x16x32_bf16 v[68:71], v[148:151], v[224:227], v[68:71]
	v_mfma_f32_16x16x32_bf16 v[64:67], v[156:159], v[224:227], v[64:67]
	s_setprio 0
	s_barrier
	ds_read_b128 v[160:163], v215 offset:49152
	ds_read_b128 v[164:167], v215 offset:50176
	ds_read_b128 v[168:171], v215 offset:51200
	ds_read_b128 v[172:175], v215 offset:52224
	ds_read_b128 v[176:179], v215 offset:53248
	ds_read_b128 v[180:183], v215 offset:54272
	ds_read_b128 v[220:223], v215 offset:55296
	ds_read_b128 v[224:227], v215 offset:56320
	s_add_u32 s36, s34, 0x80
	s_addc_u32 s37, s35, 0
	s_mov_b32 m0, s50
	s_nop 0
	global_load_lds_dwordx4 v201, s[36:37]
	s_add_u32 s34, s34, 0x160080
	s_mov_b32 m0, s51
	s_nop 0
	global_load_lds_dwordx4 v213, s[36:37]
	s_addc_u32 s35, s35, 0
	s_mov_b32 m0, s54
	s_nop 0
	global_load_lds_dwordx4 v201, s[34:35]
	s_nop 0
	s_mov_b32 m0, s55
	s_nop 0
	global_load_lds_dwordx4 v213, s[34:35]
	s_nop 0
	s_nop 0
	s_waitcnt vmcnt(6)
	s_waitcnt lgkmcnt(0)
	s_barrier
	s_setprio 1
	s_waitcnt lgkmcnt(7)
	v_mfma_f32_16x16x32_bf16 v[60:63], v[104:107], v[160:163], v[60:63]
	v_mfma_f32_16x16x32_bf16 v[56:59], v[124:127], v[160:163], v[56:59]
	s_waitcnt lgkmcnt(5)
	v_mfma_f32_16x16x32_bf16 v[44:47], v[104:107], v[168:171], v[44:47]
	v_mfma_f32_16x16x32_bf16 v[40:43], v[124:127], v[168:171], v[40:43]
	s_waitcnt lgkmcnt(3)
	v_mfma_f32_16x16x32_bf16 v[28:31], v[104:107], v[176:179], v[28:31]
	v_mfma_f32_16x16x32_bf16 v[24:27], v[124:127], v[176:179], v[24:27]
	s_waitcnt lgkmcnt(1)
	v_mfma_f32_16x16x32_bf16 v[12:15], v[104:107], v[220:223], v[12:15]
	v_mfma_f32_16x16x32_bf16 v[8:11], v[124:127], v[220:223], v[8:11]
	v_mfma_f32_16x16x32_bf16 v[60:63], v[108:111], v[164:167], v[60:63]
	v_mfma_f32_16x16x32_bf16 v[56:59], v[140:143], v[164:167], v[56:59]
	v_mfma_f32_16x16x32_bf16 v[44:47], v[108:111], v[172:175], v[44:47]
	v_mfma_f32_16x16x32_bf16 v[40:43], v[140:143], v[172:175], v[40:43]
	v_mfma_f32_16x16x32_bf16 v[28:31], v[108:111], v[180:183], v[28:31]
	v_mfma_f32_16x16x32_bf16 v[24:27], v[140:143], v[180:183], v[24:27]
	s_waitcnt lgkmcnt(0)
	v_mfma_f32_16x16x32_bf16 v[12:15], v[108:111], v[224:227], v[12:15]
	v_mfma_f32_16x16x32_bf16 v[8:11], v[140:143], v[224:227], v[8:11]
	s_setprio 0
	s_setprio 1
	v_mfma_f32_16x16x32_bf16 v[52:55], v[144:147], v[160:163], v[52:55]
	v_mfma_f32_16x16x32_bf16 v[48:51], v[152:155], v[160:163], v[48:51]
	v_mfma_f32_16x16x32_bf16 v[36:39], v[144:147], v[168:171], v[36:39]
	v_mfma_f32_16x16x32_bf16 v[32:35], v[152:155], v[168:171], v[32:35]
	v_mfma_f32_16x16x32_bf16 v[20:23], v[144:147], v[176:179], v[20:23]
	v_mfma_f32_16x16x32_bf16 v[16:19], v[152:155], v[176:179], v[16:19]
	v_mfma_f32_16x16x32_bf16 v[4:7], v[144:147], v[220:223], v[4:7]
	v_mfma_f32_16x16x32_bf16 v[0:3], v[152:155], v[220:223], v[0:3]
	v_mfma_f32_16x16x32_bf16 v[52:55], v[148:151], v[164:167], v[52:55]
	v_mfma_f32_16x16x32_bf16 v[48:51], v[156:159], v[164:167], v[48:51]
	v_mfma_f32_16x16x32_bf16 v[36:39], v[148:151], v[172:175], v[36:39]
	v_mfma_f32_16x16x32_bf16 v[32:35], v[156:159], v[172:175], v[32:35]
	v_mfma_f32_16x16x32_bf16 v[20:23], v[148:151], v[180:183], v[20:23]
	v_mfma_f32_16x16x32_bf16 v[16:19], v[156:159], v[180:183], v[16:19]
	v_mfma_f32_16x16x32_bf16 v[4:7], v[148:151], v[224:227], v[4:7]
	v_mfma_f32_16x16x32_bf16 v[0:3], v[156:159], v[224:227], v[0:3]
	s_setprio 0
	s_barrier
	s_add_i32 s66, s66, 2
	s_add_u32 s0, s0, 0x10000
	s_addc_u32 s1, s1, 0
	s_add_u32 s64, s64, 0x100
	s_addc_u32 s65, s65, 0
	s_add_u32 s28, s28, 0x10000
	s_addc_u32 s29, s29, 0
	s_cmpk_gt_u32 s66, 0x55
	s_cbranch_scc0 .LBB0_1114
	s_and_b64 vcc, exec, s[24:25]
	s_cbranch_vccz .LBB0_1117
	s_barrier

; #define PG8_STAGE(bufoff, gbase, voff) do { const unsigned long long gb_ = (unsigned long long)(gbase); _Pragma("unroll") for (int _i = 0; _i < 2; ++_i) { unsigned keep_; \
;         asm volatile("s_mov_b32 m0, %2\n\ts_nop 0\n\tglobal_load_lds_dwordx4 %0, %1" : : "v"((voff)[_i]), "s"(gb_), "s"((unsigned)(size_t)(lds + (bufoff) + ldsw + _i * 8192)) : "memory", "m0"); (void)keep_; } } while (0)
; #define PG8_LDA(dst, b, h) do { _Pragma("unroll") for (int m = 0; m < 4; ++m) _Pragma("unroll") for (int k = 0; k < 2; ++k) dst[m][k] = *(const PG8_LAS bf16x8*)(lds + PG8_SA(b, h) + aoff + m * 2048 + k * 1024); } while (0)
; #define PG8_LDB(dst, b, h) do { _Pragma("unroll") for (int n = 0; n < 2; ++n) _Pragma("unroll") for (int k = 0; k < 2; ++k) dst[n][k] = *(const PG8_LAS bf16x8*)(lds + PG8_SB(b, h) + boff + n * 2048 + k * 1024); } while (0)
; #define PG8_MMA(ai, bj, At, Bt) do { __builtin_amdgcn_s_setprio(1); _Pragma("unroll") for (int m = 0; m < 4; ++m) _Pragma("unroll") for (int n = 0; n < 2; ++n) _Pragma("unroll") for (int k = 0; k < 2; ++k) \
;         acc[ai][bj][m][n] = __builtin_amdgcn_mfma_f32_16x16x32_bf16(Bt[n][k], At[m][k], acc[ai][bj][m][n], 0, 0, 0); __builtin_amdgcn_s_setprio(0); } while (0)
; #define PG8_WAIT_V(n) asm volatile("s_waitcnt vmcnt(" #n ")" ::: "memory")
; #define PG8_BAR __builtin_amdgcn_s_barrier()
; template <class Epi, class Sched, bool ALIGN_EPI = false, bool SP2 = false>
; __device__ __forceinline__ void gemm_phase(PG8_LAS unsigned char* lds, const Gemm g, const Sched& S, const Epi& E) {
;     ...
;         for (int t = 0; t < nt; t += 2) {
;             const bool last = (t == nt - 2);
;     ...
;             const char* a1 = cA + PG8_KOFFA(t + 1);
;             const char* a2 = last ? nA : cA + PG8_KOFFA(t + 2); const char* b2 = last ? nB : cB + (size_t)(t + 2) * kstep;
;             const char* a3 = last ? nA + kstep : cA + PG8_KOFFA(t + 3); const char* b3 = b2 + kstep;
;     ...
;             if (last && has_next) S.a_ready(nxt);
;             if constexpr (SP2) {
;             PG8_LDB(B0, 0, 0); PG8_LDB(B1, 0, 1); PG8_SCHED; PG8_LDA(At, 0, 0); PG8_STAGE(PG8_SA(1, 1), a1 + hstepA, voffA);
;             PG8_WAIT_V(8); PG8_WAIT_L(0); PG8_BAR; PG8_MMA(0, 0, At, B0); PG8_MMA(0, 1, At, B1); PG8_BAR; PG8_SCHED;
;             PG8_LDA(At, 0, 1); PG8_STAGE(PG8_SB(0, 0), b2, voffB); PG8_STAGE(PG8_SB(0, 1), b2 + hstepB, voffB); PG8_STAGE(PG8_SA(0, 0), a2, voffA);
.LBB0_1235:
	s_add_i32 s45, s77, 0xfffe8000
	s_and_b32 s44, s42, 0x100
	s_and_b32 s45, s45, 0xe0000
	s_or_b32 s44, s44, s45
	s_add_u32 s78, s10, s44
	s_addc_u32 s79, s11, 0
	s_add_u32 s44, s42, 0x100
	s_addc_u32 s45, s43, 0
	s_add_i32 s47, s77, 0xffff8000
	s_and_b32 s46, s44, 0x100
	s_and_b32 s47, s47, 0x1e0000
	s_or_b32 s46, s47, s46
	ds_read_b128 v[128:131], v175
	ds_read_b128 v[132:135], v175 offset:1024
	ds_read_b128 v[162:165], v175 offset:2048
	ds_read_b128 v[166:169], v175 offset:3072
	ds_read_b128 v[182:185], v176
	ds_read_b128 v[186:189], v176 offset:1024
	ds_read_b128 v[190:193], v176 offset:2048
	ds_read_b128 v[194:197], v176 offset:3072
	s_add_u32 s46, s10, s46
	s_addc_u32 s47, s11, 0
	s_add_u32 s80, s41, s42
	s_addc_u32 s43, s73, s43
	s_add_i32 s48, s42, 0x180
	s_and_b32 s48, s48, 0x180
	s_and_b32 s49, s77, 0x1e0000
	s_or_b32 s48, s49, s48
	s_add_u32 s81, s10, s48
	s_addc_u32 s82, s11, 0
	s_cmpk_eq_i32 s42, 0xf00
	s_cselect_b32 s49, s0, s47
	s_cselect_b32 s47, s4, s43
	s_cselect_b32 s43, s35, s82
	s_cselect_b32 s42, s31, s81
	s_cselect_b32 s48, s1, s46
	s_cselect_b32 s46, s5, s80
	ds_read_b128 v[202:205], v177
	ds_read_b128 v[206:209], v177 offset:1024
	ds_read_b128 v[210:213], v177 offset:2048
	ds_read_b128 v[214:217], v177 offset:3072
	ds_read_b128 v[218:221], v177 offset:4096
	ds_read_b128 v[222:225], v177 offset:5120
	ds_read_b128 v[226:229], v177 offset:6144
	ds_read_b128 v[230:233], v177 offset:7168
	s_add_u32 s78, s78, 0x10080
	s_addc_u32 s79, s79, 0
	s_sub_u32 s98, s78, 0x10000
	s_subb_u32 s99, s79, 0
	s_mov_b32 m0, s64
	s_nop 0
	global_load_lds_dwordx4 v139, s[98:99]
	s_nop 0
	s_mov_b32 m0, s65
	s_nop 0
	global_load_lds_dwordx4 v173, s[98:99]
	s_nop 0
	s_mov_b32 m0, s68
	s_nop 0
	global_load_lds_dwordx4 v139, s[78:79]
	s_nop 0
	s_mov_b32 m0, s69
	s_nop 0
	global_load_lds_dwordx4 v173, s[78:79]
	s_waitcnt vmcnt(8)
	s_waitcnt lgkmcnt(0)
	s_barrier
	s_setprio 1
	s_waitcnt lgkmcnt(7)
	v_mfma_f32_16x16x32_bf16 v[124:127], v[128:131], v[202:205], v[124:127]
	v_mfma_f32_16x16x32_bf16 v[120:123], v[162:165], v[202:205], v[120:123]
	s_waitcnt lgkmcnt(5)
	v_mfma_f32_16x16x32_bf16 v[108:111], v[128:131], v[210:213], v[108:111]
	v_mfma_f32_16x16x32_bf16 v[104:107], v[162:165], v[210:213], v[104:107]
	s_waitcnt lgkmcnt(3)
	v_mfma_f32_16x16x32_bf16 v[92:95], v[128:131], v[218:221], v[92:95]
	v_mfma_f32_16x16x32_bf16 v[88:91], v[162:165], v[218:221], v[88:91]
	s_waitcnt lgkmcnt(1)
	v_mfma_f32_16x16x32_bf16 v[76:79], v[128:131], v[226:229], v[76:79]
	v_mfma_f32_16x16x32_bf16 v[72:75], v[162:165], v[226:229], v[72:75]
	v_mfma_f32_16x16x32_bf16 v[124:127], v[132:135], v[206:209], v[124:127]
	v_mfma_f32_16x16x32_bf16 v[120:123], v[166:169], v[206:209], v[120:123]
	v_mfma_f32_16x16x32_bf16 v[108:111], v[132:135], v[214:217], v[108:111]
	v_mfma_f32_16x16x32_bf16 v[104:107], v[166:169], v[214:217], v[104:107]
	v_mfma_f32_16x16x32_bf16 v[92:95], v[132:135], v[222:225], v[92:95]
	v_mfma_f32_16x16x32_bf16 v[88:91], v[166:169], v[222:225], v[88:91]
	s_waitcnt lgkmcnt(0)
	v_mfma_f32_16x16x32_bf16 v[76:79], v[132:135], v[230:233], v[76:79]
	v_mfma_f32_16x16x32_bf16 v[72:75], v[166:169], v[230:233], v[72:75]
	s_setprio 0
	s_setprio 1
	v_mfma_f32_16x16x32_bf16 v[116:119], v[182:185], v[202:205], v[116:119]
	v_mfma_f32_16x16x32_bf16 v[112:115], v[190:193], v[202:205], v[112:115]
	v_mfma_f32_16x16x32_bf16 v[100:103], v[182:185], v[210:213], v[100:103]
	v_mfma_f32_16x16x32_bf16 v[96:99], v[190:193], v[210:213], v[96:99]
	v_mfma_f32_16x16x32_bf16 v[84:87], v[182:185], v[218:221], v[84:87]
	v_mfma_f32_16x16x32_bf16 v[80:83], v[190:193], v[218:221], v[80:83]
	v_mfma_f32_16x16x32_bf16 v[68:71], v[182:185], v[226:229], v[68:71]
	v_mfma_f32_16x16x32_bf16 v[64:67], v[190:193], v[226:229], v[64:67]
	v_mfma_f32_16x16x32_bf16 v[116:119], v[186:189], v[206:209], v[116:119]
	v_mfma_f32_16x16x32_bf16 v[112:115], v[194:197], v[206:209], v[112:115]
	v_mfma_f32_16x16x32_bf16 v[100:103], v[186:189], v[214:217], v[100:103]
	v_mfma_f32_16x16x32_bf16 v[96:99], v[194:197], v[214:217], v[96:99]
	v_mfma_f32_16x16x32_bf16 v[84:87], v[186:189], v[222:225], v[84:87]
	v_mfma_f32_16x16x32_bf16 v[80:83], v[194:197], v[222:225], v[80:83]
	v_mfma_f32_16x16x32_bf16 v[68:71], v[186:189], v[230:233], v[68:71]
	v_mfma_f32_16x16x32_bf16 v[64:67], v[194:197], v[230:233], v[64:67]
	s_setprio 0
	s_barrier
	ds_read_b128 v[202:205], v177 offset:16384
	ds_read_b128 v[206:209], v177 offset:17408
	ds_read_b128 v[210:213], v177 offset:18432
	ds_read_b128 v[214:217], v177 offset:19456
	ds_read_b128 v[218:221], v177 offset:20480
	ds_read_b128 v[222:225], v177 offset:21504
	ds_read_b128 v[226:229], v177 offset:22528
	ds_read_b128 v[230:233], v177 offset:23552
	s_mov_b32 m0, s54
	s_nop 0
	global_load_lds_dwordx4 v172, s[46:47]
	s_add_u32 s78, s46, 0x80000
	s_mov_b32 m0, s55
	s_nop 0
	global_load_lds_dwordx4 v174, s[46:47]
	s_addc_u32 s79, s47, 0
	s_mov_b32 m0, s56
	s_nop 0
	global_load_lds_dwordx4 v172, s[78:79]
	s_nop 0
	s_mov_b32 m0, s57
	s_nop 0
	global_load_lds_dwordx4 v174, s[78:79]
	s_nop 0
	s_nop 0
	s_waitcnt vmcnt(6)
	s_waitcnt lgkmcnt(0)
	s_barrier
; #define PG8_STAGE(bufoff, gbase, voff) do { const unsigned long long gb_ = (unsigned long long)(gbase); _Pragma("unroll") for (int _i = 0; _i < 2; ++_i) { unsigned keep_; \
;         asm volatile("s_mov_b32 m0, %2\n\ts_nop 0\n\tglobal_load_lds_dwordx4 %0, %1" : : "v"((voff)[_i]), "s"(gb_), "s"((unsigned)(size_t)(lds + (bufoff) + ldsw + _i * 8192)) : "memory", "m0"); (void)keep_; } } while (0)
; #define PG8_LDA(dst, b, h) do { _Pragma("unroll") for (int m = 0; m < 4; ++m) _Pragma("unroll") for (int k = 0; k < 2; ++k) dst[m][k] = *(const PG8_LAS bf16x8*)(lds + PG8_SA(b, h) + aoff + m * 2048 + k * 1024); } while (0)
; #define PG8_LDB(dst, b, h) do { _Pragma("unroll") for (int n = 0; n < 2; ++n) _Pragma("unroll") for (int k = 0; k < 2; ++k) dst[n][k] = *(const PG8_LAS bf16x8*)(lds + PG8_SB(b, h) + boff + n * 2048 + k * 1024); } while (0)
; #define PG8_MMA(ai, bj, At, Bt) do { __builtin_amdgcn_s_setprio(1); _Pragma("unroll") for (int m = 0; m < 4; ++m) _Pragma("unroll") for (int n = 0; n < 2; ++n) _Pragma("unroll") for (int k = 0; k < 2; ++k) \
;         acc[ai][bj][m][n] = __builtin_amdgcn_mfma_f32_16x16x32_bf16(Bt[n][k], At[m][k], acc[ai][bj][m][n], 0, 0, 0); __builtin_amdgcn_s_setprio(0); } while (0)
; #define PG8_WAIT_V(n) asm volatile("s_waitcnt vmcnt(" #n ")" ::: "memory")
; #define PG8_WAIT_L(n) asm volatile("s_waitcnt lgkmcnt(" #n ")" ::: "memory")
; #define PG8_BAR __builtin_amdgcn_s_barrier()
; #define PG8_SCHED __builtin_amdgcn_sched_barrier(0)
; template <class Epi, class Sched, bool ALIGN_EPI = false, bool SP2 = false>
; __device__ __forceinline__ void gemm_phase(PG8_LAS unsigned char* lds, const Gemm g, const Sched& S, const Epi& E) {
;     ...
;             PG8_WAIT_V(8); PG8_WAIT_L(0); PG8_BAR; PG8_MMA(1, 0, At, B0); PG8_MMA(1, 1, At, B1); PG8_BAR; PG8_SCHED;
;             PG8_LDB(B0, 1, 0); PG8_LDB(B1, 1, 1); PG8_SCHED; PG8_LDA(At, 1, 0); PG8_STAGE(PG8_SA(0, 1), a2 + hstepA, voffA);
	s_setprio 1
	s_waitcnt lgkmcnt(7)
	v_mfma_f32_16x16x32_bf16 v[60:63], v[128:131], v[202:205], v[60:63]
	v_mfma_f32_16x16x32_bf16 v[56:59], v[162:165], v[202:205], v[56:59]
	s_waitcnt lgkmcnt(5)
	v_mfma_f32_16x16x32_bf16 v[44:47], v[128:131], v[210:213], v[44:47]
	v_mfma_f32_16x16x32_bf16 v[40:43], v[162:165], v[210:213], v[40:43]
	s_waitcnt lgkmcnt(3)
	v_mfma_f32_16x16x32_bf16 v[28:31], v[128:131], v[218:221], v[28:31]
	v_mfma_f32_16x16x32_bf16 v[24:27], v[162:165], v[218:221], v[24:27]
	s_waitcnt lgkmcnt(1)
	v_mfma_f32_16x16x32_bf16 v[12:15], v[128:131], v[226:229], v[12:15]
	v_mfma_f32_16x16x32_bf16 v[8:11], v[162:165], v[226:229], v[8:11]
	v_mfma_f32_16x16x32_bf16 v[60:63], v[132:135], v[206:209], v[60:63]
	v_mfma_f32_16x16x32_bf16 v[56:59], v[166:169], v[206:209], v[56:59]
	v_mfma_f32_16x16x32_bf16 v[44:47], v[132:135], v[214:217], v[44:47]
	v_mfma_f32_16x16x32_bf16 v[40:43], v[166:169], v[214:217], v[40:43]
	v_mfma_f32_16x16x32_bf16 v[28:31], v[132:135], v[222:225], v[28:31]
	v_mfma_f32_16x16x32_bf16 v[24:27], v[166:169], v[222:225], v[24:27]
	s_waitcnt lgkmcnt(0)
	v_mfma_f32_16x16x32_bf16 v[12:15], v[132:135], v[230:233], v[12:15]
	v_mfma_f32_16x16x32_bf16 v[8:11], v[166:169], v[230:233], v[8:11]
	s_setprio 0
	s_setprio 1
	v_mfma_f32_16x16x32_bf16 v[52:55], v[182:185], v[202:205], v[52:55]
	v_mfma_f32_16x16x32_bf16 v[48:51], v[190:193], v[202:205], v[48:51]
	v_mfma_f32_16x16x32_bf16 v[36:39], v[182:185], v[210:213], v[36:39]
	v_mfma_f32_16x16x32_bf16 v[32:35], v[190:193], v[210:213], v[32:35]
	v_mfma_f32_16x16x32_bf16 v[20:23], v[182:185], v[218:221], v[20:23]
	v_mfma_f32_16x16x32_bf16 v[16:19], v[190:193], v[218:221], v[16:19]
	v_mfma_f32_16x16x32_bf16 v[4:7], v[182:185], v[226:229], v[4:7]
	v_mfma_f32_16x16x32_bf16 v[0:3], v[190:193], v[226:229], v[0:3]
	v_mfma_f32_16x16x32_bf16 v[52:55], v[186:189], v[206:209], v[52:55]
	v_mfma_f32_16x16x32_bf16 v[48:51], v[194:197], v[206:209], v[48:51]
	v_mfma_f32_16x16x32_bf16 v[36:39], v[186:189], v[214:217], v[36:39]
	v_mfma_f32_16x16x32_bf16 v[32:35], v[194:197], v[214:217], v[32:35]
	v_mfma_f32_16x16x32_bf16 v[20:23], v[186:189], v[222:225], v[20:23]
	v_mfma_f32_16x16x32_bf16 v[16:19], v[194:197], v[222:225], v[16:19]
	v_mfma_f32_16x16x32_bf16 v[4:7], v[186:189], v[230:233], v[4:7]
	v_mfma_f32_16x16x32_bf16 v[0:3], v[194:197], v[230:233], v[0:3]
	s_setprio 0
	s_barrier
	ds_read_b128 v[128:131], v178
	ds_read_b128 v[132:135], v178 offset:1024
	ds_read_b128 v[162:165], v178 offset:2048
	ds_read_b128 v[166:169], v178 offset:3072
	ds_read_b128 v[182:185], v179
	ds_read_b128 v[186:189], v179 offset:1024
	ds_read_b128 v[190:193], v179 offset:2048
	ds_read_b128 v[194:197], v179 offset:3072
	ds_read_b128 v[202:205], v177 offset:32768
	ds_read_b128 v[206:209], v177 offset:33792
	ds_read_b128 v[210:213], v177 offset:34816
	ds_read_b128 v[214:217], v177 offset:35840
	ds_read_b128 v[218:221], v177 offset:36864
	ds_read_b128 v[222:225], v177 offset:37888
	ds_read_b128 v[226:229], v177 offset:38912
	ds_read_b128 v[230:233], v177 offset:39936
	s_mov_b32 m0, s53
	s_nop 0
	global_load_lds_dwordx4 v139, s[48:49]
	s_nop 0
	s_mov_b32 m0, s58
	s_nop 0
	global_load_lds_dwordx4 v173, s[48:49]
	s_nop 0
	s_add_u32 s48, s48, 0x10000
	s_addc_u32 s49, s49, 0
	s_mov_b32 m0, s59
	s_nop 0
	global_load_lds_dwordx4 v139, s[48:49]
	s_nop 0
	s_mov_b32 m0, s60
	s_nop 0
	global_load_lds_dwordx4 v173, s[48:49]
	s_waitcnt vmcnt(8)
	s_waitcnt lgkmcnt(0)
	s_barrier
; #define PG8_STAGE(bufoff, gbase, voff) do { const unsigned long long gb_ = (unsigned long long)(gbase); _Pragma("unroll") for (int _i = 0; _i < 2; ++_i) { unsigned keep_; \
;         asm volatile("s_mov_b32 m0, %2\n\ts_nop 0\n\tglobal_load_lds_dwordx4 %0, %1" : : "v"((voff)[_i]), "s"(gb_), "s"((unsigned)(size_t)(lds + (bufoff) + ldsw + _i * 8192)) : "memory", "m0"); (void)keep_; } } while (0)
; #define PG8_LDA(dst, b, h) do { _Pragma("unroll") for (int m = 0; m < 4; ++m) _Pragma("unroll") for (int k = 0; k < 2; ++k) dst[m][k] = *(const PG8_LAS bf16x8*)(lds + PG8_SA(b, h) + aoff + m * 2048 + k * 1024); } while (0)
; #define PG8_MMA(ai, bj, At, Bt) do { __builtin_amdgcn_s_setprio(1); _Pragma("unroll") for (int m = 0; m < 4; ++m) _Pragma("unroll") for (int n = 0; n < 2; ++n) _Pragma("unroll") for (int k = 0; k < 2; ++k) \
;         acc[ai][bj][m][n] = __builtin_amdgcn_mfma_f32_16x16x32_bf16(Bt[n][k], At[m][k], acc[ai][bj][m][n], 0, 0, 0); __builtin_amdgcn_s_setprio(0); } while (0)
; #define PG8_WAIT_V(n) asm volatile("s_waitcnt vmcnt(" #n ")" ::: "memory")
; #define PG8_WAIT_L(n) asm volatile("s_waitcnt lgkmcnt(" #n ")" ::: "memory")
; #define PG8_BAR __builtin_amdgcn_s_barrier()
; #define PG8_SCHED __builtin_amdgcn_sched_barrier(0)
; template <class Epi, class Sched, bool ALIGN_EPI = false, bool SP2 = false>
; __device__ __forceinline__ void gemm_phase(PG8_LAS unsigned char* lds, const Gemm g, const Sched& S, const Epi& E) {
;     ...
;             PG8_WAIT_V(8); PG8_WAIT_L(0); PG8_BAR; PG8_MMA(0, 0, At, B0); PG8_MMA(0, 1, At, B1); PG8_BAR; PG8_SCHED;
;             PG8_LDA(At, 1, 1); PG8_STAGE(PG8_SB(1, 0), b3, voffB); PG8_STAGE(PG8_SB(1, 1), b3 + hstepB, voffB); PG8_STAGE(PG8_SA(1, 0), a3, voffA);
;             PG8_WAIT_V(8); PG8_WAIT_L(0); PG8_BAR; PG8_MMA(1, 0, At, B0); PG8_MMA(1, 1, At, B1); PG8_BAR; PG8_SCHED;
	s_setprio 1
	s_waitcnt lgkmcnt(7)
	v_mfma_f32_16x16x32_bf16 v[124:127], v[128:131], v[202:205], v[124:127]
	v_mfma_f32_16x16x32_bf16 v[120:123], v[162:165], v[202:205], v[120:123]
	s_waitcnt lgkmcnt(5)
	v_mfma_f32_16x16x32_bf16 v[108:111], v[128:131], v[210:213], v[108:111]
	v_mfma_f32_16x16x32_bf16 v[104:107], v[162:165], v[210:213], v[104:107]
	s_waitcnt lgkmcnt(3)
	v_mfma_f32_16x16x32_bf16 v[92:95], v[128:131], v[218:221], v[92:95]
	v_mfma_f32_16x16x32_bf16 v[88:91], v[162:165], v[218:221], v[88:91]
	s_waitcnt lgkmcnt(1)
	v_mfma_f32_16x16x32_bf16 v[76:79], v[128:131], v[226:229], v[76:79]
	v_mfma_f32_16x16x32_bf16 v[72:75], v[162:165], v[226:229], v[72:75]
	v_mfma_f32_16x16x32_bf16 v[124:127], v[132:135], v[206:209], v[124:127]
	v_mfma_f32_16x16x32_bf16 v[120:123], v[166:169], v[206:209], v[120:123]
	v_mfma_f32_16x16x32_bf16 v[108:111], v[132:135], v[214:217], v[108:111]
	v_mfma_f32_16x16x32_bf16 v[104:107], v[166:169], v[214:217], v[104:107]
	v_mfma_f32_16x16x32_bf16 v[92:95], v[132:135], v[222:225], v[92:95]
	v_mfma_f32_16x16x32_bf16 v[88:91], v[166:169], v[222:225], v[88:91]
	s_waitcnt lgkmcnt(0)
	v_mfma_f32_16x16x32_bf16 v[76:79], v[132:135], v[230:233], v[76:79]
	v_mfma_f32_16x16x32_bf16 v[72:75], v[166:169], v[230:233], v[72:75]
	s_setprio 0
	s_setprio 1
	v_mfma_f32_16x16x32_bf16 v[116:119], v[182:185], v[202:205], v[116:119]
	v_mfma_f32_16x16x32_bf16 v[112:115], v[190:193], v[202:205], v[112:115]
	v_mfma_f32_16x16x32_bf16 v[100:103], v[182:185], v[210:213], v[100:103]
	v_mfma_f32_16x16x32_bf16 v[96:99], v[190:193], v[210:213], v[96:99]
	v_mfma_f32_16x16x32_bf16 v[84:87], v[182:185], v[218:221], v[84:87]
	v_mfma_f32_16x16x32_bf16 v[80:83], v[190:193], v[218:221], v[80:83]
	v_mfma_f32_16x16x32_bf16 v[68:71], v[182:185], v[226:229], v[68:71]
	v_mfma_f32_16x16x32_bf16 v[64:67], v[190:193], v[226:229], v[64:67]
	v_mfma_f32_16x16x32_bf16 v[116:119], v[186:189], v[206:209], v[116:119]
	v_mfma_f32_16x16x32_bf16 v[112:115], v[194:197], v[206:209], v[112:115]
	v_mfma_f32_16x16x32_bf16 v[100:103], v[186:189], v[214:217], v[100:103]
	v_mfma_f32_16x16x32_bf16 v[96:99], v[194:197], v[214:217], v[96:99]
	v_mfma_f32_16x16x32_bf16 v[84:87], v[186:189], v[222:225], v[84:87]
	v_mfma_f32_16x16x32_bf16 v[80:83], v[194:197], v[222:225], v[80:83]
	v_mfma_f32_16x16x32_bf16 v[68:71], v[186:189], v[230:233], v[68:71]
	v_mfma_f32_16x16x32_bf16 v[64:67], v[194:197], v[230:233], v[64:67]
	s_setprio 0
	s_barrier
	ds_read_b128 v[202:205], v177 offset:49152
	ds_read_b128 v[206:209], v177 offset:50176
	ds_read_b128 v[210:213], v177 offset:51200
	ds_read_b128 v[214:217], v177 offset:52224
	ds_read_b128 v[218:221], v177 offset:53248
	ds_read_b128 v[222:225], v177 offset:54272
	ds_read_b128 v[226:229], v177 offset:55296
	ds_read_b128 v[230:233], v177 offset:56320
	s_add_u32 s48, s46, 0x80
	s_addc_u32 s49, s47, 0
	s_mov_b32 m0, s62
	s_nop 0
	global_load_lds_dwordx4 v172, s[48:49]
	s_add_u32 s46, s46, 0x80080
	s_mov_b32 m0, s63
	s_nop 0
	global_load_lds_dwordx4 v174, s[48:49]
	s_addc_u32 s47, s47, 0
	s_mov_b32 m0, s66
	s_nop 0
	global_load_lds_dwordx4 v172, s[46:47]
	s_nop 0
	s_mov_b32 m0, s67
	s_nop 0
	global_load_lds_dwordx4 v174, s[46:47]
	s_nop 0
	s_nop 0
	s_waitcnt vmcnt(6)
	s_waitcnt lgkmcnt(0)
	s_barrier
	s_setprio 1
	s_waitcnt lgkmcnt(7)
	v_mfma_f32_16x16x32_bf16 v[60:63], v[128:131], v[202:205], v[60:63]
	v_mfma_f32_16x16x32_bf16 v[56:59], v[162:165], v[202:205], v[56:59]
	s_waitcnt lgkmcnt(5)
	v_mfma_f32_16x16x32_bf16 v[44:47], v[128:131], v[210:213], v[44:47]
	v_mfma_f32_16x16x32_bf16 v[40:43], v[162:165], v[210:213], v[40:43]
	s_waitcnt lgkmcnt(3)
	v_mfma_f32_16x16x32_bf16 v[28:31], v[128:131], v[218:221], v[28:31]
	v_mfma_f32_16x16x32_bf16 v[24:27], v[162:165], v[218:221], v[24:27]
	s_waitcnt lgkmcnt(1)
	v_mfma_f32_16x16x32_bf16 v[12:15], v[128:131], v[226:229], v[12:15]
	v_mfma_f32_16x16x32_bf16 v[8:11], v[162:165], v[226:229], v[8:11]
	v_mfma_f32_16x16x32_bf16 v[60:63], v[132:135], v[206:209], v[60:63]
	v_mfma_f32_16x16x32_bf16 v[56:59], v[166:169], v[206:209], v[56:59]
	v_mfma_f32_16x16x32_bf16 v[44:47], v[132:135], v[214:217], v[44:47]
	v_mfma_f32_16x16x32_bf16 v[40:43], v[166:169], v[214:217], v[40:43]
	v_mfma_f32_16x16x32_bf16 v[28:31], v[132:135], v[222:225], v[28:31]
	v_mfma_f32_16x16x32_bf16 v[24:27], v[166:169], v[222:225], v[24:27]
	s_waitcnt lgkmcnt(0)
	v_mfma_f32_16x16x32_bf16 v[12:15], v[132:135], v[230:233], v[12:15]
	v_mfma_f32_16x16x32_bf16 v[8:11], v[166:169], v[230:233], v[8:11]
	s_setprio 0
	s_setprio 1
	v_mfma_f32_16x16x32_bf16 v[52:55], v[182:185], v[202:205], v[52:55]
	v_mfma_f32_16x16x32_bf16 v[48:51], v[190:193], v[202:205], v[48:51]
	v_mfma_f32_16x16x32_bf16 v[36:39], v[182:185], v[210:213], v[36:39]
	v_mfma_f32_16x16x32_bf16 v[32:35], v[190:193], v[210:213], v[32:35]
	v_mfma_f32_16x16x32_bf16 v[20:23], v[182:185], v[218:221], v[20:23]
	v_mfma_f32_16x16x32_bf16 v[16:19], v[190:193], v[218:221], v[16:19]
	v_mfma_f32_16x16x32_bf16 v[4:7], v[182:185], v[226:229], v[4:7]
	v_mfma_f32_16x16x32_bf16 v[0:3], v[190:193], v[226:229], v[0:3]
	v_mfma_f32_16x16x32_bf16 v[52:55], v[186:189], v[206:209], v[52:55]
	v_mfma_f32_16x16x32_bf16 v[48:51], v[194:197], v[206:209], v[48:51]
	v_mfma_f32_16x16x32_bf16 v[36:39], v[186:189], v[214:217], v[36:39]
	v_mfma_f32_16x16x32_bf16 v[32:35], v[194:197], v[214:217], v[32:35]
	v_mfma_f32_16x16x32_bf16 v[20:23], v[186:189], v[222:225], v[20:23]
	v_mfma_f32_16x16x32_bf16 v[16:19], v[194:197], v[222:225], v[16:19]
	v_mfma_f32_16x16x32_bf16 v[4:7], v[186:189], v[230:233], v[4:7]
	v_mfma_f32_16x16x32_bf16 v[0:3], v[194:197], v[230:233], v[0:3]
	s_setprio 0
	s_barrier
	s_add_i32 s76, s76, 2
	s_add_i32 s77, s77, 0x10000
	s_cmp_gt_u32 s76, 29
	s_mov_b64 s[42:43], s[44:45]
	s_cbranch_scc0 .LBB0_1235
	s_and_b64 vcc, exec, s[28:29]
	s_cbranch_vccz .LBB0_1238
	s_barrier

; #define PG8_STAGE(bufoff, gbase, voff) do { const unsigned long long gb_ = (unsigned long long)(gbase); _Pragma("unroll") for (int _i = 0; _i < 2; ++_i) { unsigned keep_; \
;         asm volatile("s_mov_b32 m0, %2\n\ts_nop 0\n\tglobal_load_lds_dwordx4 %0, %1" : : "v"((voff)[_i]), "s"(gb_), "s"((unsigned)(size_t)(lds + (bufoff) + ldsw + _i * 8192)) : "memory", "m0"); (void)keep_; } } while (0)
; #define PG8_LDA(dst, b, h) do { _Pragma("unroll") for (int m = 0; m < 4; ++m) _Pragma("unroll") for (int k = 0; k < 2; ++k) dst[m][k] = *(const PG8_LAS bf16x8*)(lds + PG8_SA(b, h) + aoff + m * 2048 + k * 1024); } while (0)
; #define PG8_LDB(dst, b, h) do { _Pragma("unroll") for (int n = 0; n < 2; ++n) _Pragma("unroll") for (int k = 0; k < 2; ++k) dst[n][k] = *(const PG8_LAS bf16x8*)(lds + PG8_SB(b, h) + boff + n * 2048 + k * 1024); } while (0)
; #define PG8_MMA(ai, bj, At, Bt) do { __builtin_amdgcn_s_setprio(1); _Pragma("unroll") for (int m = 0; m < 4; ++m) _Pragma("unroll") for (int n = 0; n < 2; ++n) _Pragma("unroll") for (int k = 0; k < 2; ++k) \
;         acc[ai][bj][m][n] = __builtin_amdgcn_mfma_f32_16x16x32_bf16(Bt[n][k], At[m][k], acc[ai][bj][m][n], 0, 0, 0); __builtin_amdgcn_s_setprio(0); } while (0)
; #define PG8_WAIT_V(n) asm volatile("s_waitcnt vmcnt(" #n ")" ::: "memory")
; #define PG8_BAR __builtin_amdgcn_s_barrier()
; template <class Epi, class Sched, bool ALIGN_EPI = false, bool SP2 = false>
; __device__ __forceinline__ void gemm_phase(PG8_LAS unsigned char* lds, const Gemm g, const Sched& S, const Epi& E) {
;     ...
;         for (int t = 0; t < nt; t += 2) {
;             const bool last = (t == nt - 2);
;     ...
;             const char* a1 = cA + PG8_KOFFA(t + 1);
;             const char* a2 = last ? nA : cA + PG8_KOFFA(t + 2); const char* b2 = last ? nB : cB + (size_t)(t + 2) * kstep;
;             const char* a3 = last ? nA + kstep : cA + PG8_KOFFA(t + 3); const char* b3 = b2 + kstep;
;     ...
;             if (last && has_next) S.a_ready(nxt);
;             if constexpr (SP2) {
;             PG8_LDB(B0, 0, 0); PG8_LDB(B1, 0, 1); PG8_SCHED; PG8_LDA(At, 0, 0); PG8_STAGE(PG8_SA(1, 1), a1 + hstepA, voffA);
;             PG8_WAIT_V(8); PG8_WAIT_L(0); PG8_BAR; PG8_MMA(0, 0, At, B0); PG8_MMA(0, 1, At, B1); PG8_BAR; PG8_SCHED;
;             PG8_LDA(At, 0, 1); PG8_STAGE(PG8_SB(0, 0), b2, voffB); PG8_STAGE(PG8_SB(0, 1), b2 + hstepB, voffB); PG8_STAGE(PG8_SA(0, 0), a2, voffA);
.LBB0_1380:
	s_add_i32 s37, s71, 0xfffe8000
	s_and_b32 s36, s34, 0x100
	s_and_b32 s37, s37, 0xe0000
	s_or_b32 s36, s36, s37
	s_add_u32 s72, s8, s36
	s_addc_u32 s73, s9, 0
	s_add_u32 s36, s34, 0x100
	s_addc_u32 s37, s35, 0
	s_add_i32 s39, s71, 0xffff8000
	s_and_b32 s38, s36, 0x100
	s_and_b32 s39, s39, 0x1e0000
	s_or_b32 s38, s39, s38
	ds_read_b128 v[154:157], v167
	ds_read_b128 v[178:181], v167 offset:1024
	ds_read_b128 v[182:185], v167 offset:2048
	ds_read_b128 v[186:189], v167 offset:3072
	ds_read_b128 v[190:193], v169
	ds_read_b128 v[194:197], v169 offset:1024
	ds_read_b128 v[202:205], v169 offset:2048
	ds_read_b128 v[206:209], v169 offset:3072
	s_add_u32 s38, s8, s38
	s_addc_u32 s39, s9, 0
	s_add_u32 s76, s68, s34
	s_addc_u32 s35, s69, s35
	s_add_i32 s40, s34, 0x180
	s_and_b32 s40, s40, 0x180
	s_and_b32 s41, s71, 0x1e0000
	s_or_b32 s40, s41, s40
	s_add_u32 s77, s8, s40
	s_addc_u32 s78, s9, 0
	s_cmpk_eq_i32 s34, 0xf00
	s_cselect_b32 s41, s0, s39
	s_cselect_b32 s39, s21, s35
	s_cselect_b32 s35, s67, s78
	s_cselect_b32 s34, s29, s77
	s_cselect_b32 s40, s1, s38
	s_cselect_b32 s38, s23, s76
	ds_read_b128 v[210:213], v172
	ds_read_b128 v[214:217], v172 offset:1024
	ds_read_b128 v[218:221], v172 offset:2048
	ds_read_b128 v[222:225], v172 offset:3072
	ds_read_b128 v[226:229], v172 offset:4096
	ds_read_b128 v[230:233], v172 offset:5120
	ds_read_b128 v[234:237], v172 offset:6144
	ds_read_b128 v[238:241], v172 offset:7168
	s_add_u32 s72, s72, 0x10080
	s_addc_u32 s73, s73, 0
	s_sub_u32 s98, s72, 0x10000
	s_subb_u32 s99, s73, 0
	s_mov_b32 m0, s57
	s_nop 0
	global_load_lds_dwordx4 v159, s[98:99]
	s_nop 0
	s_mov_b32 m0, s58
	s_nop 0
	global_load_lds_dwordx4 v163, s[98:99]
	s_nop 0
	s_mov_b32 m0, s61
	s_nop 0
	global_load_lds_dwordx4 v159, s[72:73]
	s_nop 0
	s_mov_b32 m0, s62
	s_nop 0
	global_load_lds_dwordx4 v163, s[72:73]
	s_waitcnt vmcnt(8)
	s_waitcnt lgkmcnt(0)
	s_barrier
	s_setprio 1
	s_waitcnt lgkmcnt(7)
	v_mfma_f32_16x16x32_bf16 v[124:127], v[154:157], v[210:213], v[124:127]
	v_mfma_f32_16x16x32_bf16 v[116:119], v[182:185], v[210:213], v[116:119]
	s_waitcnt lgkmcnt(5)
	v_mfma_f32_16x16x32_bf16 v[108:111], v[154:157], v[218:221], v[108:111]
	v_mfma_f32_16x16x32_bf16 v[100:103], v[182:185], v[218:221], v[100:103]
	s_waitcnt lgkmcnt(3)
	v_mfma_f32_16x16x32_bf16 v[92:95], v[154:157], v[226:229], v[92:95]
	v_mfma_f32_16x16x32_bf16 v[84:87], v[182:185], v[226:229], v[84:87]
	s_waitcnt lgkmcnt(1)
	v_mfma_f32_16x16x32_bf16 v[76:79], v[154:157], v[234:237], v[76:79]
	v_mfma_f32_16x16x32_bf16 v[68:71], v[182:185], v[234:237], v[68:71]
	v_mfma_f32_16x16x32_bf16 v[124:127], v[178:181], v[214:217], v[124:127]
	v_mfma_f32_16x16x32_bf16 v[116:119], v[186:189], v[214:217], v[116:119]
	v_mfma_f32_16x16x32_bf16 v[108:111], v[178:181], v[222:225], v[108:111]
	v_mfma_f32_16x16x32_bf16 v[100:103], v[186:189], v[222:225], v[100:103]
	v_mfma_f32_16x16x32_bf16 v[92:95], v[178:181], v[230:233], v[92:95]
	v_mfma_f32_16x16x32_bf16 v[84:87], v[186:189], v[230:233], v[84:87]
	s_waitcnt lgkmcnt(0)
	v_mfma_f32_16x16x32_bf16 v[76:79], v[178:181], v[238:241], v[76:79]
	v_mfma_f32_16x16x32_bf16 v[68:71], v[186:189], v[238:241], v[68:71]
	s_setprio 0
	s_setprio 1
	v_mfma_f32_16x16x32_bf16 v[120:123], v[190:193], v[210:213], v[120:123]
	v_mfma_f32_16x16x32_bf16 v[112:115], v[202:205], v[210:213], v[112:115]
	v_mfma_f32_16x16x32_bf16 v[104:107], v[190:193], v[218:221], v[104:107]
	v_mfma_f32_16x16x32_bf16 v[96:99], v[202:205], v[218:221], v[96:99]
	v_mfma_f32_16x16x32_bf16 v[88:91], v[190:193], v[226:229], v[88:91]
	v_mfma_f32_16x16x32_bf16 v[80:83], v[202:205], v[226:229], v[80:83]
	v_mfma_f32_16x16x32_bf16 v[72:75], v[190:193], v[234:237], v[72:75]
	v_mfma_f32_16x16x32_bf16 v[64:67], v[202:205], v[234:237], v[64:67]
	v_mfma_f32_16x16x32_bf16 v[120:123], v[194:197], v[214:217], v[120:123]
	v_mfma_f32_16x16x32_bf16 v[112:115], v[206:209], v[214:217], v[112:115]
	v_mfma_f32_16x16x32_bf16 v[104:107], v[194:197], v[222:225], v[104:107]
	v_mfma_f32_16x16x32_bf16 v[96:99], v[206:209], v[222:225], v[96:99]
	v_mfma_f32_16x16x32_bf16 v[88:91], v[194:197], v[230:233], v[88:91]
	v_mfma_f32_16x16x32_bf16 v[80:83], v[206:209], v[230:233], v[80:83]
	v_mfma_f32_16x16x32_bf16 v[72:75], v[194:197], v[238:241], v[72:75]
	v_mfma_f32_16x16x32_bf16 v[64:67], v[206:209], v[238:241], v[64:67]
	s_setprio 0
	s_barrier
	ds_read_b128 v[210:213], v172 offset:16384
	ds_read_b128 v[214:217], v172 offset:17408
	ds_read_b128 v[218:221], v172 offset:18432
	ds_read_b128 v[222:225], v172 offset:19456
	ds_read_b128 v[226:229], v172 offset:20480
	ds_read_b128 v[230:233], v172 offset:21504
	ds_read_b128 v[234:237], v172 offset:22528
	ds_read_b128 v[238:241], v172 offset:23552
	s_mov_b32 m0, s45
	s_nop 0
	global_load_lds_dwordx4 v161, s[38:39]
	s_add_u32 s72, s38, 0x80000
	s_mov_b32 m0, s46
	s_nop 0
	global_load_lds_dwordx4 v165, s[38:39]
	s_addc_u32 s73, s39, 0
	s_mov_b32 m0, s47
	s_nop 0
	global_load_lds_dwordx4 v161, s[72:73]
	s_nop 0
	s_mov_b32 m0, s48
	s_nop 0
	global_load_lds_dwordx4 v165, s[72:73]
	s_nop 0
	s_nop 0
	s_waitcnt vmcnt(6)
	s_waitcnt lgkmcnt(0)
	s_barrier
; #define PG8_STAGE(bufoff, gbase, voff) do { const unsigned long long gb_ = (unsigned long long)(gbase); _Pragma("unroll") for (int _i = 0; _i < 2; ++_i) { unsigned keep_; \
;         asm volatile("s_mov_b32 m0, %2\n\ts_nop 0\n\tglobal_load_lds_dwordx4 %0, %1" : : "v"((voff)[_i]), "s"(gb_), "s"((unsigned)(size_t)(lds + (bufoff) + ldsw + _i * 8192)) : "memory", "m0"); (void)keep_; } } while (0)
; #define PG8_LDA(dst, b, h) do { _Pragma("unroll") for (int m = 0; m < 4; ++m) _Pragma("unroll") for (int k = 0; k < 2; ++k) dst[m][k] = *(const PG8_LAS bf16x8*)(lds + PG8_SA(b, h) + aoff + m * 2048 + k * 1024); } while (0)
; #define PG8_LDB(dst, b, h) do { _Pragma("unroll") for (int n = 0; n < 2; ++n) _Pragma("unroll") for (int k = 0; k < 2; ++k) dst[n][k] = *(const PG8_LAS bf16x8*)(lds + PG8_SB(b, h) + boff + n * 2048 + k * 1024); } while (0)
; #define PG8_MMA(ai, bj, At, Bt) do { __builtin_amdgcn_s_setprio(1); _Pragma("unroll") for (int m = 0; m < 4; ++m) _Pragma("unroll") for (int n = 0; n < 2; ++n) _Pragma("unroll") for (int k = 0; k < 2; ++k) \
;         acc[ai][bj][m][n] = __builtin_amdgcn_mfma_f32_16x16x32_bf16(Bt[n][k], At[m][k], acc[ai][bj][m][n], 0, 0, 0); __builtin_amdgcn_s_setprio(0); } while (0)
; #define PG8_WAIT_V(n) asm volatile("s_waitcnt vmcnt(" #n ")" ::: "memory")
; #define PG8_WAIT_L(n) asm volatile("s_waitcnt lgkmcnt(" #n ")" ::: "memory")
; #define PG8_BAR __builtin_amdgcn_s_barrier()
; #define PG8_SCHED __builtin_amdgcn_sched_barrier(0)
; template <class Epi, class Sched, bool ALIGN_EPI = false, bool SP2 = false>
; __device__ __forceinline__ void gemm_phase(PG8_LAS unsigned char* lds, const Gemm g, const Sched& S, const Epi& E) {
;     ...
;             PG8_WAIT_V(8); PG8_WAIT_L(0); PG8_BAR; PG8_MMA(1, 0, At, B0); PG8_MMA(1, 1, At, B1); PG8_BAR; PG8_SCHED;
;             PG8_LDB(B0, 1, 0); PG8_LDB(B1, 1, 1); PG8_SCHED; PG8_LDA(At, 1, 0); PG8_STAGE(PG8_SA(0, 1), a2 + hstepA, voffA);
	s_setprio 1
	s_waitcnt lgkmcnt(7)
	v_mfma_f32_16x16x32_bf16 v[60:63], v[154:157], v[210:213], v[60:63]
	v_mfma_f32_16x16x32_bf16 v[52:55], v[182:185], v[210:213], v[52:55]
	s_waitcnt lgkmcnt(5)
	v_mfma_f32_16x16x32_bf16 v[44:47], v[154:157], v[218:221], v[44:47]
	v_mfma_f32_16x16x32_bf16 v[36:39], v[182:185], v[218:221], v[36:39]
	s_waitcnt lgkmcnt(3)
	v_mfma_f32_16x16x32_bf16 v[28:31], v[154:157], v[226:229], v[28:31]
	v_mfma_f32_16x16x32_bf16 v[20:23], v[182:185], v[226:229], v[20:23]
	s_waitcnt lgkmcnt(1)
	v_mfma_f32_16x16x32_bf16 v[12:15], v[154:157], v[234:237], v[12:15]
	v_mfma_f32_16x16x32_bf16 v[4:7], v[182:185], v[234:237], v[4:7]
	v_mfma_f32_16x16x32_bf16 v[60:63], v[178:181], v[214:217], v[60:63]
	v_mfma_f32_16x16x32_bf16 v[52:55], v[186:189], v[214:217], v[52:55]
	v_mfma_f32_16x16x32_bf16 v[44:47], v[178:181], v[222:225], v[44:47]
	v_mfma_f32_16x16x32_bf16 v[36:39], v[186:189], v[222:225], v[36:39]
	v_mfma_f32_16x16x32_bf16 v[28:31], v[178:181], v[230:233], v[28:31]
	v_mfma_f32_16x16x32_bf16 v[20:23], v[186:189], v[230:233], v[20:23]
	s_waitcnt lgkmcnt(0)
	v_mfma_f32_16x16x32_bf16 v[12:15], v[178:181], v[238:241], v[12:15]
	v_mfma_f32_16x16x32_bf16 v[4:7], v[186:189], v[238:241], v[4:7]
	s_setprio 0
	s_setprio 1
	v_mfma_f32_16x16x32_bf16 v[56:59], v[190:193], v[210:213], v[56:59]
	v_mfma_f32_16x16x32_bf16 v[48:51], v[202:205], v[210:213], v[48:51]
	v_mfma_f32_16x16x32_bf16 v[40:43], v[190:193], v[218:221], v[40:43]
	v_mfma_f32_16x16x32_bf16 v[32:35], v[202:205], v[218:221], v[32:35]
	v_mfma_f32_16x16x32_bf16 v[24:27], v[190:193], v[226:229], v[24:27]
	v_mfma_f32_16x16x32_bf16 v[16:19], v[202:205], v[226:229], v[16:19]
	v_mfma_f32_16x16x32_bf16 v[8:11], v[190:193], v[234:237], v[8:11]
	v_mfma_f32_16x16x32_bf16 v[0:3], v[202:205], v[234:237], v[0:3]
	v_mfma_f32_16x16x32_bf16 v[56:59], v[194:197], v[214:217], v[56:59]
	v_mfma_f32_16x16x32_bf16 v[48:51], v[206:209], v[214:217], v[48:51]
	v_mfma_f32_16x16x32_bf16 v[40:43], v[194:197], v[222:225], v[40:43]
	v_mfma_f32_16x16x32_bf16 v[32:35], v[206:209], v[222:225], v[32:35]
	v_mfma_f32_16x16x32_bf16 v[24:27], v[194:197], v[230:233], v[24:27]
	v_mfma_f32_16x16x32_bf16 v[16:19], v[206:209], v[230:233], v[16:19]
	v_mfma_f32_16x16x32_bf16 v[8:11], v[194:197], v[238:241], v[8:11]
	v_mfma_f32_16x16x32_bf16 v[0:3], v[206:209], v[238:241], v[0:3]
	s_setprio 0
	s_barrier
	ds_read_b128 v[154:157], v173
	ds_read_b128 v[178:181], v173 offset:1024
	ds_read_b128 v[182:185], v173 offset:2048
	ds_read_b128 v[186:189], v173 offset:3072
	ds_read_b128 v[190:193], v174
	ds_read_b128 v[194:197], v174 offset:1024
	ds_read_b128 v[202:205], v174 offset:2048
	ds_read_b128 v[206:209], v174 offset:3072
	ds_read_b128 v[210:213], v172 offset:32768
	ds_read_b128 v[214:217], v172 offset:33792
	ds_read_b128 v[218:221], v172 offset:34816
	ds_read_b128 v[222:225], v172 offset:35840
	ds_read_b128 v[226:229], v172 offset:36864
	ds_read_b128 v[230:233], v172 offset:37888
	ds_read_b128 v[234:237], v172 offset:38912
	ds_read_b128 v[238:241], v172 offset:39936
	s_mov_b32 m0, s31
	s_nop 0
	global_load_lds_dwordx4 v159, s[40:41]
	s_nop 0
	s_mov_b32 m0, s49
	s_nop 0
	global_load_lds_dwordx4 v163, s[40:41]
	s_nop 0
	s_add_u32 s40, s40, 0x10000
	s_addc_u32 s41, s41, 0
	s_mov_b32 m0, s50
	s_nop 0
	global_load_lds_dwordx4 v159, s[40:41]
	s_nop 0
	s_mov_b32 m0, s51
	s_nop 0
	global_load_lds_dwordx4 v163, s[40:41]
	s_waitcnt vmcnt(8)
	s_waitcnt lgkmcnt(0)
	s_barrier
; #define PG8_STAGE(bufoff, gbase, voff) do { const unsigned long long gb_ = (unsigned long long)(gbase); _Pragma("unroll") for (int _i = 0; _i < 2; ++_i) { unsigned keep_; \
;         asm volatile("s_mov_b32 m0, %2\n\ts_nop 0\n\tglobal_load_lds_dwordx4 %0, %1" : : "v"((voff)[_i]), "s"(gb_), "s"((unsigned)(size_t)(lds + (bufoff) + ldsw + _i * 8192)) : "memory", "m0"); (void)keep_; } } while (0)
; #define PG8_LDA(dst, b, h) do { _Pragma("unroll") for (int m = 0; m < 4; ++m) _Pragma("unroll") for (int k = 0; k < 2; ++k) dst[m][k] = *(const PG8_LAS bf16x8*)(lds + PG8_SA(b, h) + aoff + m * 2048 + k * 1024); } while (0)
; #define PG8_MMA(ai, bj, At, Bt) do { __builtin_amdgcn_s_setprio(1); _Pragma("unroll") for (int m = 0; m < 4; ++m) _Pragma("unroll") for (int n = 0; n < 2; ++n) _Pragma("unroll") for (int k = 0; k < 2; ++k) \
;         acc[ai][bj][m][n] = __builtin_amdgcn_mfma_f32_16x16x32_bf16(Bt[n][k], At[m][k], acc[ai][bj][m][n], 0, 0, 0); __builtin_amdgcn_s_setprio(0); } while (0)
; #define PG8_WAIT_V(n) asm volatile("s_waitcnt vmcnt(" #n ")" ::: "memory")
; #define PG8_WAIT_L(n) asm volatile("s_waitcnt lgkmcnt(" #n ")" ::: "memory")
; #define PG8_BAR __builtin_amdgcn_s_barrier()
; #define PG8_SCHED __builtin_amdgcn_sched_barrier(0)
; template <class Epi, class Sched, bool ALIGN_EPI = false, bool SP2 = false>
; __device__ __forceinline__ void gemm_phase(PG8_LAS unsigned char* lds, const Gemm g, const Sched& S, const Epi& E) {
;     ...
;             PG8_WAIT_V(8); PG8_WAIT_L(0); PG8_BAR; PG8_MMA(0, 0, At, B0); PG8_MMA(0, 1, At, B1); PG8_BAR; PG8_SCHED;
;             PG8_LDA(At, 1, 1); PG8_STAGE(PG8_SB(1, 0), b3, voffB); PG8_STAGE(PG8_SB(1, 1), b3 + hstepB, voffB); PG8_STAGE(PG8_SA(1, 0), a3, voffA);
;             PG8_WAIT_V(8); PG8_WAIT_L(0); PG8_BAR; PG8_MMA(1, 0, At, B0); PG8_MMA(1, 1, At, B1); PG8_BAR; PG8_SCHED;
	s_setprio 1
	s_waitcnt lgkmcnt(7)
	v_mfma_f32_16x16x32_bf16 v[124:127], v[154:157], v[210:213], v[124:127]
	v_mfma_f32_16x16x32_bf16 v[116:119], v[182:185], v[210:213], v[116:119]
	s_waitcnt lgkmcnt(5)
	v_mfma_f32_16x16x32_bf16 v[108:111], v[154:157], v[218:221], v[108:111]
	v_mfma_f32_16x16x32_bf16 v[100:103], v[182:185], v[218:221], v[100:103]
	s_waitcnt lgkmcnt(3)
	v_mfma_f32_16x16x32_bf16 v[92:95], v[154:157], v[226:229], v[92:95]
	v_mfma_f32_16x16x32_bf16 v[84:87], v[182:185], v[226:229], v[84:87]
	s_waitcnt lgkmcnt(1)
	v_mfma_f32_16x16x32_bf16 v[76:79], v[154:157], v[234:237], v[76:79]
	v_mfma_f32_16x16x32_bf16 v[68:71], v[182:185], v[234:237], v[68:71]
	v_mfma_f32_16x16x32_bf16 v[124:127], v[178:181], v[214:217], v[124:127]
	v_mfma_f32_16x16x32_bf16 v[116:119], v[186:189], v[214:217], v[116:119]
	v_mfma_f32_16x16x32_bf16 v[108:111], v[178:181], v[222:225], v[108:111]
	v_mfma_f32_16x16x32_bf16 v[100:103], v[186:189], v[222:225], v[100:103]
	v_mfma_f32_16x16x32_bf16 v[92:95], v[178:181], v[230:233], v[92:95]
	v_mfma_f32_16x16x32_bf16 v[84:87], v[186:189], v[230:233], v[84:87]
	s_waitcnt lgkmcnt(0)
	v_mfma_f32_16x16x32_bf16 v[76:79], v[178:181], v[238:241], v[76:79]
	v_mfma_f32_16x16x32_bf16 v[68:71], v[186:189], v[238:241], v[68:71]
	s_setprio 0
	s_setprio 1
	v_mfma_f32_16x16x32_bf16 v[120:123], v[190:193], v[210:213], v[120:123]
	v_mfma_f32_16x16x32_bf16 v[112:115], v[202:205], v[210:213], v[112:115]
	v_mfma_f32_16x16x32_bf16 v[104:107], v[190:193], v[218:221], v[104:107]
	v_mfma_f32_16x16x32_bf16 v[96:99], v[202:205], v[218:221], v[96:99]
	v_mfma_f32_16x16x32_bf16 v[88:91], v[190:193], v[226:229], v[88:91]
	v_mfma_f32_16x16x32_bf16 v[80:83], v[202:205], v[226:229], v[80:83]
	v_mfma_f32_16x16x32_bf16 v[72:75], v[190:193], v[234:237], v[72:75]
	v_mfma_f32_16x16x32_bf16 v[64:67], v[202:205], v[234:237], v[64:67]
	v_mfma_f32_16x16x32_bf16 v[120:123], v[194:197], v[214:217], v[120:123]
	v_mfma_f32_16x16x32_bf16 v[112:115], v[206:209], v[214:217], v[112:115]
	v_mfma_f32_16x16x32_bf16 v[104:107], v[194:197], v[222:225], v[104:107]
	v_mfma_f32_16x16x32_bf16 v[96:99], v[206:209], v[222:225], v[96:99]
	v_mfma_f32_16x16x32_bf16 v[88:91], v[194:197], v[230:233], v[88:91]
	v_mfma_f32_16x16x32_bf16 v[80:83], v[206:209], v[230:233], v[80:83]
	v_mfma_f32_16x16x32_bf16 v[72:75], v[194:197], v[238:241], v[72:75]
	v_mfma_f32_16x16x32_bf16 v[64:67], v[206:209], v[238:241], v[64:67]
	s_setprio 0
	s_barrier
	ds_read_b128 v[210:213], v172 offset:49152
	ds_read_b128 v[214:217], v172 offset:50176
	ds_read_b128 v[218:221], v172 offset:51200
	ds_read_b128 v[222:225], v172 offset:52224
	ds_read_b128 v[226:229], v172 offset:53248
	ds_read_b128 v[230:233], v172 offset:54272
	ds_read_b128 v[234:237], v172 offset:55296
	ds_read_b128 v[238:241], v172 offset:56320
	s_add_u32 s40, s38, 0x80
	s_addc_u32 s41, s39, 0
	s_mov_b32 m0, s55
	s_nop 0
	global_load_lds_dwordx4 v161, s[40:41]
	s_add_u32 s38, s38, 0x80080
	s_mov_b32 m0, s56
	s_nop 0
	global_load_lds_dwordx4 v165, s[40:41]
	s_addc_u32 s39, s39, 0
	s_mov_b32 m0, s59
	s_nop 0
	global_load_lds_dwordx4 v161, s[38:39]
	s_nop 0
	s_mov_b32 m0, s60
	s_nop 0
	global_load_lds_dwordx4 v165, s[38:39]
	s_nop 0
	s_nop 0
	s_waitcnt vmcnt(6)
	s_waitcnt lgkmcnt(0)
	s_barrier
	s_setprio 1
	s_waitcnt lgkmcnt(7)
	v_mfma_f32_16x16x32_bf16 v[60:63], v[154:157], v[210:213], v[60:63]
	v_mfma_f32_16x16x32_bf16 v[52:55], v[182:185], v[210:213], v[52:55]
	s_waitcnt lgkmcnt(5)
	v_mfma_f32_16x16x32_bf16 v[44:47], v[154:157], v[218:221], v[44:47]
	v_mfma_f32_16x16x32_bf16 v[36:39], v[182:185], v[218:221], v[36:39]
	s_waitcnt lgkmcnt(3)
	v_mfma_f32_16x16x32_bf16 v[28:31], v[154:157], v[226:229], v[28:31]
	v_mfma_f32_16x16x32_bf16 v[20:23], v[182:185], v[226:229], v[20:23]
	s_waitcnt lgkmcnt(1)
	v_mfma_f32_16x16x32_bf16 v[12:15], v[154:157], v[234:237], v[12:15]
	v_mfma_f32_16x16x32_bf16 v[4:7], v[182:185], v[234:237], v[4:7]
	v_mfma_f32_16x16x32_bf16 v[60:63], v[178:181], v[214:217], v[60:63]
	v_mfma_f32_16x16x32_bf16 v[52:55], v[186:189], v[214:217], v[52:55]
	v_mfma_f32_16x16x32_bf16 v[44:47], v[178:181], v[222:225], v[44:47]
	v_mfma_f32_16x16x32_bf16 v[36:39], v[186:189], v[222:225], v[36:39]
	v_mfma_f32_16x16x32_bf16 v[28:31], v[178:181], v[230:233], v[28:31]
	v_mfma_f32_16x16x32_bf16 v[20:23], v[186:189], v[230:233], v[20:23]
	s_waitcnt lgkmcnt(0)
	v_mfma_f32_16x16x32_bf16 v[12:15], v[178:181], v[238:241], v[12:15]
	v_mfma_f32_16x16x32_bf16 v[4:7], v[186:189], v[238:241], v[4:7]
	s_setprio 0
	s_setprio 1
	v_mfma_f32_16x16x32_bf16 v[56:59], v[190:193], v[210:213], v[56:59]
	v_mfma_f32_16x16x32_bf16 v[48:51], v[202:205], v[210:213], v[48:51]
	v_mfma_f32_16x16x32_bf16 v[40:43], v[190:193], v[218:221], v[40:43]
	v_mfma_f32_16x16x32_bf16 v[32:35], v[202:205], v[218:221], v[32:35]
	v_mfma_f32_16x16x32_bf16 v[24:27], v[190:193], v[226:229], v[24:27]
	v_mfma_f32_16x16x32_bf16 v[16:19], v[202:205], v[226:229], v[16:19]
	v_mfma_f32_16x16x32_bf16 v[8:11], v[190:193], v[234:237], v[8:11]
	v_mfma_f32_16x16x32_bf16 v[0:3], v[202:205], v[234:237], v[0:3]
	v_mfma_f32_16x16x32_bf16 v[56:59], v[194:197], v[214:217], v[56:59]
	v_mfma_f32_16x16x32_bf16 v[48:51], v[206:209], v[214:217], v[48:51]
	v_mfma_f32_16x16x32_bf16 v[40:43], v[194:197], v[222:225], v[40:43]
	v_mfma_f32_16x16x32_bf16 v[32:35], v[206:209], v[222:225], v[32:35]
	v_mfma_f32_16x16x32_bf16 v[24:27], v[194:197], v[230:233], v[24:27]
	v_mfma_f32_16x16x32_bf16 v[16:19], v[206:209], v[230:233], v[16:19]
	v_mfma_f32_16x16x32_bf16 v[8:11], v[194:197], v[238:241], v[8:11]
	v_mfma_f32_16x16x32_bf16 v[0:3], v[206:209], v[238:241], v[0:3]
	s_setprio 0
	s_barrier
	s_add_i32 s70, s70, 2
	s_add_i32 s71, s71, 0x10000
	s_cmp_gt_u32 s70, 29
	s_mov_b64 s[34:35], s[36:37]
	s_cbranch_scc0 .LBB0_1380
	s_and_b64 vcc, exec, s[18:19]
	s_cbranch_vccz .LBB0_1383
	s_barrier

; #define PG8_STAGE(bufoff, gbase, voff) do { const unsigned long long gb_ = (unsigned long long)(gbase); _Pragma("unroll") for (int _i = 0; _i < 2; ++_i) { unsigned keep_; \
;         asm volatile("s_mov_b32 m0, %2\n\ts_nop 0\n\tglobal_load_lds_dwordx4 %0, %1" : : "v"((voff)[_i]), "s"(gb_), "s"((unsigned)(size_t)(lds + (bufoff) + ldsw + _i * 8192)) : "memory", "m0"); (void)keep_; } } while (0)
; #define PG8_LDA(dst, b, h) do { _Pragma("unroll") for (int m = 0; m < 4; ++m) _Pragma("unroll") for (int k = 0; k < 2; ++k) dst[m][k] = *(const PG8_LAS bf16x8*)(lds + PG8_SA(b, h) + aoff + m * 2048 + k * 1024); } while (0)
; #define PG8_LDB(dst, b, h) do { _Pragma("unroll") for (int n = 0; n < 2; ++n) _Pragma("unroll") for (int k = 0; k < 2; ++k) dst[n][k] = *(const PG8_LAS bf16x8*)(lds + PG8_SB(b, h) + boff + n * 2048 + k * 1024); } while (0)
; #define PG8_MMA(ai, bj, At, Bt) do { __builtin_amdgcn_s_setprio(1); _Pragma("unroll") for (int m = 0; m < 4; ++m) _Pragma("unroll") for (int n = 0; n < 2; ++n) _Pragma("unroll") for (int k = 0; k < 2; ++k) \
;         acc[ai][bj][m][n] = __builtin_amdgcn_mfma_f32_16x16x32_bf16(Bt[n][k], At[m][k], acc[ai][bj][m][n], 0, 0, 0); __builtin_amdgcn_s_setprio(0); } while (0)
; #define PG8_WAIT_V(n) asm volatile("s_waitcnt vmcnt(" #n ")" ::: "memory")
; #define PG8_BAR __builtin_amdgcn_s_barrier()
; template <class Epi, class Sched, bool ALIGN_EPI = false, bool SP2 = false>
; __device__ __forceinline__ void gemm_phase(PG8_LAS unsigned char* lds, const Gemm g, const Sched& S, const Epi& E) {
;     ...
;         for (int t = 0; t < nt; t += 2) {
;             const bool last = (t == nt - 2);
;     ...
;             const char* a1 = cA + PG8_KOFFA(t + 1);
;             const char* a2 = last ? nA : cA + PG8_KOFFA(t + 2); const char* b2 = last ? nB : cB + (size_t)(t + 2) * kstep;
;             const char* a3 = last ? nA + kstep : cA + PG8_KOFFA(t + 3); const char* b3 = b2 + kstep;
;     ...
;             if (last && has_next) S.a_ready(nxt);
;             if constexpr (SP2) {
;             PG8_LDB(B0, 0, 0); PG8_LDB(B1, 0, 1); PG8_SCHED; PG8_LDA(At, 0, 0); PG8_STAGE(PG8_SA(1, 1), a1 + hstepA, voffA);
;             PG8_WAIT_V(8); PG8_WAIT_L(0); PG8_BAR; PG8_MMA(0, 0, At, B0); PG8_MMA(0, 1, At, B1); PG8_BAR; PG8_SCHED;
;             PG8_LDA(At, 0, 1); PG8_STAGE(PG8_SB(0, 0), b2, voffB); PG8_STAGE(PG8_SB(0, 1), b2 + hstepB, voffB); PG8_STAGE(PG8_SA(0, 0), a2, voffA);
.LBB0_1630:
	s_add_i32 s78, s46, 2
	s_lshr_b32 s20, s78, 2
	s_lshl_b64 s[48:49], s[20:21], 17
	s_add_i32 s20, s44, 0xffffff00
	s_and_b32 s20, s20, 0x100
	s_add_u32 s47, s42, s48
	s_addc_u32 s48, s43, s49
	s_add_u32 s79, s47, s20
	s_addc_u32 s81, s48, 0
	s_add_i32 s20, s46, 4
	s_lshr_b32 s20, s20, 2
	s_lshl_b64 s[48:49], s[20:21], 17
	s_and_b32 s20, s44, 0x100
	s_add_u32 s47, s42, s48
	s_addc_u32 s48, s43, s49
	s_add_u32 s47, s47, s20
	s_addc_u32 s50, s48, 0
	s_add_u32 s80, s40, s44
	ds_read_b128 v[128:131], v173
	ds_read_b128 v[132:135], v173 offset:1024
	ds_read_b128 v[136:139], v173 offset:2048
	ds_read_b128 v[140:143], v173 offset:3072
	ds_read_b128 v[156:159], v174
	ds_read_b128 v[162:165], v174 offset:1024
	ds_read_b128 v[180:183], v174 offset:2048
	ds_read_b128 v[184:187], v174 offset:3072
	s_addc_u32 s82, s41, s45
	s_add_i32 s20, s46, 5
	s_lshr_b32 s20, s20, 2
	s_lshl_b64 s[48:49], s[20:21], 17
	s_add_i32 s20, s44, 0x80
	s_and_b32 s20, s20, 0x180
	s_add_u32 s48, s42, s48
	s_addc_u32 s49, s43, s49
	s_add_u32 s20, s48, s20
	s_addc_u32 s83, s49, 0
	s_cmp_eq_u32 s46, 28
	s_cselect_b32 s46, s31, s20
	s_cselect_b32 s51, s0, s50
	s_cselect_b32 s50, s1, s47
	s_cselect_b32 s49, s9, s82
	s_cselect_b32 s48, s29, s80
	s_cselect_b32 s47, s77, s83
	ds_read_b128 v[188:191], v175
	ds_read_b128 v[192:195], v175 offset:1024
	ds_read_b128 v[196:199], v175 offset:2048
	ds_read_b128 v[202:205], v175 offset:3072
	ds_read_b128 v[206:209], v175 offset:4096
	ds_read_b128 v[210:213], v175 offset:5120
	ds_read_b128 v[214:217], v175 offset:6144
	ds_read_b128 v[218:221], v175 offset:7168
	s_add_u32 s80, s79, 0x10080
	s_addc_u32 s81, s81, 0
	s_sub_u32 s98, s80, 0x10000
	s_subb_u32 s99, s81, 0
	s_mov_b32 m0, s64
	s_nop 0
	global_load_lds_dwordx4 v149, s[98:99]
	s_nop 0
	s_mov_b32 m0, s65
	s_nop 0
	global_load_lds_dwordx4 v167, s[98:99]
	s_nop 0
	s_mov_b32 m0, s68
	s_nop 0
	global_load_lds_dwordx4 v149, s[80:81]
	s_nop 0
	s_mov_b32 m0, s69
	s_nop 0
	global_load_lds_dwordx4 v167, s[80:81]
	s_waitcnt vmcnt(8)
	s_waitcnt lgkmcnt(0)
	s_barrier
	s_setprio 1
	s_waitcnt lgkmcnt(7)
	v_mfma_f32_16x16x32_bf16 v[124:127], v[128:131], v[188:191], v[124:127]
	v_mfma_f32_16x16x32_bf16 v[120:123], v[136:139], v[188:191], v[120:123]
	s_waitcnt lgkmcnt(5)
	v_mfma_f32_16x16x32_bf16 v[112:115], v[128:131], v[196:199], v[112:115]
	v_mfma_f32_16x16x32_bf16 v[104:107], v[136:139], v[196:199], v[104:107]
	s_waitcnt lgkmcnt(3)
	v_mfma_f32_16x16x32_bf16 v[96:99], v[128:131], v[206:209], v[96:99]
	v_mfma_f32_16x16x32_bf16 v[88:91], v[136:139], v[206:209], v[88:91]
	s_waitcnt lgkmcnt(1)
	v_mfma_f32_16x16x32_bf16 v[80:83], v[128:131], v[214:217], v[80:83]
	v_mfma_f32_16x16x32_bf16 v[72:75], v[136:139], v[214:217], v[72:75]
	v_mfma_f32_16x16x32_bf16 v[124:127], v[132:135], v[192:195], v[124:127]
	v_mfma_f32_16x16x32_bf16 v[120:123], v[140:143], v[192:195], v[120:123]
	v_mfma_f32_16x16x32_bf16 v[112:115], v[132:135], v[202:205], v[112:115]
	v_mfma_f32_16x16x32_bf16 v[104:107], v[140:143], v[202:205], v[104:107]
	v_mfma_f32_16x16x32_bf16 v[96:99], v[132:135], v[210:213], v[96:99]
	v_mfma_f32_16x16x32_bf16 v[88:91], v[140:143], v[210:213], v[88:91]
	s_waitcnt lgkmcnt(0)
	v_mfma_f32_16x16x32_bf16 v[80:83], v[132:135], v[218:221], v[80:83]
	v_mfma_f32_16x16x32_bf16 v[72:75], v[140:143], v[218:221], v[72:75]
	s_setprio 0
	s_setprio 1
	v_mfma_f32_16x16x32_bf16 v[116:119], v[156:159], v[188:191], v[116:119]
	v_mfma_f32_16x16x32_bf16 v[108:111], v[180:183], v[188:191], v[108:111]
	v_mfma_f32_16x16x32_bf16 v[100:103], v[156:159], v[196:199], v[100:103]
	v_mfma_f32_16x16x32_bf16 v[92:95], v[180:183], v[196:199], v[92:95]
	v_mfma_f32_16x16x32_bf16 v[84:87], v[156:159], v[206:209], v[84:87]
	v_mfma_f32_16x16x32_bf16 v[76:79], v[180:183], v[206:209], v[76:79]
	v_mfma_f32_16x16x32_bf16 v[68:71], v[156:159], v[214:217], v[68:71]
	v_mfma_f32_16x16x32_bf16 v[64:67], v[180:183], v[214:217], v[64:67]
	v_mfma_f32_16x16x32_bf16 v[116:119], v[162:165], v[192:195], v[116:119]
	v_mfma_f32_16x16x32_bf16 v[108:111], v[184:187], v[192:195], v[108:111]
	v_mfma_f32_16x16x32_bf16 v[100:103], v[162:165], v[202:205], v[100:103]
	v_mfma_f32_16x16x32_bf16 v[92:95], v[184:187], v[202:205], v[92:95]
	v_mfma_f32_16x16x32_bf16 v[84:87], v[162:165], v[210:213], v[84:87]
	v_mfma_f32_16x16x32_bf16 v[76:79], v[184:187], v[210:213], v[76:79]
	v_mfma_f32_16x16x32_bf16 v[68:71], v[162:165], v[218:221], v[68:71]
	v_mfma_f32_16x16x32_bf16 v[64:67], v[184:187], v[218:221], v[64:67]
	s_setprio 0
	s_barrier
	ds_read_b128 v[188:191], v175 offset:16384
	ds_read_b128 v[192:195], v175 offset:17408
	ds_read_b128 v[196:199], v175 offset:18432
	ds_read_b128 v[202:205], v175 offset:19456
	ds_read_b128 v[206:209], v175 offset:20480
	ds_read_b128 v[210:213], v175 offset:21504
	ds_read_b128 v[214:217], v175 offset:22528
	ds_read_b128 v[218:221], v175 offset:23552
	s_mov_b32 m0, s55
	s_nop 0
	global_load_lds_dwordx4 v161, s[48:49]
	s_add_u32 s80, s48, 0x80000
	s_mov_b32 m0, s56
	s_nop 0
	global_load_lds_dwordx4 v169, s[48:49]
	s_addc_u32 s81, s49, 0
	s_mov_b32 m0, s57
	s_nop 0
	global_load_lds_dwordx4 v161, s[80:81]
	s_nop 0
	s_mov_b32 m0, s58
	s_nop 0
	global_load_lds_dwordx4 v169, s[80:81]
	s_nop 0
	s_nop 0
	s_waitcnt vmcnt(6)
	s_waitcnt lgkmcnt(0)
	s_barrier
; #define PG8_STAGE(bufoff, gbase, voff) do { const unsigned long long gb_ = (unsigned long long)(gbase); _Pragma("unroll") for (int _i = 0; _i < 2; ++_i) { unsigned keep_; \
;         asm volatile("s_mov_b32 m0, %2\n\ts_nop 0\n\tglobal_load_lds_dwordx4 %0, %1" : : "v"((voff)[_i]), "s"(gb_), "s"((unsigned)(size_t)(lds + (bufoff) + ldsw + _i * 8192)) : "memory", "m0"); (void)keep_; } } while (0)
; #define PG8_LDA(dst, b, h) do { _Pragma("unroll") for (int m = 0; m < 4; ++m) _Pragma("unroll") for (int k = 0; k < 2; ++k) dst[m][k] = *(const PG8_LAS bf16x8*)(lds + PG8_SA(b, h) + aoff + m * 2048 + k * 1024); } while (0)
; #define PG8_LDB(dst, b, h) do { _Pragma("unroll") for (int n = 0; n < 2; ++n) _Pragma("unroll") for (int k = 0; k < 2; ++k) dst[n][k] = *(const PG8_LAS bf16x8*)(lds + PG8_SB(b, h) + boff + n * 2048 + k * 1024); } while (0)
; #define PG8_MMA(ai, bj, At, Bt) do { __builtin_amdgcn_s_setprio(1); _Pragma("unroll") for (int m = 0; m < 4; ++m) _Pragma("unroll") for (int n = 0; n < 2; ++n) _Pragma("unroll") for (int k = 0; k < 2; ++k) \
;         acc[ai][bj][m][n] = __builtin_amdgcn_mfma_f32_16x16x32_bf16(Bt[n][k], At[m][k], acc[ai][bj][m][n], 0, 0, 0); __builtin_amdgcn_s_setprio(0); } while (0)
; #define PG8_WAIT_V(n) asm volatile("s_waitcnt vmcnt(" #n ")" ::: "memory")
; #define PG8_WAIT_L(n) asm volatile("s_waitcnt lgkmcnt(" #n ")" ::: "memory")
; #define PG8_BAR __builtin_amdgcn_s_barrier()
; #define PG8_SCHED __builtin_amdgcn_sched_barrier(0)
; template <class Epi, class Sched, bool ALIGN_EPI = false, bool SP2 = false>
; __device__ __forceinline__ void gemm_phase(PG8_LAS unsigned char* lds, const Gemm g, const Sched& S, const Epi& E) {
;     ...
;             PG8_WAIT_V(8); PG8_WAIT_L(0); PG8_BAR; PG8_MMA(1, 0, At, B0); PG8_MMA(1, 1, At, B1); PG8_BAR; PG8_SCHED;
;             PG8_LDB(B0, 1, 0); PG8_LDB(B1, 1, 1); PG8_SCHED; PG8_LDA(At, 1, 0); PG8_STAGE(PG8_SA(0, 1), a2 + hstepA, voffA);
	s_setprio 1
	s_waitcnt lgkmcnt(7)
	v_mfma_f32_16x16x32_bf16 v[60:63], v[128:131], v[188:191], v[60:63]
	v_mfma_f32_16x16x32_bf16 v[56:59], v[136:139], v[188:191], v[56:59]
	s_waitcnt lgkmcnt(5)
	v_mfma_f32_16x16x32_bf16 v[48:51], v[128:131], v[196:199], v[48:51]
	v_mfma_f32_16x16x32_bf16 v[40:43], v[136:139], v[196:199], v[40:43]
	s_waitcnt lgkmcnt(3)
	v_mfma_f32_16x16x32_bf16 v[32:35], v[128:131], v[206:209], v[32:35]
	v_mfma_f32_16x16x32_bf16 v[24:27], v[136:139], v[206:209], v[24:27]
	s_waitcnt lgkmcnt(1)
	v_mfma_f32_16x16x32_bf16 v[16:19], v[128:131], v[214:217], v[16:19]
	v_mfma_f32_16x16x32_bf16 v[8:11], v[136:139], v[214:217], v[8:11]
	v_mfma_f32_16x16x32_bf16 v[60:63], v[132:135], v[192:195], v[60:63]
	v_mfma_f32_16x16x32_bf16 v[56:59], v[140:143], v[192:195], v[56:59]
	v_mfma_f32_16x16x32_bf16 v[48:51], v[132:135], v[202:205], v[48:51]
	v_mfma_f32_16x16x32_bf16 v[40:43], v[140:143], v[202:205], v[40:43]
	v_mfma_f32_16x16x32_bf16 v[32:35], v[132:135], v[210:213], v[32:35]
	v_mfma_f32_16x16x32_bf16 v[24:27], v[140:143], v[210:213], v[24:27]
	s_waitcnt lgkmcnt(0)
	v_mfma_f32_16x16x32_bf16 v[16:19], v[132:135], v[218:221], v[16:19]
	v_mfma_f32_16x16x32_bf16 v[8:11], v[140:143], v[218:221], v[8:11]
	s_setprio 0
	s_setprio 1
	v_mfma_f32_16x16x32_bf16 v[52:55], v[156:159], v[188:191], v[52:55]
	v_mfma_f32_16x16x32_bf16 v[44:47], v[180:183], v[188:191], v[44:47]
	v_mfma_f32_16x16x32_bf16 v[36:39], v[156:159], v[196:199], v[36:39]
	v_mfma_f32_16x16x32_bf16 v[28:31], v[180:183], v[196:199], v[28:31]
	v_mfma_f32_16x16x32_bf16 v[20:23], v[156:159], v[206:209], v[20:23]
	v_mfma_f32_16x16x32_bf16 v[12:15], v[180:183], v[206:209], v[12:15]
	v_mfma_f32_16x16x32_bf16 v[4:7], v[156:159], v[214:217], v[4:7]
	v_mfma_f32_16x16x32_bf16 v[0:3], v[180:183], v[214:217], v[0:3]
	v_mfma_f32_16x16x32_bf16 v[52:55], v[162:165], v[192:195], v[52:55]
	v_mfma_f32_16x16x32_bf16 v[44:47], v[184:187], v[192:195], v[44:47]
	v_mfma_f32_16x16x32_bf16 v[36:39], v[162:165], v[202:205], v[36:39]
	v_mfma_f32_16x16x32_bf16 v[28:31], v[184:187], v[202:205], v[28:31]
	v_mfma_f32_16x16x32_bf16 v[20:23], v[162:165], v[210:213], v[20:23]
	v_mfma_f32_16x16x32_bf16 v[12:15], v[184:187], v[210:213], v[12:15]
	v_mfma_f32_16x16x32_bf16 v[4:7], v[162:165], v[218:221], v[4:7]
	v_mfma_f32_16x16x32_bf16 v[0:3], v[184:187], v[218:221], v[0:3]
	s_setprio 0
	s_barrier
	ds_read_b128 v[128:131], v176
	ds_read_b128 v[132:135], v176 offset:1024
	ds_read_b128 v[136:139], v176 offset:2048
	ds_read_b128 v[140:143], v176 offset:3072
	ds_read_b128 v[156:159], v177
	ds_read_b128 v[162:165], v177 offset:1024
	ds_read_b128 v[180:183], v177 offset:2048
	ds_read_b128 v[184:187], v177 offset:3072
	ds_read_b128 v[188:191], v175 offset:32768
	ds_read_b128 v[192:195], v175 offset:33792
	ds_read_b128 v[196:199], v175 offset:34816
	ds_read_b128 v[202:205], v175 offset:35840
	ds_read_b128 v[206:209], v175 offset:36864
	ds_read_b128 v[210:213], v175 offset:37888
	ds_read_b128 v[214:217], v175 offset:38912
	ds_read_b128 v[218:221], v175 offset:39936
	s_mov_b32 m0, s39
	s_nop 0
	global_load_lds_dwordx4 v149, s[50:51]
	s_nop 0
	s_mov_b32 m0, s59
	s_nop 0
	global_load_lds_dwordx4 v167, s[50:51]
	s_nop 0
	s_add_u32 s50, s50, 0x10000
	s_addc_u32 s51, s51, 0
	s_mov_b32 m0, s60
	s_nop 0
	global_load_lds_dwordx4 v149, s[50:51]
	s_nop 0
	s_mov_b32 m0, s61
	s_nop 0
	global_load_lds_dwordx4 v167, s[50:51]
	s_waitcnt vmcnt(8)
	s_waitcnt lgkmcnt(0)
	s_barrier
; #define PG8_STAGE(bufoff, gbase, voff) do { const unsigned long long gb_ = (unsigned long long)(gbase); _Pragma("unroll") for (int _i = 0; _i < 2; ++_i) { unsigned keep_; \
;         asm volatile("s_mov_b32 m0, %2\n\ts_nop 0\n\tglobal_load_lds_dwordx4 %0, %1" : : "v"((voff)[_i]), "s"(gb_), "s"((unsigned)(size_t)(lds + (bufoff) + ldsw + _i * 8192)) : "memory", "m0"); (void)keep_; } } while (0)
; #define PG8_LDA(dst, b, h) do { _Pragma("unroll") for (int m = 0; m < 4; ++m) _Pragma("unroll") for (int k = 0; k < 2; ++k) dst[m][k] = *(const PG8_LAS bf16x8*)(lds + PG8_SA(b, h) + aoff + m * 2048 + k * 1024); } while (0)
; #define PG8_LDB(dst, b, h) do { _Pragma("unroll") for (int n = 0; n < 2; ++n) _Pragma("unroll") for (int k = 0; k < 2; ++k) dst[n][k] = *(const PG8_LAS bf16x8*)(lds + PG8_SB(b, h) + boff + n * 2048 + k * 1024); } while (0)
; #define PG8_MMA(ai, bj, At, Bt) do { __builtin_amdgcn_s_setprio(1); _Pragma("unroll") for (int m = 0; m < 4; ++m) _Pragma("unroll") for (int n = 0; n < 2; ++n) _Pragma("unroll") for (int k = 0; k < 2; ++k) \
;         acc[ai][bj][m][n] = __builtin_amdgcn_mfma_f32_16x16x32_bf16(Bt[n][k], At[m][k], acc[ai][bj][m][n], 0, 0, 0); __builtin_amdgcn_s_setprio(0); } while (0)
; #define PG8_WAIT_V(n) asm volatile("s_waitcnt vmcnt(" #n ")" ::: "memory")
; #define PG8_WAIT_L(n) asm volatile("s_waitcnt lgkmcnt(" #n ")" ::: "memory")
; #define PG8_BAR __builtin_amdgcn_s_barrier()
; #define PG8_SCHED __builtin_amdgcn_sched_barrier(0)
; template <class Epi, class Sched, bool ALIGN_EPI = false, bool SP2 = false>
; __device__ __forceinline__ void gemm_phase(PG8_LAS unsigned char* lds, const Gemm g, const Sched& S, const Epi& E) {
;     ...
;             PG8_LDB(B0, 1, 0); PG8_LDB(B1, 1, 1); PG8_SCHED; PG8_LDA(At, 1, 0); PG8_STAGE(PG8_SA(0, 1), a2 + hstepA, voffA);
;             PG8_WAIT_V(8); PG8_WAIT_L(0); PG8_BAR; PG8_MMA(0, 0, At, B0); PG8_MMA(0, 1, At, B1); PG8_BAR; PG8_SCHED;
;             PG8_LDA(At, 1, 1); PG8_STAGE(PG8_SB(1, 0), b3, voffB); PG8_STAGE(PG8_SB(1, 1), b3 + hstepB, voffB); PG8_STAGE(PG8_SA(1, 0), a3, voffA);
;             PG8_WAIT_V(8); PG8_WAIT_L(0); PG8_BAR; PG8_MMA(1, 0, At, B0); PG8_MMA(1, 1, At, B1); PG8_BAR; PG8_SCHED;
;     ...
;         if constexpr (ALIGN_EPI) { if (wr == 0) PG8_BAR; }
	s_setprio 1
	s_waitcnt lgkmcnt(7)
	v_mfma_f32_16x16x32_bf16 v[124:127], v[128:131], v[188:191], v[124:127]
	v_mfma_f32_16x16x32_bf16 v[120:123], v[136:139], v[188:191], v[120:123]
	s_waitcnt lgkmcnt(5)
	v_mfma_f32_16x16x32_bf16 v[112:115], v[128:131], v[196:199], v[112:115]
	v_mfma_f32_16x16x32_bf16 v[104:107], v[136:139], v[196:199], v[104:107]
	s_waitcnt lgkmcnt(3)
	v_mfma_f32_16x16x32_bf16 v[96:99], v[128:131], v[206:209], v[96:99]
	v_mfma_f32_16x16x32_bf16 v[88:91], v[136:139], v[206:209], v[88:91]
	s_waitcnt lgkmcnt(1)
	v_mfma_f32_16x16x32_bf16 v[80:83], v[128:131], v[214:217], v[80:83]
	v_mfma_f32_16x16x32_bf16 v[72:75], v[136:139], v[214:217], v[72:75]
	v_mfma_f32_16x16x32_bf16 v[124:127], v[132:135], v[192:195], v[124:127]
	v_mfma_f32_16x16x32_bf16 v[120:123], v[140:143], v[192:195], v[120:123]
	v_mfma_f32_16x16x32_bf16 v[112:115], v[132:135], v[202:205], v[112:115]
	v_mfma_f32_16x16x32_bf16 v[104:107], v[140:143], v[202:205], v[104:107]
	v_mfma_f32_16x16x32_bf16 v[96:99], v[132:135], v[210:213], v[96:99]
	v_mfma_f32_16x16x32_bf16 v[88:91], v[140:143], v[210:213], v[88:91]
	s_waitcnt lgkmcnt(0)
	v_mfma_f32_16x16x32_bf16 v[80:83], v[132:135], v[218:221], v[80:83]
	v_mfma_f32_16x16x32_bf16 v[72:75], v[140:143], v[218:221], v[72:75]
	s_setprio 0
	s_setprio 1
	v_mfma_f32_16x16x32_bf16 v[116:119], v[156:159], v[188:191], v[116:119]
	v_mfma_f32_16x16x32_bf16 v[108:111], v[180:183], v[188:191], v[108:111]
	v_mfma_f32_16x16x32_bf16 v[100:103], v[156:159], v[196:199], v[100:103]
	v_mfma_f32_16x16x32_bf16 v[92:95], v[180:183], v[196:199], v[92:95]
	v_mfma_f32_16x16x32_bf16 v[84:87], v[156:159], v[206:209], v[84:87]
	v_mfma_f32_16x16x32_bf16 v[76:79], v[180:183], v[206:209], v[76:79]
	v_mfma_f32_16x16x32_bf16 v[68:71], v[156:159], v[214:217], v[68:71]
	v_mfma_f32_16x16x32_bf16 v[64:67], v[180:183], v[214:217], v[64:67]
	v_mfma_f32_16x16x32_bf16 v[116:119], v[162:165], v[192:195], v[116:119]
	v_mfma_f32_16x16x32_bf16 v[108:111], v[184:187], v[192:195], v[108:111]
	v_mfma_f32_16x16x32_bf16 v[100:103], v[162:165], v[202:205], v[100:103]
	v_mfma_f32_16x16x32_bf16 v[92:95], v[184:187], v[202:205], v[92:95]
	v_mfma_f32_16x16x32_bf16 v[84:87], v[162:165], v[210:213], v[84:87]
	v_mfma_f32_16x16x32_bf16 v[76:79], v[184:187], v[210:213], v[76:79]
	v_mfma_f32_16x16x32_bf16 v[68:71], v[162:165], v[218:221], v[68:71]
	v_mfma_f32_16x16x32_bf16 v[64:67], v[184:187], v[218:221], v[64:67]
	s_setprio 0
	s_barrier
	ds_read_b128 v[188:191], v175 offset:49152
	ds_read_b128 v[192:195], v175 offset:50176
	ds_read_b128 v[196:199], v175 offset:51200
	ds_read_b128 v[202:205], v175 offset:52224
	ds_read_b128 v[206:209], v175 offset:53248
	ds_read_b128 v[210:213], v175 offset:54272
	ds_read_b128 v[214:217], v175 offset:55296
	ds_read_b128 v[218:221], v175 offset:56320
	s_add_u32 s50, s48, 0x80
	s_addc_u32 s51, s49, 0
	s_mov_b32 m0, s62
	s_nop 0
	global_load_lds_dwordx4 v161, s[50:51]
	s_add_u32 s48, s48, 0x80080
	s_mov_b32 m0, s63
	s_nop 0
	global_load_lds_dwordx4 v169, s[50:51]
	s_addc_u32 s49, s49, 0
	s_mov_b32 m0, s66
	s_nop 0
	global_load_lds_dwordx4 v161, s[48:49]
	s_nop 0
	s_mov_b32 m0, s67
	s_nop 0
	global_load_lds_dwordx4 v169, s[48:49]
	s_nop 0
	s_nop 0
	s_waitcnt vmcnt(6)
	s_waitcnt lgkmcnt(0)
	s_barrier
	s_setprio 1
	s_waitcnt lgkmcnt(7)
	v_mfma_f32_16x16x32_bf16 v[60:63], v[128:131], v[188:191], v[60:63]
	v_mfma_f32_16x16x32_bf16 v[56:59], v[136:139], v[188:191], v[56:59]
	s_waitcnt lgkmcnt(5)
	v_mfma_f32_16x16x32_bf16 v[48:51], v[128:131], v[196:199], v[48:51]
	v_mfma_f32_16x16x32_bf16 v[40:43], v[136:139], v[196:199], v[40:43]
	s_waitcnt lgkmcnt(3)
	v_mfma_f32_16x16x32_bf16 v[32:35], v[128:131], v[206:209], v[32:35]
	v_mfma_f32_16x16x32_bf16 v[24:27], v[136:139], v[206:209], v[24:27]
	s_waitcnt lgkmcnt(1)
	v_mfma_f32_16x16x32_bf16 v[16:19], v[128:131], v[214:217], v[16:19]
	v_mfma_f32_16x16x32_bf16 v[8:11], v[136:139], v[214:217], v[8:11]
	v_mfma_f32_16x16x32_bf16 v[60:63], v[132:135], v[192:195], v[60:63]
	v_mfma_f32_16x16x32_bf16 v[56:59], v[140:143], v[192:195], v[56:59]
	v_mfma_f32_16x16x32_bf16 v[48:51], v[132:135], v[202:205], v[48:51]
	v_mfma_f32_16x16x32_bf16 v[40:43], v[140:143], v[202:205], v[40:43]
	v_mfma_f32_16x16x32_bf16 v[32:35], v[132:135], v[210:213], v[32:35]
	v_mfma_f32_16x16x32_bf16 v[24:27], v[140:143], v[210:213], v[24:27]
	s_waitcnt lgkmcnt(0)
	v_mfma_f32_16x16x32_bf16 v[16:19], v[132:135], v[218:221], v[16:19]
	v_mfma_f32_16x16x32_bf16 v[8:11], v[140:143], v[218:221], v[8:11]
	s_setprio 0
	s_setprio 1
	v_mfma_f32_16x16x32_bf16 v[52:55], v[156:159], v[188:191], v[52:55]
	v_mfma_f32_16x16x32_bf16 v[44:47], v[180:183], v[188:191], v[44:47]
	v_mfma_f32_16x16x32_bf16 v[36:39], v[156:159], v[196:199], v[36:39]
	v_mfma_f32_16x16x32_bf16 v[28:31], v[180:183], v[196:199], v[28:31]
	v_mfma_f32_16x16x32_bf16 v[20:23], v[156:159], v[206:209], v[20:23]
	v_mfma_f32_16x16x32_bf16 v[12:15], v[180:183], v[206:209], v[12:15]
	v_mfma_f32_16x16x32_bf16 v[4:7], v[156:159], v[214:217], v[4:7]
	v_mfma_f32_16x16x32_bf16 v[0:3], v[180:183], v[214:217], v[0:3]
	v_mfma_f32_16x16x32_bf16 v[52:55], v[162:165], v[192:195], v[52:55]
	v_mfma_f32_16x16x32_bf16 v[44:47], v[184:187], v[192:195], v[44:47]
	v_mfma_f32_16x16x32_bf16 v[36:39], v[162:165], v[202:205], v[36:39]
	v_mfma_f32_16x16x32_bf16 v[28:31], v[184:187], v[202:205], v[28:31]
	v_mfma_f32_16x16x32_bf16 v[20:23], v[162:165], v[210:213], v[20:23]
	v_mfma_f32_16x16x32_bf16 v[12:15], v[184:187], v[210:213], v[12:15]
	v_mfma_f32_16x16x32_bf16 v[4:7], v[162:165], v[218:221], v[4:7]
	v_mfma_f32_16x16x32_bf16 v[0:3], v[184:187], v[218:221], v[0:3]
	s_setprio 0
	s_barrier
	s_add_u32 s44, s44, 0x100
	s_addc_u32 s45, s45, 0
	s_cmp_gt_u32 s78, 29
	s_mov_b32 s46, s78
	s_cbranch_scc0 .LBB0_1630
	s_and_b64 vcc, exec, s[24:25]
	s_cbranch_vccz .LBB0_1633
	s_barrier

; #define PG8_STAGE(bufoff, gbase, voff) do { const unsigned long long gb_ = (unsigned long long)(gbase); _Pragma("unroll") for (int _i = 0; _i < 2; ++_i) { unsigned keep_; \
;         asm volatile("s_mov_b32 m0, %2\n\ts_nop 0\n\tglobal_load_lds_dwordx4 %0, %1" : : "v"((voff)[_i]), "s"(gb_), "s"((unsigned)(size_t)(lds + (bufoff) + ldsw + _i * 8192)) : "memory", "m0"); (void)keep_; } } while (0)
; #define PG8_LDA(dst, b, h) do { _Pragma("unroll") for (int m = 0; m < 4; ++m) _Pragma("unroll") for (int k = 0; k < 2; ++k) dst[m][k] = *(const PG8_LAS bf16x8*)(lds + PG8_SA(b, h) + aoff + m * 2048 + k * 1024); } while (0)
; #define PG8_LDB(dst, b, h) do { _Pragma("unroll") for (int n = 0; n < 2; ++n) _Pragma("unroll") for (int k = 0; k < 2; ++k) dst[n][k] = *(const PG8_LAS bf16x8*)(lds + PG8_SB(b, h) + boff + n * 2048 + k * 1024); } while (0)
; #define PG8_MMA(ai, bj, At, Bt) do { __builtin_amdgcn_s_setprio(1); _Pragma("unroll") for (int m = 0; m < 4; ++m) _Pragma("unroll") for (int n = 0; n < 2; ++n) _Pragma("unroll") for (int k = 0; k < 2; ++k) \
;         acc[ai][bj][m][n] = __builtin_amdgcn_mfma_f32_16x16x32_bf16(Bt[n][k], At[m][k], acc[ai][bj][m][n], 0, 0, 0); __builtin_amdgcn_s_setprio(0); } while (0)
; #define PG8_BAR __builtin_amdgcn_s_barrier()
; template <class Epi, class Sched, bool ALIGN_EPI = false, bool SP2 = false>
; __device__ __forceinline__ void gemm_phase(PG8_LAS unsigned char* lds, const Gemm g, const Sched& S, const Epi& E) {
;     ...
;             const bool last = (t == nt - 2);
;     ...
;             const char* a1 = cA + PG8_KOFFA(t + 1);
;             const char* a2 = last ? nA : cA + PG8_KOFFA(t + 2); const char* b2 = last ? nB : cB + (size_t)(t + 2) * kstep;
;             const char* a3 = last ? nA + kstep : cA + PG8_KOFFA(t + 3); const char* b3 = b2 + kstep;
;     ...
;             if (last && has_next) S.a_ready(nxt);
;             if constexpr (SP2) {
;             PG8_LDB(B0, 0, 0); PG8_LDB(B1, 0, 1); PG8_SCHED; PG8_LDA(At, 0, 0); PG8_STAGE(PG8_SA(1, 1), a1 + hstepA, voffA);
;             PG8_WAIT_V(8); PG8_WAIT_L(0); PG8_BAR; PG8_MMA(0, 0, At, B0); PG8_MMA(0, 1, At, B1); PG8_BAR; PG8_SCHED;
;             PG8_LDA(At, 0, 1); PG8_STAGE(PG8_SB(0, 0), b2, voffB); PG8_STAGE(PG8_SB(0, 1), b2 + hstepB, voffB); PG8_STAGE(PG8_SA(0, 0), a2, voffA);
;             PG8_WAIT_V(8); PG8_WAIT_L(0); PG8_BAR; PG8_MMA(1, 0, At, B0); PG8_MMA(1, 1, At, B1); PG8_BAR; PG8_SCHED;
.LBB0_1825:
	ds_read_b128 v[88:91], v203
	ds_read_b128 v[92:95], v203 offset:1024
	ds_read_b128 v[96:99], v203 offset:2048
	ds_read_b128 v[100:103], v203 offset:3072
	ds_read_b128 v[128:131], v232
	ds_read_b128 v[136:139], v232 offset:1024
	ds_read_b128 v[152:155], v232 offset:2048
	ds_read_b128 v[156:159], v232 offset:3072
	s_cmp_eq_u32 s79, 28
	s_cselect_b32 s49, s0, s78
	s_cselect_b32 s48, s1, s77
	s_cselect_b32 s47, s16, s76
	s_cselect_b32 s46, s31, s73
	s_cselect_b32 s45, s70, s72
	s_cselect_b32 s44, s35, s71
	ds_read_b128 v[160:163], v233
	ds_read_b128 v[164:167], v233 offset:1024
	ds_read_b128 v[168:171], v233 offset:2048
	ds_read_b128 v[172:175], v233 offset:3072
	ds_read_b128 v[176:179], v233 offset:4096
	ds_read_b128 v[180:183], v233 offset:5120
	ds_read_b128 v[184:187], v233 offset:6144
	ds_read_b128 v[188:191], v233 offset:7168
	s_sub_u32 s98, s10, 0x80000
	s_subb_u32 s99, s11, 0
	s_mov_b32 m0, s61
	s_nop 0
	global_load_lds_dwordx4 v201, s[98:99]
	s_nop 0
	s_mov_b32 m0, s62
	s_nop 0
	global_load_lds_dwordx4 v230, s[98:99]
	s_nop 0
	s_mov_b32 m0, s65
	s_nop 0
	global_load_lds_dwordx4 v201, s[10:11]
	s_nop 0
	s_mov_b32 m0, s66
	s_nop 0
	global_load_lds_dwordx4 v230, s[10:11]
	s_waitcnt vmcnt(8)
	s_waitcnt lgkmcnt(0)
	s_barrier
	s_setprio 1
	s_waitcnt lgkmcnt(7)
	v_mfma_f32_16x16x32_bf16 v[148:151], v[88:91], v[160:163], v[148:151]
	v_mfma_f32_16x16x32_bf16 v[144:147], v[96:99], v[160:163], v[144:147]
	s_waitcnt lgkmcnt(5)
	v_mfma_f32_16x16x32_bf16 v[124:127], v[88:91], v[168:171], v[124:127]
	v_mfma_f32_16x16x32_bf16 v[120:123], v[96:99], v[168:171], v[120:123]
	s_waitcnt lgkmcnt(3)
	v_mfma_f32_16x16x32_bf16 v[108:111], v[88:91], v[176:179], v[108:111]
	v_mfma_f32_16x16x32_bf16 v[104:107], v[96:99], v[176:179], v[104:107]
	s_waitcnt lgkmcnt(1)
	v_mfma_f32_16x16x32_bf16 v[76:79], v[88:91], v[184:187], v[76:79]
	v_mfma_f32_16x16x32_bf16 v[72:75], v[96:99], v[184:187], v[72:75]
	v_mfma_f32_16x16x32_bf16 v[148:151], v[92:95], v[164:167], v[148:151]
	v_mfma_f32_16x16x32_bf16 v[144:147], v[100:103], v[164:167], v[144:147]
	v_mfma_f32_16x16x32_bf16 v[124:127], v[92:95], v[172:175], v[124:127]
	v_mfma_f32_16x16x32_bf16 v[120:123], v[100:103], v[172:175], v[120:123]
	v_mfma_f32_16x16x32_bf16 v[108:111], v[92:95], v[180:183], v[108:111]
	v_mfma_f32_16x16x32_bf16 v[104:107], v[100:103], v[180:183], v[104:107]
	s_waitcnt lgkmcnt(0)
	v_mfma_f32_16x16x32_bf16 v[76:79], v[92:95], v[188:191], v[76:79]
	v_mfma_f32_16x16x32_bf16 v[72:75], v[100:103], v[188:191], v[72:75]
	s_setprio 0
	s_setprio 1
	v_mfma_f32_16x16x32_bf16 v[140:143], v[128:131], v[160:163], v[140:143]
	v_mfma_f32_16x16x32_bf16 v[132:135], v[152:155], v[160:163], v[132:135]
	v_mfma_f32_16x16x32_bf16 v[116:119], v[128:131], v[168:171], v[116:119]
	v_mfma_f32_16x16x32_bf16 v[112:115], v[152:155], v[168:171], v[112:115]
	v_mfma_f32_16x16x32_bf16 v[84:87], v[128:131], v[176:179], v[84:87]
	v_mfma_f32_16x16x32_bf16 v[80:83], v[152:155], v[176:179], v[80:83]
	v_mfma_f32_16x16x32_bf16 v[68:71], v[128:131], v[184:187], v[68:71]
	v_mfma_f32_16x16x32_bf16 v[64:67], v[152:155], v[184:187], v[64:67]
	v_mfma_f32_16x16x32_bf16 v[140:143], v[136:139], v[164:167], v[140:143]
	v_mfma_f32_16x16x32_bf16 v[132:135], v[156:159], v[164:167], v[132:135]
	v_mfma_f32_16x16x32_bf16 v[116:119], v[136:139], v[172:175], v[116:119]
	v_mfma_f32_16x16x32_bf16 v[112:115], v[156:159], v[172:175], v[112:115]
	v_mfma_f32_16x16x32_bf16 v[84:87], v[136:139], v[180:183], v[84:87]
	v_mfma_f32_16x16x32_bf16 v[80:83], v[156:159], v[180:183], v[80:83]
	v_mfma_f32_16x16x32_bf16 v[68:71], v[136:139], v[188:191], v[68:71]
	v_mfma_f32_16x16x32_bf16 v[64:67], v[156:159], v[188:191], v[64:67]
	s_setprio 0
	s_barrier
	ds_read_b128 v[160:163], v233 offset:16384
	ds_read_b128 v[164:167], v233 offset:17408
	ds_read_b128 v[168:171], v233 offset:18432
	ds_read_b128 v[172:175], v233 offset:19456
	ds_read_b128 v[176:179], v233 offset:20480
	ds_read_b128 v[180:183], v233 offset:21504
	ds_read_b128 v[184:187], v233 offset:22528
	ds_read_b128 v[188:191], v233 offset:23552
	s_mov_b32 m0, s43
	s_nop 0
	global_load_lds_dwordx4 v205, s[46:47]
	s_add_u32 s80, s46, 0x80000
	s_mov_b32 m0, s52
	s_nop 0
	global_load_lds_dwordx4 v231, s[46:47]
	s_addc_u32 s81, s47, 0
	s_mov_b32 m0, s53
	s_nop 0
	global_load_lds_dwordx4 v205, s[80:81]
	s_nop 0
	s_mov_b32 m0, s54
	s_nop 0
	global_load_lds_dwordx4 v231, s[80:81]
	s_nop 0
	s_nop 0
	s_waitcnt vmcnt(6)
	s_waitcnt lgkmcnt(0)
	s_barrier
	s_setprio 1
	s_waitcnt lgkmcnt(7)
	v_mfma_f32_16x16x32_bf16 v[60:63], v[88:91], v[160:163], v[60:63]
	v_mfma_f32_16x16x32_bf16 v[56:59], v[96:99], v[160:163], v[56:59]
	s_waitcnt lgkmcnt(5)
	v_mfma_f32_16x16x32_bf16 v[44:47], v[88:91], v[168:171], v[44:47]
	v_mfma_f32_16x16x32_bf16 v[40:43], v[96:99], v[168:171], v[40:43]
	s_waitcnt lgkmcnt(3)
	v_mfma_f32_16x16x32_bf16 v[28:31], v[88:91], v[176:179], v[28:31]
	v_mfma_f32_16x16x32_bf16 v[24:27], v[96:99], v[176:179], v[24:27]
	s_waitcnt lgkmcnt(1)
	v_mfma_f32_16x16x32_bf16 v[12:15], v[88:91], v[184:187], v[12:15]
	v_mfma_f32_16x16x32_bf16 v[8:11], v[96:99], v[184:187], v[8:11]
	v_mfma_f32_16x16x32_bf16 v[60:63], v[92:95], v[164:167], v[60:63]
	v_mfma_f32_16x16x32_bf16 v[56:59], v[100:103], v[164:167], v[56:59]
	v_mfma_f32_16x16x32_bf16 v[44:47], v[92:95], v[172:175], v[44:47]
	v_mfma_f32_16x16x32_bf16 v[40:43], v[100:103], v[172:175], v[40:43]
	v_mfma_f32_16x16x32_bf16 v[28:31], v[92:95], v[180:183], v[28:31]
	v_mfma_f32_16x16x32_bf16 v[24:27], v[100:103], v[180:183], v[24:27]
	s_waitcnt lgkmcnt(0)
	v_mfma_f32_16x16x32_bf16 v[12:15], v[92:95], v[188:191], v[12:15]
	v_mfma_f32_16x16x32_bf16 v[8:11], v[100:103], v[188:191], v[8:11]
	s_setprio 0
	s_setprio 1
	v_mfma_f32_16x16x32_bf16 v[52:55], v[128:131], v[160:163], v[52:55]
	v_mfma_f32_16x16x32_bf16 v[48:51], v[152:155], v[160:163], v[48:51]
	v_mfma_f32_16x16x32_bf16 v[36:39], v[128:131], v[168:171], v[36:39]
	v_mfma_f32_16x16x32_bf16 v[32:35], v[152:155], v[168:171], v[32:35]
	v_mfma_f32_16x16x32_bf16 v[20:23], v[128:131], v[176:179], v[20:23]
	v_mfma_f32_16x16x32_bf16 v[16:19], v[152:155], v[176:179], v[16:19]
	v_mfma_f32_16x16x32_bf16 v[4:7], v[128:131], v[184:187], v[4:7]
	v_mfma_f32_16x16x32_bf16 v[0:3], v[152:155], v[184:187], v[0:3]
	v_mfma_f32_16x16x32_bf16 v[52:55], v[136:139], v[164:167], v[52:55]
	v_mfma_f32_16x16x32_bf16 v[48:51], v[156:159], v[164:167], v[48:51]
	v_mfma_f32_16x16x32_bf16 v[36:39], v[136:139], v[172:175], v[36:39]
	v_mfma_f32_16x16x32_bf16 v[32:35], v[156:159], v[172:175], v[32:35]
	v_mfma_f32_16x16x32_bf16 v[20:23], v[136:139], v[180:183], v[20:23]
	v_mfma_f32_16x16x32_bf16 v[16:19], v[156:159], v[180:183], v[16:19]
	v_mfma_f32_16x16x32_bf16 v[4:7], v[136:139], v[188:191], v[4:7]
	v_mfma_f32_16x16x32_bf16 v[0:3], v[156:159], v[188:191], v[0:3]
	s_setprio 0
	s_barrier
; #define PG8_STAGE(bufoff, gbase, voff) do { const unsigned long long gb_ = (unsigned long long)(gbase); _Pragma("unroll") for (int _i = 0; _i < 2; ++_i) { unsigned keep_; \
;         asm volatile("s_mov_b32 m0, %2\n\ts_nop 0\n\tglobal_load_lds_dwordx4 %0, %1" : : "v"((voff)[_i]), "s"(gb_), "s"((unsigned)(size_t)(lds + (bufoff) + ldsw + _i * 8192)) : "memory", "m0"); (void)keep_; } } while (0)
; #define PG8_LDA(dst, b, h) do { _Pragma("unroll") for (int m = 0; m < 4; ++m) _Pragma("unroll") for (int k = 0; k < 2; ++k) dst[m][k] = *(const PG8_LAS bf16x8*)(lds + PG8_SA(b, h) + aoff + m * 2048 + k * 1024); } while (0)
; #define PG8_LDB(dst, b, h) do { _Pragma("unroll") for (int n = 0; n < 2; ++n) _Pragma("unroll") for (int k = 0; k < 2; ++k) dst[n][k] = *(const PG8_LAS bf16x8*)(lds + PG8_SB(b, h) + boff + n * 2048 + k * 1024); } while (0)
; #define PG8_MMA(ai, bj, At, Bt) do { __builtin_amdgcn_s_setprio(1); _Pragma("unroll") for (int m = 0; m < 4; ++m) _Pragma("unroll") for (int n = 0; n < 2; ++n) _Pragma("unroll") for (int k = 0; k < 2; ++k) \
;         acc[ai][bj][m][n] = __builtin_amdgcn_mfma_f32_16x16x32_bf16(Bt[n][k], At[m][k], acc[ai][bj][m][n], 0, 0, 0); __builtin_amdgcn_s_setprio(0); } while (0)
; #define PG8_WAIT_V(n) asm volatile("s_waitcnt vmcnt(" #n ")" ::: "memory")
; #define PG8_WAIT_L(n) asm volatile("s_waitcnt lgkmcnt(" #n ")" ::: "memory")
; #define PG8_BAR __builtin_amdgcn_s_barrier()
; #define PG8_SCHED __builtin_amdgcn_sched_barrier(0)
; template <class Epi, class Sched, bool ALIGN_EPI = false, bool SP2 = false>
; __device__ __forceinline__ void gemm_phase(PG8_LAS unsigned char* lds, const Gemm g, const Sched& S, const Epi& E) {
;     ...
;             PG8_LDB(B0, 1, 0); PG8_LDB(B1, 1, 1); PG8_SCHED; PG8_LDA(At, 1, 0); PG8_STAGE(PG8_SA(0, 1), a2 + hstepA, voffA);
;             PG8_WAIT_V(8); PG8_WAIT_L(0); PG8_BAR; PG8_MMA(0, 0, At, B0); PG8_MMA(0, 1, At, B1); PG8_BAR; PG8_SCHED;
;             PG8_LDA(At, 1, 1); PG8_STAGE(PG8_SB(1, 0), b3, voffB); PG8_STAGE(PG8_SB(1, 1), b3 + hstepB, voffB); PG8_STAGE(PG8_SA(1, 0), a3, voffA);
;             PG8_WAIT_V(8); PG8_WAIT_L(0); PG8_BAR; PG8_MMA(1, 0, At, B0); PG8_MMA(1, 1, At, B1); PG8_BAR; PG8_SCHED;
;     ...
;         if constexpr (ALIGN_EPI) { if (wr == 0) PG8_BAR; }
	ds_read_b128 v[88:91], v234
	ds_read_b128 v[92:95], v234 offset:1024
	ds_read_b128 v[96:99], v234 offset:2048
	ds_read_b128 v[100:103], v234 offset:3072
	ds_read_b128 v[128:131], v235
	ds_read_b128 v[136:139], v235 offset:1024
	ds_read_b128 v[152:155], v235 offset:2048
	ds_read_b128 v[156:159], v235 offset:3072
	ds_read_b128 v[160:163], v233 offset:32768
	ds_read_b128 v[164:167], v233 offset:33792
	ds_read_b128 v[168:171], v233 offset:34816
	ds_read_b128 v[172:175], v233 offset:35840
	ds_read_b128 v[176:179], v233 offset:36864
	ds_read_b128 v[180:183], v233 offset:37888
	ds_read_b128 v[184:187], v233 offset:38912
	ds_read_b128 v[188:191], v233 offset:39936
	s_mov_b32 m0, s41
	s_nop 0
	global_load_lds_dwordx4 v201, s[48:49]
	s_nop 0
	s_mov_b32 m0, s55
	s_nop 0
	global_load_lds_dwordx4 v230, s[48:49]
	s_nop 0
	s_add_u32 s48, s48, 0x80000
	s_addc_u32 s49, s49, 0
	s_mov_b32 m0, s56
	s_nop 0
	global_load_lds_dwordx4 v201, s[48:49]
	s_nop 0
	s_mov_b32 m0, s57
	s_nop 0
	global_load_lds_dwordx4 v230, s[48:49]
	s_waitcnt vmcnt(8)
	s_waitcnt lgkmcnt(0)
	s_barrier
	s_setprio 1
	s_waitcnt lgkmcnt(7)
	v_mfma_f32_16x16x32_bf16 v[148:151], v[88:91], v[160:163], v[148:151]
	v_mfma_f32_16x16x32_bf16 v[144:147], v[96:99], v[160:163], v[144:147]
	s_waitcnt lgkmcnt(5)
	v_mfma_f32_16x16x32_bf16 v[124:127], v[88:91], v[168:171], v[124:127]
	v_mfma_f32_16x16x32_bf16 v[120:123], v[96:99], v[168:171], v[120:123]
	s_waitcnt lgkmcnt(3)
	v_mfma_f32_16x16x32_bf16 v[108:111], v[88:91], v[176:179], v[108:111]
	v_mfma_f32_16x16x32_bf16 v[104:107], v[96:99], v[176:179], v[104:107]
	s_waitcnt lgkmcnt(1)
	v_mfma_f32_16x16x32_bf16 v[76:79], v[88:91], v[184:187], v[76:79]
	v_mfma_f32_16x16x32_bf16 v[72:75], v[96:99], v[184:187], v[72:75]
	v_mfma_f32_16x16x32_bf16 v[148:151], v[92:95], v[164:167], v[148:151]
	v_mfma_f32_16x16x32_bf16 v[144:147], v[100:103], v[164:167], v[144:147]
	v_mfma_f32_16x16x32_bf16 v[124:127], v[92:95], v[172:175], v[124:127]
	v_mfma_f32_16x16x32_bf16 v[120:123], v[100:103], v[172:175], v[120:123]
	v_mfma_f32_16x16x32_bf16 v[108:111], v[92:95], v[180:183], v[108:111]
	v_mfma_f32_16x16x32_bf16 v[104:107], v[100:103], v[180:183], v[104:107]
	s_waitcnt lgkmcnt(0)
	v_mfma_f32_16x16x32_bf16 v[76:79], v[92:95], v[188:191], v[76:79]
	v_mfma_f32_16x16x32_bf16 v[72:75], v[100:103], v[188:191], v[72:75]
	s_setprio 0
	s_setprio 1
	v_mfma_f32_16x16x32_bf16 v[140:143], v[128:131], v[160:163], v[140:143]
	v_mfma_f32_16x16x32_bf16 v[132:135], v[152:155], v[160:163], v[132:135]
	v_mfma_f32_16x16x32_bf16 v[116:119], v[128:131], v[168:171], v[116:119]
	v_mfma_f32_16x16x32_bf16 v[112:115], v[152:155], v[168:171], v[112:115]
	v_mfma_f32_16x16x32_bf16 v[84:87], v[128:131], v[176:179], v[84:87]
	v_mfma_f32_16x16x32_bf16 v[80:83], v[152:155], v[176:179], v[80:83]
	v_mfma_f32_16x16x32_bf16 v[68:71], v[128:131], v[184:187], v[68:71]
	v_mfma_f32_16x16x32_bf16 v[64:67], v[152:155], v[184:187], v[64:67]
	v_mfma_f32_16x16x32_bf16 v[140:143], v[136:139], v[164:167], v[140:143]
	v_mfma_f32_16x16x32_bf16 v[132:135], v[156:159], v[164:167], v[132:135]
	v_mfma_f32_16x16x32_bf16 v[116:119], v[136:139], v[172:175], v[116:119]
	v_mfma_f32_16x16x32_bf16 v[112:115], v[156:159], v[172:175], v[112:115]
	v_mfma_f32_16x16x32_bf16 v[84:87], v[136:139], v[180:183], v[84:87]
	v_mfma_f32_16x16x32_bf16 v[80:83], v[156:159], v[180:183], v[80:83]
	v_mfma_f32_16x16x32_bf16 v[68:71], v[136:139], v[188:191], v[68:71]
	v_mfma_f32_16x16x32_bf16 v[64:67], v[156:159], v[188:191], v[64:67]
	s_setprio 0
	s_barrier
	ds_read_b128 v[160:163], v233 offset:49152
	ds_read_b128 v[164:167], v233 offset:50176
	ds_read_b128 v[168:171], v233 offset:51200
	ds_read_b128 v[172:175], v233 offset:52224
	ds_read_b128 v[176:179], v233 offset:53248
	ds_read_b128 v[180:183], v233 offset:54272
	ds_read_b128 v[184:187], v233 offset:55296
	ds_read_b128 v[188:191], v233 offset:56320
	s_add_u32 s48, s46, 0x80
	s_addc_u32 s49, s47, 0
	s_mov_b32 m0, s59
	s_nop 0
	global_load_lds_dwordx4 v205, s[48:49]
	s_add_u32 s46, s46, 0x80080
	s_mov_b32 m0, s60
	s_nop 0
	global_load_lds_dwordx4 v231, s[48:49]
	s_addc_u32 s47, s47, 0
	s_mov_b32 m0, s63
	s_nop 0
	global_load_lds_dwordx4 v205, s[46:47]
	s_nop 0
	s_mov_b32 m0, s64
	s_nop 0
	global_load_lds_dwordx4 v231, s[46:47]
	s_nop 0
	s_nop 0
	s_waitcnt vmcnt(6)
	s_waitcnt lgkmcnt(0)
	s_barrier
	s_setprio 1
	s_waitcnt lgkmcnt(7)
	v_mfma_f32_16x16x32_bf16 v[60:63], v[88:91], v[160:163], v[60:63]
	v_mfma_f32_16x16x32_bf16 v[56:59], v[96:99], v[160:163], v[56:59]
	s_waitcnt lgkmcnt(5)
	v_mfma_f32_16x16x32_bf16 v[44:47], v[88:91], v[168:171], v[44:47]
	v_mfma_f32_16x16x32_bf16 v[40:43], v[96:99], v[168:171], v[40:43]
	s_waitcnt lgkmcnt(3)
	v_mfma_f32_16x16x32_bf16 v[28:31], v[88:91], v[176:179], v[28:31]
	v_mfma_f32_16x16x32_bf16 v[24:27], v[96:99], v[176:179], v[24:27]
	s_waitcnt lgkmcnt(1)
	v_mfma_f32_16x16x32_bf16 v[12:15], v[88:91], v[184:187], v[12:15]
	v_mfma_f32_16x16x32_bf16 v[8:11], v[96:99], v[184:187], v[8:11]
	v_mfma_f32_16x16x32_bf16 v[60:63], v[92:95], v[164:167], v[60:63]
	v_mfma_f32_16x16x32_bf16 v[56:59], v[100:103], v[164:167], v[56:59]
	v_mfma_f32_16x16x32_bf16 v[44:47], v[92:95], v[172:175], v[44:47]
	v_mfma_f32_16x16x32_bf16 v[40:43], v[100:103], v[172:175], v[40:43]
	v_mfma_f32_16x16x32_bf16 v[28:31], v[92:95], v[180:183], v[28:31]
	v_mfma_f32_16x16x32_bf16 v[24:27], v[100:103], v[180:183], v[24:27]
	s_waitcnt lgkmcnt(0)
	v_mfma_f32_16x16x32_bf16 v[12:15], v[92:95], v[188:191], v[12:15]
	v_mfma_f32_16x16x32_bf16 v[8:11], v[100:103], v[188:191], v[8:11]
	s_setprio 0
	s_setprio 1
	v_mfma_f32_16x16x32_bf16 v[52:55], v[128:131], v[160:163], v[52:55]
	v_mfma_f32_16x16x32_bf16 v[48:51], v[152:155], v[160:163], v[48:51]
	v_mfma_f32_16x16x32_bf16 v[36:39], v[128:131], v[168:171], v[36:39]
	v_mfma_f32_16x16x32_bf16 v[32:35], v[152:155], v[168:171], v[32:35]
	v_mfma_f32_16x16x32_bf16 v[20:23], v[128:131], v[176:179], v[20:23]
	v_mfma_f32_16x16x32_bf16 v[16:19], v[152:155], v[176:179], v[16:19]
	v_mfma_f32_16x16x32_bf16 v[4:7], v[128:131], v[184:187], v[4:7]
	v_mfma_f32_16x16x32_bf16 v[0:3], v[152:155], v[184:187], v[0:3]
	v_mfma_f32_16x16x32_bf16 v[52:55], v[136:139], v[164:167], v[52:55]
	v_mfma_f32_16x16x32_bf16 v[48:51], v[156:159], v[164:167], v[48:51]
	v_mfma_f32_16x16x32_bf16 v[36:39], v[136:139], v[172:175], v[36:39]
	v_mfma_f32_16x16x32_bf16 v[32:35], v[156:159], v[172:175], v[32:35]
	v_mfma_f32_16x16x32_bf16 v[20:23], v[136:139], v[180:183], v[20:23]
	v_mfma_f32_16x16x32_bf16 v[16:19], v[156:159], v[180:183], v[16:19]
	v_mfma_f32_16x16x32_bf16 v[4:7], v[136:139], v[188:191], v[4:7]
	v_mfma_f32_16x16x32_bf16 v[0:3], v[156:159], v[188:191], v[0:3]
	s_setprio 0
	s_barrier
	s_add_i32 s79, s79, 2
	s_add_u32 s71, s71, 0x100
	s_addc_u32 s72, s72, 0
	s_add_u32 s73, s73, 0x100
	s_addc_u32 s76, s76, 0
	s_add_u32 s77, s77, 0x100
	s_addc_u32 s78, s78, 0
	s_add_u32 s10, s10, 0x100
	s_addc_u32 s11, s11, 0
	s_cmp_gt_u32 s79, 29
	s_cbranch_scc0 .LBB0_1825
	s_and_b64 vcc, exec, s[26:27]
	s_cbranch_vccz .LBB0_1828
	s_barrier

; #define PG8_STAGE(bufoff, gbase, voff) do { const unsigned long long gb_ = (unsigned long long)(gbase); _Pragma("unroll") for (int _i = 0; _i < 2; ++_i) { unsigned keep_; \
;         asm volatile("s_mov_b32 m0, %2\n\ts_nop 0\n\tglobal_load_lds_dwordx4 %0, %1" : : "v"((voff)[_i]), "s"(gb_), "s"((unsigned)(size_t)(lds + (bufoff) + ldsw + _i * 8192)) : "memory", "m0"); (void)keep_; } } while (0)
; #define PG8_LDA(dst, b, h) do { _Pragma("unroll") for (int m = 0; m < 4; ++m) _Pragma("unroll") for (int k = 0; k < 2; ++k) dst[m][k] = *(const PG8_LAS bf16x8*)(lds + PG8_SA(b, h) + aoff + m * 2048 + k * 1024); } while (0)
; #define PG8_LDB(dst, b, h) do { _Pragma("unroll") for (int n = 0; n < 2; ++n) _Pragma("unroll") for (int k = 0; k < 2; ++k) dst[n][k] = *(const PG8_LAS bf16x8*)(lds + PG8_SB(b, h) + boff + n * 2048 + k * 1024); } while (0)
; #define PG8_MMA(ai, bj, At, Bt) do { __builtin_amdgcn_s_setprio(1); _Pragma("unroll") for (int m = 0; m < 4; ++m) _Pragma("unroll") for (int n = 0; n < 2; ++n) _Pragma("unroll") for (int k = 0; k < 2; ++k) \
;         acc[ai][bj][m][n] = __builtin_amdgcn_mfma_f32_16x16x32_bf16(Bt[n][k], At[m][k], acc[ai][bj][m][n], 0, 0, 0); __builtin_amdgcn_s_setprio(0); } while (0)
; #define PG8_WAIT_V(n) asm volatile("s_waitcnt vmcnt(" #n ")" ::: "memory")
; #define PG8_WAIT_L(n) asm volatile("s_waitcnt lgkmcnt(" #n ")" ::: "memory")
; template <class Epi, class Sched, bool ALIGN_EPI = false, bool SP2 = false>
; __device__ __forceinline__ void gemm_phase(PG8_LAS unsigned char* lds, const Gemm g, const Sched& S, const Epi& E) {
;     ...
;             const bool last = (t == nt - 2);
;     ...
;             const char* a1 = cA + PG8_KOFFA(t + 1);
;             const char* a2 = last ? nA : cA + PG8_KOFFA(t + 2); const char* b2 = last ? nB : cB + (size_t)(t + 2) * kstep;
;             const char* a3 = last ? nA + kstep : cA + PG8_KOFFA(t + 3); const char* b3 = b2 + kstep;
;     ...
;             if (last && has_next) S.a_ready(nxt);
;             if constexpr (SP2) {
;             PG8_LDB(B0, 0, 0); PG8_LDB(B1, 0, 1); PG8_SCHED; PG8_LDA(At, 0, 0); PG8_STAGE(PG8_SA(1, 1), a1 + hstepA, voffA);
;             PG8_WAIT_V(8); PG8_WAIT_L(0); PG8_BAR; PG8_MMA(0, 0, At, B0); PG8_MMA(0, 1, At, B1); PG8_BAR; PG8_SCHED;
;             PG8_LDA(At, 0, 1); PG8_STAGE(PG8_SB(0, 0), b2, voffB); PG8_STAGE(PG8_SB(0, 1), b2 + hstepB, voffB); PG8_STAGE(PG8_SA(0, 0), a2, voffA);
.LBB0_2228:
	s_add_i32 s43, s77, 0xfffe8000
	s_and_b32 s42, s40, 0x100
	s_and_b32 s43, s43, 0xe0000
	s_or_b32 s42, s42, s43
	s_add_u32 s78, s10, s42
	s_addc_u32 s79, s11, 0
	s_add_u32 s42, s40, 0x100
	s_addc_u32 s43, s41, 0
	s_add_i32 s45, s77, 0xffff8000
	s_and_b32 s44, s42, 0x100
	s_and_b32 s45, s45, 0x1e0000
	s_or_b32 s44, s45, s44
	ds_read_b128 v[128:131], v177
	ds_read_b128 v[132:135], v177 offset:1024
	ds_read_b128 v[162:165], v177 offset:2048
	ds_read_b128 v[166:169], v177 offset:3072
	ds_read_b128 v[184:187], v178
	ds_read_b128 v[188:191], v178 offset:1024
	ds_read_b128 v[192:195], v178 offset:2048
	ds_read_b128 v[196:199], v178 offset:3072
	s_add_u32 s44, s10, s44
	s_addc_u32 s45, s11, 0
	s_add_u32 s80, s39, s40
	s_addc_u32 s41, s73, s41
	s_add_i32 s46, s40, 0x180
	s_and_b32 s46, s46, 0x180
	s_and_b32 s47, s77, 0x1e0000
	s_or_b32 s46, s47, s46
	s_add_u32 s81, s10, s46
	s_addc_u32 s82, s11, 0
	s_cmpk_eq_i32 s40, 0xf00
	s_cselect_b32 s47, s0, s45
	s_cselect_b32 s45, s4, s41
	s_cselect_b32 s41, s31, s82
	s_cselect_b32 s40, s29, s81
	s_cselect_b32 s46, s1, s44
	s_cselect_b32 s44, s5, s80
	ds_read_b128 v[202:205], v179
	ds_read_b128 v[206:209], v179 offset:1024
	ds_read_b128 v[210:213], v179 offset:2048
	ds_read_b128 v[214:217], v179 offset:3072
	ds_read_b128 v[218:221], v179 offset:4096
	ds_read_b128 v[222:225], v179 offset:5120
	ds_read_b128 v[226:229], v179 offset:6144
	ds_read_b128 v[230:233], v179 offset:7168
	s_add_u32 s78, s78, 0x10080
	s_addc_u32 s79, s79, 0
	s_sub_u32 s98, s78, 0x10000
	s_subb_u32 s99, s79, 0
	s_mov_b32 m0, s64
	s_nop 0
	global_load_lds_dwordx4 v172, s[98:99]
	s_nop 0
	s_mov_b32 m0, s65
	s_nop 0
	global_load_lds_dwordx4 v174, s[98:99]
	s_nop 0
	s_mov_b32 m0, s68
	s_nop 0
	global_load_lds_dwordx4 v172, s[78:79]
	s_nop 0
	s_mov_b32 m0, s69
	s_nop 0
	global_load_lds_dwordx4 v174, s[78:79]
	s_waitcnt vmcnt(8)
	s_waitcnt lgkmcnt(0)
	s_barrier
	s_setprio 1
	s_waitcnt lgkmcnt(7)
	v_mfma_f32_16x16x32_bf16 v[124:127], v[128:131], v[202:205], v[124:127]
	v_mfma_f32_16x16x32_bf16 v[120:123], v[162:165], v[202:205], v[120:123]
	s_waitcnt lgkmcnt(5)
	v_mfma_f32_16x16x32_bf16 v[108:111], v[128:131], v[210:213], v[108:111]
	v_mfma_f32_16x16x32_bf16 v[104:107], v[162:165], v[210:213], v[104:107]
	s_waitcnt lgkmcnt(3)
	v_mfma_f32_16x16x32_bf16 v[92:95], v[128:131], v[218:221], v[92:95]
	v_mfma_f32_16x16x32_bf16 v[88:91], v[162:165], v[218:221], v[88:91]
	s_waitcnt lgkmcnt(1)
	v_mfma_f32_16x16x32_bf16 v[76:79], v[128:131], v[226:229], v[76:79]
	v_mfma_f32_16x16x32_bf16 v[72:75], v[162:165], v[226:229], v[72:75]
	v_mfma_f32_16x16x32_bf16 v[124:127], v[132:135], v[206:209], v[124:127]
	v_mfma_f32_16x16x32_bf16 v[120:123], v[166:169], v[206:209], v[120:123]
	v_mfma_f32_16x16x32_bf16 v[108:111], v[132:135], v[214:217], v[108:111]
	v_mfma_f32_16x16x32_bf16 v[104:107], v[166:169], v[214:217], v[104:107]
	v_mfma_f32_16x16x32_bf16 v[92:95], v[132:135], v[222:225], v[92:95]
	v_mfma_f32_16x16x32_bf16 v[88:91], v[166:169], v[222:225], v[88:91]
	s_waitcnt lgkmcnt(0)
	v_mfma_f32_16x16x32_bf16 v[76:79], v[132:135], v[230:233], v[76:79]
	v_mfma_f32_16x16x32_bf16 v[72:75], v[166:169], v[230:233], v[72:75]
	s_setprio 0
	s_setprio 1
	v_mfma_f32_16x16x32_bf16 v[116:119], v[184:187], v[202:205], v[116:119]
	v_mfma_f32_16x16x32_bf16 v[112:115], v[192:195], v[202:205], v[112:115]
	v_mfma_f32_16x16x32_bf16 v[100:103], v[184:187], v[210:213], v[100:103]
	v_mfma_f32_16x16x32_bf16 v[96:99], v[192:195], v[210:213], v[96:99]
	v_mfma_f32_16x16x32_bf16 v[84:87], v[184:187], v[218:221], v[84:87]
	v_mfma_f32_16x16x32_bf16 v[80:83], v[192:195], v[218:221], v[80:83]
	v_mfma_f32_16x16x32_bf16 v[68:71], v[184:187], v[226:229], v[68:71]
	v_mfma_f32_16x16x32_bf16 v[64:67], v[192:195], v[226:229], v[64:67]
	v_mfma_f32_16x16x32_bf16 v[116:119], v[188:191], v[206:209], v[116:119]
	v_mfma_f32_16x16x32_bf16 v[112:115], v[196:199], v[206:209], v[112:115]
	v_mfma_f32_16x16x32_bf16 v[100:103], v[188:191], v[214:217], v[100:103]
	v_mfma_f32_16x16x32_bf16 v[96:99], v[196:199], v[214:217], v[96:99]
	v_mfma_f32_16x16x32_bf16 v[84:87], v[188:191], v[222:225], v[84:87]
	v_mfma_f32_16x16x32_bf16 v[80:83], v[196:199], v[222:225], v[80:83]
	v_mfma_f32_16x16x32_bf16 v[68:71], v[188:191], v[230:233], v[68:71]
	v_mfma_f32_16x16x32_bf16 v[64:67], v[196:199], v[230:233], v[64:67]
	s_setprio 0
	s_barrier
	ds_read_b128 v[202:205], v179 offset:16384
	ds_read_b128 v[206:209], v179 offset:17408
	ds_read_b128 v[210:213], v179 offset:18432
	ds_read_b128 v[214:217], v179 offset:19456
	ds_read_b128 v[218:221], v179 offset:20480
	ds_read_b128 v[222:225], v179 offset:21504
	ds_read_b128 v[226:229], v179 offset:22528
	ds_read_b128 v[230:233], v179 offset:23552
	s_mov_b32 m0, s54
	s_nop 0
	global_load_lds_dwordx4 v173, s[44:45]
	s_add_u32 s78, s44, 0x80000
	s_mov_b32 m0, s55
	s_nop 0
	global_load_lds_dwordx4 v175, s[44:45]
	s_addc_u32 s79, s45, 0
	s_mov_b32 m0, s56
	s_nop 0
	global_load_lds_dwordx4 v173, s[78:79]
	s_nop 0
	s_mov_b32 m0, s57
	s_nop 0
	global_load_lds_dwordx4 v175, s[78:79]
	s_nop 0
	s_nop 0
	s_waitcnt vmcnt(6)
	s_waitcnt lgkmcnt(0)
	s_barrier
; #define PG8_STAGE(bufoff, gbase, voff) do { const unsigned long long gb_ = (unsigned long long)(gbase); _Pragma("unroll") for (int _i = 0; _i < 2; ++_i) { unsigned keep_; \
;         asm volatile("s_mov_b32 m0, %2\n\ts_nop 0\n\tglobal_load_lds_dwordx4 %0, %1" : : "v"((voff)[_i]), "s"(gb_), "s"((unsigned)(size_t)(lds + (bufoff) + ldsw + _i * 8192)) : "memory", "m0"); (void)keep_; } } while (0)
; #define PG8_LDA(dst, b, h) do { _Pragma("unroll") for (int m = 0; m < 4; ++m) _Pragma("unroll") for (int k = 0; k < 2; ++k) dst[m][k] = *(const PG8_LAS bf16x8*)(lds + PG8_SA(b, h) + aoff + m * 2048 + k * 1024); } while (0)
; #define PG8_LDB(dst, b, h) do { _Pragma("unroll") for (int n = 0; n < 2; ++n) _Pragma("unroll") for (int k = 0; k < 2; ++k) dst[n][k] = *(const PG8_LAS bf16x8*)(lds + PG8_SB(b, h) + boff + n * 2048 + k * 1024); } while (0)
; #define PG8_MMA(ai, bj, At, Bt) do { __builtin_amdgcn_s_setprio(1); _Pragma("unroll") for (int m = 0; m < 4; ++m) _Pragma("unroll") for (int n = 0; n < 2; ++n) _Pragma("unroll") for (int k = 0; k < 2; ++k) \
;         acc[ai][bj][m][n] = __builtin_amdgcn_mfma_f32_16x16x32_bf16(Bt[n][k], At[m][k], acc[ai][bj][m][n], 0, 0, 0); __builtin_amdgcn_s_setprio(0); } while (0)
; #define PG8_WAIT_V(n) asm volatile("s_waitcnt vmcnt(" #n ")" ::: "memory")
; #define PG8_WAIT_L(n) asm volatile("s_waitcnt lgkmcnt(" #n ")" ::: "memory")
; #define PG8_BAR __builtin_amdgcn_s_barrier()
; #define PG8_SCHED __builtin_amdgcn_sched_barrier(0)
; template <class Epi, class Sched, bool ALIGN_EPI = false, bool SP2 = false>
; __device__ __forceinline__ void gemm_phase(PG8_LAS unsigned char* lds, const Gemm g, const Sched& S, const Epi& E) {
;     ...
;             PG8_WAIT_V(8); PG8_WAIT_L(0); PG8_BAR; PG8_MMA(1, 0, At, B0); PG8_MMA(1, 1, At, B1); PG8_BAR; PG8_SCHED;
;             PG8_LDB(B0, 1, 0); PG8_LDB(B1, 1, 1); PG8_SCHED; PG8_LDA(At, 1, 0); PG8_STAGE(PG8_SA(0, 1), a2 + hstepA, voffA);
	s_setprio 1
	s_waitcnt lgkmcnt(7)
	v_mfma_f32_16x16x32_bf16 v[60:63], v[128:131], v[202:205], v[60:63]
	v_mfma_f32_16x16x32_bf16 v[56:59], v[162:165], v[202:205], v[56:59]
	s_waitcnt lgkmcnt(5)
	v_mfma_f32_16x16x32_bf16 v[44:47], v[128:131], v[210:213], v[44:47]
	v_mfma_f32_16x16x32_bf16 v[40:43], v[162:165], v[210:213], v[40:43]
	s_waitcnt lgkmcnt(3)
	v_mfma_f32_16x16x32_bf16 v[28:31], v[128:131], v[218:221], v[28:31]
	v_mfma_f32_16x16x32_bf16 v[24:27], v[162:165], v[218:221], v[24:27]
	s_waitcnt lgkmcnt(1)
	v_mfma_f32_16x16x32_bf16 v[12:15], v[128:131], v[226:229], v[12:15]
	v_mfma_f32_16x16x32_bf16 v[8:11], v[162:165], v[226:229], v[8:11]
	v_mfma_f32_16x16x32_bf16 v[60:63], v[132:135], v[206:209], v[60:63]
	v_mfma_f32_16x16x32_bf16 v[56:59], v[166:169], v[206:209], v[56:59]
	v_mfma_f32_16x16x32_bf16 v[44:47], v[132:135], v[214:217], v[44:47]
	v_mfma_f32_16x16x32_bf16 v[40:43], v[166:169], v[214:217], v[40:43]
	v_mfma_f32_16x16x32_bf16 v[28:31], v[132:135], v[222:225], v[28:31]
	v_mfma_f32_16x16x32_bf16 v[24:27], v[166:169], v[222:225], v[24:27]
	s_waitcnt lgkmcnt(0)
	v_mfma_f32_16x16x32_bf16 v[12:15], v[132:135], v[230:233], v[12:15]
	v_mfma_f32_16x16x32_bf16 v[8:11], v[166:169], v[230:233], v[8:11]
	s_setprio 0
	s_setprio 1
	v_mfma_f32_16x16x32_bf16 v[52:55], v[184:187], v[202:205], v[52:55]
	v_mfma_f32_16x16x32_bf16 v[48:51], v[192:195], v[202:205], v[48:51]
	v_mfma_f32_16x16x32_bf16 v[36:39], v[184:187], v[210:213], v[36:39]
	v_mfma_f32_16x16x32_bf16 v[32:35], v[192:195], v[210:213], v[32:35]
	v_mfma_f32_16x16x32_bf16 v[20:23], v[184:187], v[218:221], v[20:23]
	v_mfma_f32_16x16x32_bf16 v[16:19], v[192:195], v[218:221], v[16:19]
	v_mfma_f32_16x16x32_bf16 v[4:7], v[184:187], v[226:229], v[4:7]
	v_mfma_f32_16x16x32_bf16 v[0:3], v[192:195], v[226:229], v[0:3]
	v_mfma_f32_16x16x32_bf16 v[52:55], v[188:191], v[206:209], v[52:55]
	v_mfma_f32_16x16x32_bf16 v[48:51], v[196:199], v[206:209], v[48:51]
	v_mfma_f32_16x16x32_bf16 v[36:39], v[188:191], v[214:217], v[36:39]
	v_mfma_f32_16x16x32_bf16 v[32:35], v[196:199], v[214:217], v[32:35]
	v_mfma_f32_16x16x32_bf16 v[20:23], v[188:191], v[222:225], v[20:23]
	v_mfma_f32_16x16x32_bf16 v[16:19], v[196:199], v[222:225], v[16:19]
	v_mfma_f32_16x16x32_bf16 v[4:7], v[188:191], v[230:233], v[4:7]
	v_mfma_f32_16x16x32_bf16 v[0:3], v[196:199], v[230:233], v[0:3]
	s_setprio 0
	s_barrier
	ds_read_b128 v[128:131], v180
	ds_read_b128 v[132:135], v180 offset:1024
	ds_read_b128 v[162:165], v180 offset:2048
	ds_read_b128 v[166:169], v180 offset:3072
	ds_read_b128 v[184:187], v181
	ds_read_b128 v[188:191], v181 offset:1024
	ds_read_b128 v[192:195], v181 offset:2048
	ds_read_b128 v[196:199], v181 offset:3072
	ds_read_b128 v[202:205], v179 offset:32768
	ds_read_b128 v[206:209], v179 offset:33792
	ds_read_b128 v[210:213], v179 offset:34816
	ds_read_b128 v[214:217], v179 offset:35840
	ds_read_b128 v[218:221], v179 offset:36864
	ds_read_b128 v[222:225], v179 offset:37888
	ds_read_b128 v[226:229], v179 offset:38912
	ds_read_b128 v[230:233], v179 offset:39936
	s_mov_b32 m0, s53
	s_nop 0
	global_load_lds_dwordx4 v172, s[46:47]
	s_nop 0
	s_mov_b32 m0, s58
	s_nop 0
	global_load_lds_dwordx4 v174, s[46:47]
	s_nop 0
	s_add_u32 s46, s46, 0x10000
	s_addc_u32 s47, s47, 0
	s_mov_b32 m0, s59
	s_nop 0
	global_load_lds_dwordx4 v172, s[46:47]
	s_nop 0
	s_mov_b32 m0, s60
	s_nop 0
	global_load_lds_dwordx4 v174, s[46:47]
	s_waitcnt vmcnt(8)
	s_waitcnt lgkmcnt(0)
	s_barrier
; #define PG8_STAGE(bufoff, gbase, voff) do { const unsigned long long gb_ = (unsigned long long)(gbase); _Pragma("unroll") for (int _i = 0; _i < 2; ++_i) { unsigned keep_; \
;         asm volatile("s_mov_b32 m0, %2\n\ts_nop 0\n\tglobal_load_lds_dwordx4 %0, %1" : : "v"((voff)[_i]), "s"(gb_), "s"((unsigned)(size_t)(lds + (bufoff) + ldsw + _i * 8192)) : "memory", "m0"); (void)keep_; } } while (0)
; #define PG8_LDA(dst, b, h) do { _Pragma("unroll") for (int m = 0; m < 4; ++m) _Pragma("unroll") for (int k = 0; k < 2; ++k) dst[m][k] = *(const PG8_LAS bf16x8*)(lds + PG8_SA(b, h) + aoff + m * 2048 + k * 1024); } while (0)
; #define PG8_MMA(ai, bj, At, Bt) do { __builtin_amdgcn_s_setprio(1); _Pragma("unroll") for (int m = 0; m < 4; ++m) _Pragma("unroll") for (int n = 0; n < 2; ++n) _Pragma("unroll") for (int k = 0; k < 2; ++k) \
;         acc[ai][bj][m][n] = __builtin_amdgcn_mfma_f32_16x16x32_bf16(Bt[n][k], At[m][k], acc[ai][bj][m][n], 0, 0, 0); __builtin_amdgcn_s_setprio(0); } while (0)
; #define PG8_WAIT_V(n) asm volatile("s_waitcnt vmcnt(" #n ")" ::: "memory")
; #define PG8_WAIT_L(n) asm volatile("s_waitcnt lgkmcnt(" #n ")" ::: "memory")
; #define PG8_BAR __builtin_amdgcn_s_barrier()
; #define PG8_SCHED __builtin_amdgcn_sched_barrier(0)
; template <class Epi, class Sched, bool ALIGN_EPI = false, bool SP2 = false>
; __device__ __forceinline__ void gemm_phase(PG8_LAS unsigned char* lds, const Gemm g, const Sched& S, const Epi& E) {
;     ...
;             PG8_WAIT_V(8); PG8_WAIT_L(0); PG8_BAR; PG8_MMA(0, 0, At, B0); PG8_MMA(0, 1, At, B1); PG8_BAR; PG8_SCHED;
;             PG8_LDA(At, 1, 1); PG8_STAGE(PG8_SB(1, 0), b3, voffB); PG8_STAGE(PG8_SB(1, 1), b3 + hstepB, voffB); PG8_STAGE(PG8_SA(1, 0), a3, voffA);
;             PG8_WAIT_V(8); PG8_WAIT_L(0); PG8_BAR; PG8_MMA(1, 0, At, B0); PG8_MMA(1, 1, At, B1); PG8_BAR; PG8_SCHED;
;     ...
;         if constexpr (ALIGN_EPI) { if (wr == 0) PG8_BAR; }
	s_setprio 1
	s_waitcnt lgkmcnt(7)
	v_mfma_f32_16x16x32_bf16 v[124:127], v[128:131], v[202:205], v[124:127]
	v_mfma_f32_16x16x32_bf16 v[120:123], v[162:165], v[202:205], v[120:123]
	s_waitcnt lgkmcnt(5)
	v_mfma_f32_16x16x32_bf16 v[108:111], v[128:131], v[210:213], v[108:111]
	v_mfma_f32_16x16x32_bf16 v[104:107], v[162:165], v[210:213], v[104:107]
	s_waitcnt lgkmcnt(3)
	v_mfma_f32_16x16x32_bf16 v[92:95], v[128:131], v[218:221], v[92:95]
	v_mfma_f32_16x16x32_bf16 v[88:91], v[162:165], v[218:221], v[88:91]
	s_waitcnt lgkmcnt(1)
	v_mfma_f32_16x16x32_bf16 v[76:79], v[128:131], v[226:229], v[76:79]
	v_mfma_f32_16x16x32_bf16 v[72:75], v[162:165], v[226:229], v[72:75]
	v_mfma_f32_16x16x32_bf16 v[124:127], v[132:135], v[206:209], v[124:127]
	v_mfma_f32_16x16x32_bf16 v[120:123], v[166:169], v[206:209], v[120:123]
	v_mfma_f32_16x16x32_bf16 v[108:111], v[132:135], v[214:217], v[108:111]
	v_mfma_f32_16x16x32_bf16 v[104:107], v[166:169], v[214:217], v[104:107]
	v_mfma_f32_16x16x32_bf16 v[92:95], v[132:135], v[222:225], v[92:95]
	v_mfma_f32_16x16x32_bf16 v[88:91], v[166:169], v[222:225], v[88:91]
	s_waitcnt lgkmcnt(0)
	v_mfma_f32_16x16x32_bf16 v[76:79], v[132:135], v[230:233], v[76:79]
	v_mfma_f32_16x16x32_bf16 v[72:75], v[166:169], v[230:233], v[72:75]
	s_setprio 0
	s_setprio 1
	v_mfma_f32_16x16x32_bf16 v[116:119], v[184:187], v[202:205], v[116:119]
	v_mfma_f32_16x16x32_bf16 v[112:115], v[192:195], v[202:205], v[112:115]
	v_mfma_f32_16x16x32_bf16 v[100:103], v[184:187], v[210:213], v[100:103]
	v_mfma_f32_16x16x32_bf16 v[96:99], v[192:195], v[210:213], v[96:99]
	v_mfma_f32_16x16x32_bf16 v[84:87], v[184:187], v[218:221], v[84:87]
	v_mfma_f32_16x16x32_bf16 v[80:83], v[192:195], v[218:221], v[80:83]
	v_mfma_f32_16x16x32_bf16 v[68:71], v[184:187], v[226:229], v[68:71]
	v_mfma_f32_16x16x32_bf16 v[64:67], v[192:195], v[226:229], v[64:67]
	v_mfma_f32_16x16x32_bf16 v[116:119], v[188:191], v[206:209], v[116:119]
	v_mfma_f32_16x16x32_bf16 v[112:115], v[196:199], v[206:209], v[112:115]
	v_mfma_f32_16x16x32_bf16 v[100:103], v[188:191], v[214:217], v[100:103]
	v_mfma_f32_16x16x32_bf16 v[96:99], v[196:199], v[214:217], v[96:99]
	v_mfma_f32_16x16x32_bf16 v[84:87], v[188:191], v[222:225], v[84:87]
	v_mfma_f32_16x16x32_bf16 v[80:83], v[196:199], v[222:225], v[80:83]
	v_mfma_f32_16x16x32_bf16 v[68:71], v[188:191], v[230:233], v[68:71]
	v_mfma_f32_16x16x32_bf16 v[64:67], v[196:199], v[230:233], v[64:67]
	s_setprio 0
	s_barrier
	ds_read_b128 v[202:205], v179 offset:49152
	ds_read_b128 v[206:209], v179 offset:50176
	ds_read_b128 v[210:213], v179 offset:51200
	ds_read_b128 v[214:217], v179 offset:52224
	ds_read_b128 v[218:221], v179 offset:53248
	ds_read_b128 v[222:225], v179 offset:54272
	ds_read_b128 v[226:229], v179 offset:55296
	ds_read_b128 v[230:233], v179 offset:56320
	s_add_u32 s46, s44, 0x80
	s_addc_u32 s47, s45, 0
	s_mov_b32 m0, s62
	s_nop 0
	global_load_lds_dwordx4 v173, s[46:47]
	s_add_u32 s44, s44, 0x80080
	s_mov_b32 m0, s63
	s_nop 0
	global_load_lds_dwordx4 v175, s[46:47]
	s_addc_u32 s45, s45, 0
	s_mov_b32 m0, s66
	s_nop 0
	global_load_lds_dwordx4 v173, s[44:45]
	s_nop 0
	s_mov_b32 m0, s67
	s_nop 0
	global_load_lds_dwordx4 v175, s[44:45]
	s_nop 0
	s_nop 0
	s_waitcnt vmcnt(6)
	s_waitcnt lgkmcnt(0)
	s_barrier
	s_setprio 1
	s_waitcnt lgkmcnt(7)
	v_mfma_f32_16x16x32_bf16 v[60:63], v[128:131], v[202:205], v[60:63]
	v_mfma_f32_16x16x32_bf16 v[56:59], v[162:165], v[202:205], v[56:59]
	s_waitcnt lgkmcnt(5)
	v_mfma_f32_16x16x32_bf16 v[44:47], v[128:131], v[210:213], v[44:47]
	v_mfma_f32_16x16x32_bf16 v[40:43], v[162:165], v[210:213], v[40:43]
	s_waitcnt lgkmcnt(3)
	v_mfma_f32_16x16x32_bf16 v[28:31], v[128:131], v[218:221], v[28:31]
	v_mfma_f32_16x16x32_bf16 v[24:27], v[162:165], v[218:221], v[24:27]
	s_waitcnt lgkmcnt(1)
	v_mfma_f32_16x16x32_bf16 v[12:15], v[128:131], v[226:229], v[12:15]
	v_mfma_f32_16x16x32_bf16 v[8:11], v[162:165], v[226:229], v[8:11]
	v_mfma_f32_16x16x32_bf16 v[60:63], v[132:135], v[206:209], v[60:63]
	v_mfma_f32_16x16x32_bf16 v[56:59], v[166:169], v[206:209], v[56:59]
	v_mfma_f32_16x16x32_bf16 v[44:47], v[132:135], v[214:217], v[44:47]
	v_mfma_f32_16x16x32_bf16 v[40:43], v[166:169], v[214:217], v[40:43]
	v_mfma_f32_16x16x32_bf16 v[28:31], v[132:135], v[222:225], v[28:31]
	v_mfma_f32_16x16x32_bf16 v[24:27], v[166:169], v[222:225], v[24:27]
	s_waitcnt lgkmcnt(0)
	v_mfma_f32_16x16x32_bf16 v[12:15], v[132:135], v[230:233], v[12:15]
	v_mfma_f32_16x16x32_bf16 v[8:11], v[166:169], v[230:233], v[8:11]
	s_setprio 0
	s_setprio 1
	v_mfma_f32_16x16x32_bf16 v[52:55], v[184:187], v[202:205], v[52:55]
	v_mfma_f32_16x16x32_bf16 v[48:51], v[192:195], v[202:205], v[48:51]
	v_mfma_f32_16x16x32_bf16 v[36:39], v[184:187], v[210:213], v[36:39]
	v_mfma_f32_16x16x32_bf16 v[32:35], v[192:195], v[210:213], v[32:35]
	v_mfma_f32_16x16x32_bf16 v[20:23], v[184:187], v[218:221], v[20:23]
	v_mfma_f32_16x16x32_bf16 v[16:19], v[192:195], v[218:221], v[16:19]
	v_mfma_f32_16x16x32_bf16 v[4:7], v[184:187], v[226:229], v[4:7]
	v_mfma_f32_16x16x32_bf16 v[0:3], v[192:195], v[226:229], v[0:3]
	v_mfma_f32_16x16x32_bf16 v[52:55], v[188:191], v[206:209], v[52:55]
	v_mfma_f32_16x16x32_bf16 v[48:51], v[196:199], v[206:209], v[48:51]
	v_mfma_f32_16x16x32_bf16 v[36:39], v[188:191], v[214:217], v[36:39]
	v_mfma_f32_16x16x32_bf16 v[32:35], v[196:199], v[214:217], v[32:35]
	v_mfma_f32_16x16x32_bf16 v[20:23], v[188:191], v[222:225], v[20:23]
	v_mfma_f32_16x16x32_bf16 v[16:19], v[196:199], v[222:225], v[16:19]
	v_mfma_f32_16x16x32_bf16 v[4:7], v[188:191], v[230:233], v[4:7]
	v_mfma_f32_16x16x32_bf16 v[0:3], v[196:199], v[230:233], v[0:3]
	s_setprio 0
	s_barrier
	s_add_i32 s76, s76, 2
	s_add_i32 s77, s77, 0x10000
	s_cmp_gt_u32 s76, 29
	s_mov_b64 s[40:41], s[42:43]
	s_cbranch_scc0 .LBB0_2228
	s_and_b64 vcc, exec, s[26:27]
	s_cbranch_vccz .LBB0_2231
	s_barrier

; __global__ void __launch_bounds__(512, 2) mega_fwd(Args a) {
	.amdhsa_kernel _Z8mega_fwd4Args
		.amdhsa_group_segment_fixed_size 0
		.amdhsa_private_segment_fixed_size 0
		.amdhsa_kernarg_size 552
		.amdhsa_user_sgpr_count 2
		.amdhsa_user_sgpr_dispatch_ptr 0
		.amdhsa_user_sgpr_queue_ptr 0
		.amdhsa_user_sgpr_kernarg_segment_ptr 1
		.amdhsa_user_sgpr_dispatch_id 0
		.amdhsa_user_sgpr_kernarg_preload_length 0
		.amdhsa_user_sgpr_kernarg_preload_offset 0
		.amdhsa_user_sgpr_private_segment_size 0
		.amdhsa_uses_dynamic_stack 0
		.amdhsa_enable_private_segment 0
		.amdhsa_system_sgpr_workgroup_id_x 1
		.amdhsa_system_sgpr_workgroup_id_y 0
		.amdhsa_system_sgpr_workgroup_id_z 0
		.amdhsa_system_sgpr_workgroup_info 0
		.amdhsa_system_vgpr_workitem_id 2
		.amdhsa_next_free_vgpr 255
		.amdhsa_next_free_sgpr 100
		.amdhsa_accum_offset 256
		.amdhsa_reserve_vcc 1
		.amdhsa_float_round_mode_32 0
		.amdhsa_float_round_mode_16_64 0
		.amdhsa_float_denorm_mode_32 3
		.amdhsa_float_denorm_mode_16_64 3
		.amdhsa_dx10_clamp 1
		.amdhsa_ieee_mode 1
		.amdhsa_fp16_overflow 0
		.amdhsa_tg_split 0
		.amdhsa_exception_fp_ieee_invalid_op 0
		.amdhsa_exception_fp_denorm_src 0
		.amdhsa_exception_fp_ieee_div_zero 0
		.amdhsa_exception_fp_ieee_overflow 0
		.amdhsa_exception_fp_ieee_underflow 0
		.amdhsa_exception_fp_ieee_inexact 0
		.amdhsa_exception_int_div_zero 0
	.end_amdhsa_kernel

; __global__ void __launch_bounds__(512, 2) mega_fwd(Args a) {
.Lfunc_end0:
	.size	_Z8mega_fwd4Args, .Lfunc_end0-_Z8mega_fwd4Args
	.set _Z8mega_fwd4Args.num_vgpr, 255
	.set _Z8mega_fwd4Args.num_agpr, 0
	.set _Z8mega_fwd4Args.numbered_sgpr, 100
	.set _Z8mega_fwd4Args.num_named_barrier, 0
	.set _Z8mega_fwd4Args.private_seg_size, 0
	.set _Z8mega_fwd4Args.uses_vcc, 1
	.set _Z8mega_fwd4Args.uses_flat_scratch, 0
	.set _Z8mega_fwd4Args.has_dyn_sized_stack, 0
	.set _Z8mega_fwd4Args.has_recursion, 0
	.set _Z8mega_fwd4Args.has_indirect_call, 0

; __global__ void __launch_bounds__(512, 2) mega_fwd(Args a) {
amdhsa.kernels:
  - .agpr_count:     0
    .args:
      - .offset:         0
        .size:           296
        .value_kind:     by_value
      - .offset:         296
        .size:           4
        .value_kind:     hidden_block_count_x
      - .offset:         300
        .size:           4
        .value_kind:     hidden_block_count_y
      - .offset:         304
        .size:           4
        .value_kind:     hidden_block_count_z
      - .offset:         308
        .size:           2
        .value_kind:     hidden_group_size_x
      - .offset:         310
        .size:           2
        .value_kind:     hidden_group_size_y
      - .offset:         312
        .size:           2
        .value_kind:     hidden_group_size_z
      - .offset:         314
        .size:           2
        .value_kind:     hidden_remainder_x
      - .offset:         316
        .size:           2
        .value_kind:     hidden_remainder_y
      - .offset:         318
        .size:           2
        .value_kind:     hidden_remainder_z
      - .offset:         336
        .size:           8
        .value_kind:     hidden_global_offset_x
      - .offset:         344
        .size:           8
        .value_kind:     hidden_global_offset_y
      - .offset:         352
        .size:           8
        .value_kind:     hidden_global_offset_z
      - .offset:         360
        .size:           2
        .value_kind:     hidden_grid_dims
      - .offset:         384
        .size:           8
        .value_kind:     hidden_multigrid_sync_arg
      - .offset:         416
        .size:           4
        .value_kind:     hidden_dynamic_lds_size
    .group_segment_fixed_size: 0
    .kernarg_segment_align: 8
    .kernarg_segment_size: 552
    .language:       OpenCL C
    .language_version:
      - 2
      - 0
    .max_flat_workgroup_size: 512
    .name:           _Z8mega_fwd4Args
    .private_segment_fixed_size: 0
    .sgpr_count:     106
    .sgpr_spill_count: 57
    .symbol:         _Z8mega_fwd4Args.kd
    .uniform_work_group_size: 1
    .uses_dynamic_stack: false
    .vgpr_count:     255
    .vgpr_spill_count: 0
    .wavefront_size: 64
